# nt cache policy extended to the weight item loop's f32 loads / bf16 stores, the sample cross-attn K/V f32 loads and the x conversion loads
# baseline (speedup 1.0000x reference)
; #define LAS __attribute__((address_space(3)))
; __device__ __forceinline__ unsigned cvt_pk_bf16(float lo, float hi) { unsigned r; asm("v_cvt_pk_bf16_f32 %0, %1, %2" : "=v"(r) : "v"(lo), "v"(hi)); return r; }
; __device__ __forceinline__ void transpose_item(const float* W, int K, int N, const float* gain, bf16_t* WT, int dst_row0, LAS float* scr, int kb, int n0, int lane) {
;     ...
; #pragma unroll
;     for (int i = 0; i < 8; ++i) { LAS float* d = scr + (kr + 8 * i) * 33 + n4; d[0] = v[i][0] * g[i]; d[1] = v[i][1] * g[i]; d[2] = v[i][2] * g[i]; d[3] = v[i][3] * g[i]; }
;     asm volatile("s_waitcnt lgkmcnt(0)" ::: "memory");
;     const int c = lane & 7;
; #pragma unroll
;     for (int j = 0; j < 4; ++j) { const int n = (lane >> 3) + 8 * j; const LAS float* s = scr + (8 * c) * 33 + n;
;         u32x4 o; o.x = cvt_pk_bf16(s[0 * 33], s[1 * 33]); o.y = cvt_pk_bf16(s[2 * 33], s[3 * 33]); o.z = cvt_pk_bf16(s[4 * 33], s[5 * 33]); o.w = cvt_pk_bf16(s[6 * 33], s[7 * 33]);
;         *(u32x4*)(WT + (size_t)(dst_row0 + n) * K + k0 + 8 * c) = o; }
;     asm volatile("s_waitcnt lgkmcnt(0)" ::: "memory");
.LBB0_9:
	s_waitcnt vmcnt(7)
	v_pk_mul_f32 v[2:3], v[2:3], v[44:45] op_sel_hi:[1,0]
	v_add_u32_e32 v43, v35, v39
	ds_write2_b32 v43, v2, v3 offset1:1
	v_pk_mul_f32 v[2:3], v[4:5], v[44:45] op_sel_hi:[1,0]
	ds_write2_b32 v43, v2, v3 offset0:2 offset1:3
	s_waitcnt vmcnt(6)
	v_pk_mul_f32 v[2:3], v[6:7], v[36:37] op_sel_hi:[1,0]
	v_add_u32_e32 v4, 0x420, v43
	ds_write2_b32 v4, v2, v3 offset1:1
	v_pk_mul_f32 v[2:3], v[8:9], v[36:37] op_sel_hi:[1,0]
	v_add_u32_e32 v4, 0x428, v43
	ds_write2_b32 v4, v2, v3 offset1:1
	s_waitcnt vmcnt(5)
	v_pk_mul_f32 v[2:3], v[10:11], v[50:51] op_sel_hi:[1,0]
	v_add_u32_e32 v4, 0x840, v43
	ds_write2_b32 v4, v2, v3 offset1:1
	v_pk_mul_f32 v[2:3], v[12:13], v[50:51] op_sel_hi:[1,0]
	v_add_u32_e32 v4, 0x848, v43
	ds_write2_b32 v4, v2, v3 offset1:1
	s_waitcnt vmcnt(4)
	v_pk_mul_f32 v[2:3], v[14:15], v[46:47] op_sel_hi:[1,0]
	v_add_u32_e32 v4, 0xc60, v43
	ds_write2_b32 v4, v2, v3 offset1:1
	v_pk_mul_f32 v[2:3], v[16:17], v[46:47] op_sel_hi:[1,0]
	v_add_u32_e32 v4, 0xc68, v43
	ds_write2_b32 v4, v2, v3 offset1:1
	s_waitcnt vmcnt(3)
	v_pk_mul_f32 v[2:3], v[18:19], v[54:55] op_sel_hi:[1,0]
	v_add_u32_e32 v4, 0x1080, v43
	ds_write2_b32 v4, v2, v3 offset1:1
	v_pk_mul_f32 v[2:3], v[20:21], v[54:55] op_sel_hi:[1,0]
	v_add_u32_e32 v4, 0x1088, v43
	ds_write2_b32 v4, v2, v3 offset1:1
	s_waitcnt vmcnt(2)
	v_pk_mul_f32 v[2:3], v[22:23], v[52:53] op_sel_hi:[1,0]
	v_add_u32_e32 v4, 0x14a0, v43
	ds_write2_b32 v4, v2, v3 offset1:1
	v_pk_mul_f32 v[2:3], v[24:25], v[52:53] op_sel_hi:[1,0]
	v_add_u32_e32 v4, 0x14a8, v43
	ds_write2_b32 v4, v2, v3 offset1:1
	s_waitcnt vmcnt(1)
	v_pk_mul_f32 v[2:3], v[26:27], v[58:59] op_sel_hi:[1,0]
	v_add_u32_e32 v4, 0x18c0, v43
	ds_write2_b32 v4, v2, v3 offset1:1
	v_pk_mul_f32 v[2:3], v[28:29], v[58:59] op_sel_hi:[1,0]
	v_add_u32_e32 v4, 0x18c8, v43
	ds_write2_b32 v4, v2, v3 offset1:1
	s_waitcnt vmcnt(0)
	v_pk_mul_f32 v[2:3], v[30:31], v[56:57] op_sel_hi:[1,0]
	v_add_u32_e32 v4, 0x1ce0, v43
	ds_write2_b32 v4, v2, v3 offset1:1
	v_pk_mul_f32 v[2:3], v[32:33], v[56:57] op_sel_hi:[1,0]
	v_add_u32_e32 v4, 0x1ce8, v43
	s_lshl_b32 s2, s16, 6
	ds_write2_b32 v4, v2, v3 offset1:1
	s_and_b32 s2, s2, 0xffffff00
	s_and_b32 s3, s22, 0x60
	s_waitcnt lgkmcnt(0)
	s_ashr_i32 s19, s18, 31
	s_or_b32 s16, s2, s3
	s_lshl_b64 s[2:3], s[18:19], 1
	ds_read2_b32 v[6:7], v53 offset0:33 offset1:41
	ds_read2_b32 v[8:9], v53 offset1:8
	ds_read2_b32 v[10:11], v53 offset0:66 offset1:74
	ds_read2_b32 v[12:13], v53 offset0:99 offset1:107
	ds_read2_b32 v[14:15], v53 offset0:132 offset1:140
	ds_read2_b32 v[16:17], v53 offset0:165 offset1:173
	ds_read2_b32 v[18:19], v53 offset0:198 offset1:206
	ds_read2_b32 v[20:21], v53 offset0:231 offset1:239
	s_add_u32 s2, s49, s2
	v_or_b32_e32 v24, s16, v1
	s_addc_u32 s3, s50, s3
	v_lshlrev_b32_e32 v36, 1, v38
	v_ashrrev_i32_e32 v25, 31, v24
	v_lshl_add_u64 v[22:23], s[2:3], 0, v[36:37]
	v_lshlrev_b64 v[24:25], 11, v[24:25]
	s_waitcnt lgkmcnt(6)
	v_cvt_pk_bf16_f32 v2, v8, v6
	v_lshl_add_u64 v[24:25], v[22:23], 0, v[24:25]
	v_or_b32_e32 v6, s16, v45
	s_waitcnt lgkmcnt(4)
	v_cvt_pk_bf16_f32 v3, v10, v12
	s_waitcnt lgkmcnt(2)
	v_cvt_pk_bf16_f32 v4, v14, v16
	s_waitcnt lgkmcnt(0)
	v_cvt_pk_bf16_f32 v5, v18, v20
	global_store_dwordx4 v[24:25], v[2:5], off nt
	s_nop 1
	v_cvt_pk_bf16_f32 v2, v9, v7
	v_ashrrev_i32_e32 v7, 31, v6
	v_lshlrev_b64 v[6:7], 11, v[6:7]
	v_cvt_pk_bf16_f32 v3, v11, v13
	v_cvt_pk_bf16_f32 v4, v15, v17
	v_cvt_pk_bf16_f32 v5, v19, v21
	v_lshl_add_u64 v[6:7], v[22:23], 0, v[6:7]
	ds_read2_b32 v[8:9], v53 offset0:16 offset1:24
	ds_read2_b32 v[10:11], v53 offset0:49 offset1:57
	ds_read2_b32 v[12:13], v53 offset0:82 offset1:90
	ds_read2_b32 v[14:15], v53 offset0:115 offset1:123
	ds_read2_b32 v[16:17], v53 offset0:148 offset1:156
	ds_read2_b32 v[18:19], v53 offset0:181 offset1:189
	ds_read2_b32 v[20:21], v53 offset0:214 offset1:222
	ds_read2_b32 v[24:25], v53 offset0:247 offset1:255
	global_store_dwordx4 v[6:7], v[2:5], off nt
	v_or_b32_e32 v6, s16, v47
	v_ashrrev_i32_e32 v7, 31, v6
	v_lshlrev_b64 v[6:7], 11, v[6:7]
	v_lshl_add_u64 v[6:7], v[22:23], 0, v[6:7]
	s_waitcnt lgkmcnt(6)
	v_cvt_pk_bf16_f32 v2, v8, v10
	s_waitcnt lgkmcnt(4)
	v_cvt_pk_bf16_f32 v3, v12, v14
	s_waitcnt lgkmcnt(2)
	v_cvt_pk_bf16_f32 v4, v16, v18
	s_waitcnt lgkmcnt(0)
	v_cvt_pk_bf16_f32 v5, v20, v24
	global_store_dwordx4 v[6:7], v[2:5], off nt
	v_or_b32_e32 v6, s16, v51
	v_ashrrev_i32_e32 v7, 31, v6
	v_lshlrev_b64 v[6:7], 11, v[6:7]
	v_lshl_add_u64 v[6:7], v[22:23], 0, v[6:7]
	v_cvt_pk_bf16_f32 v2, v9, v11
	v_cvt_pk_bf16_f32 v3, v13, v15
	v_cvt_pk_bf16_f32 v4, v17, v19
	v_cvt_pk_bf16_f32 v5, v21, v25
	global_store_dwordx4 v[6:7], v[2:5], off nt
	s_waitcnt lgkmcnt(0)

; __device__ __forceinline__ void transpose_item(const float* W, int K, int N, const float* gain, bf16_t* WT, int dst_row0, LAS float* scr, int kb, int n0, int lane) {
;     const int k0 = 64 * kb, n4 = (lane & 7) * 4, kr = lane >> 3;
; __device__ __forceinline__ void weight_item(const Params& P, unsigned char* ws, LAS float* scr, int l, int r, int lane) {
;     constexpr int I_UP = WI_UP, I_DN = WI_DN, I_IN = WI_IN, I_SQ = WI_SQ;
;         bf16_t* W1a = (bf16_t*)(ws + WS_W1) + (size_t)(2 * l) * 2 * DFF * D; bf16_t* W1b = W1a + (size_t)2 * DFF * D;
;         bf16_t* WDa = (bf16_t*)(ws + WS_WD) + (size_t)(2 * l) * D * DFF; bf16_t* WDb = WDa + (size_t)D * DFF;
;         const size_t oU = (size_t)l * D * DFF, oS = (size_t)l * D * D;
;     ...
;         if (r < I_UP) TR_UP(10, 9, W1a, 0)
;         r -= I_UP;
;         if (r < I_UP) TR_UP(11, 9, W1a, 1)
;         r -= I_UP;
;         if (r < I_UP) TR_UP(28, 27, W1b, 0)
;         r -= I_UP;
;         if (r < I_UP) TR_UP(29, 27, W1b, 1)
;         r -= I_UP;
;     ...
;         if (r < I_DN) { const int kb = r / 32, n0 = (r % 32) * 32; transpose_item(P.in[12] + oU, DFF, D, nullptr, WDa, n0, scr, kb, n0, lane); return; }
;         r -= I_DN;
;         if (r < I_DN) { const int kb = r / 32, n0 = (r % 32) * 32; transpose_item(P.in[30] + oU, DFF, D, nullptr, WDb, n0, scr, kb, n0, lane); return; }
;         r -= I_DN;
;         if (r < I_IN) { const int kb = r / 80, n0 = (r % 80) * 32; transpose_item(P.in[14] + (size_t)l * D * DIN, D, DIN, P.in[13] + l * D, (bf16_t*)(ws + WS_WIN) + (size_t)l * DIN * D, n0, scr, kb, n0, lane); return; }
;         r -= I_IN;
;         {
;             const int q = r / I_SQ; r %= I_SQ; const int kb = r / 32, n0 = (r % 32) * 32;
;             if (q == 0) transpose_item(P.in[20] + oS, D, D, P.in[19] + l * D, (bf16_t*)(ws + WS_WOUT) + oS, n0, scr, kb, n0, lane);
;             else if (q == 1) transpose_item(P.in[23] + oS, D, D, P.in[21] + l * D, (bf16_t*)(ws + WS_WXQ) + oS, n0, scr, kb, n0, lane);
;             else if (q == 2) transpose_item(P.in[26] + oS, D, D, nullptr, (bf16_t*)(ws + WS_WXO) + oS, n0, scr, kb, n0, lane);
;             else if (q == 3) transpose_item(P.in[24] + oS, D, D, P.in[22] + l * D, (bf16_t*)(ws + WS_WKV), l * 2048 + n0, scr, kb, n0, lane);
;             else transpose_item(P.in[25] + oS, D, D, P.in[22] + l * D, (bf16_t*)(ws + WS_WKV), l * 2048 + 1024 + n0, scr, kb, n0, lane);
.Lwd_take:
	s_lshl_b32 s16, s18, 1
	s_mul_i32 s2, s18, 0x1600000
	s_mul_hi_i32 s3, s16, 0xb00000
	s_add_u32 s49, s28, s2
	s_addc_u32 s50, s29, s3
	s_ashr_i32 s19, s18, 31
	s_mul_hi_i32 s21, s18, 0x2c0000
	s_mul_i32 s20, s18, 0x2c0000
	s_cmpk_gt_i32 s51, 0x57f
	s_mov_b64 s[2:3], -1
	s_cbranch_scc0 .LBB0_180
	s_cmpk_gt_u32 s51, 0xaff
	s_cbranch_scc0 .LBB0_161
	s_add_u32 s52, s49, 0xb00000
	s_addc_u32 s53, s50, 0
	s_cmpk_gt_u32 s51, 0x107f
	s_cbranch_scc0 .LBB0_142
	s_cmpk_gt_u32 s51, 0x15ff
	s_cbranch_scc0 .LBB0_123
	s_mul_hi_i32 s2, s16, 0x580000
	s_mul_i32 s16, s16, 0x580000
	s_add_u32 s55, s30, s16
	s_addc_u32 s54, s31, s2
	s_cmpk_gt_u32 s51, 0x1b7f
	s_mov_b64 s[2:3], -1
	s_cbranch_scc0 .LBB0_120
	s_cmpk_gt_u32 s51, 0x20ff
	s_cbranch_scc0 .LBB0_117
	s_cmpk_gt_u32 s51, 0x25ff
	s_cbranch_scc0 .LBB0_98
	s_lshl_b64 s[22:23], s[18:19], 20
	s_add_i32 s16, s51, 0xffffda00
	s_bfe_u32 s56, s51, 0x40005
	s_and_b32 s19, s44, 0x3e0
	s_cmpk_gt_u32 s16, 0x1ff
	s_cbranch_scc0 .LBB0_80
	s_lshr_b32 s16, s16, 9
	s_cmp_lt_i32 s16, 2
	s_cbranch_scc1 .LBB0_61
	s_cmp_lt_i32 s16, 3
	s_cbranch_scc1 .LBB0_58
	s_mov_b64 s[24:25], -1
	s_cmp_lg_u32 s16, 3
	v_cmp_ne_u32_e64 s[2:3], 1, v55
	s_cbranch_scc0 .LBB0_39
	s_load_dwordx16 s[64:79], s[0:1], 0xc0
	s_lshl_b64 s[24:25], s[22:23], 2
	v_mov_b32_e32 v43, v37
	v_mov_b32_e32 v44, 1.0
	v_mov_b32_e32 v46, 1.0
	s_waitcnt lgkmcnt(0)
	s_add_u32 s57, s66, s24
	s_addc_u32 s59, s67, s25
	s_load_dwordx16 s[64:79], s[0:1], 0x80
	s_lshl_b32 s24, s18, 10
	s_ashr_i32 s25, s24, 31
	s_lshl_b64 s[24:25], s[24:25], 2
	s_waitcnt lgkmcnt(0)
	s_add_u32 s24, s76, s24
	s_addc_u32 s25, s77, s25
	s_lshl_b32 s16, s56, 6
	s_lshl_b32 s58, s19, 2
	s_add_u32 s58, s57, s58
	v_or_b32_e32 v32, s16, v1
	s_addc_u32 s59, s59, 0
	v_lshl_add_u64 v[30:31], s[58:59], 0, v[42:43]
	v_lshlrev_b32_e32 v36, 12, v32
	v_lshl_add_u64 v[2:3], v[30:31], 0, v[36:37]
	global_load_dwordx4 v[2:5], v[2:3], off nt
	s_and_b64 vcc, exec, s[2:3]
	v_lshlrev_b32_e32 v43, 2, v32
	s_cbranch_vccnz .LBB0_24
	global_load_dword v46, v43, s[24:25]
.LBB0_24:
	v_lshl_or_b32 v36, v32, 12, v57
	v_lshl_add_u64 v[6:7], v[30:31], 0, v[36:37]
	global_load_dwordx4 v[6:9], v[6:7], off nt
	s_and_b64 vcc, exec, s[2:3]
	s_cbranch_vccnz .LBB0_26
	global_load_dword v44, v43, s[24:25] offset:32
.LBB0_26:
	v_lshl_or_b32 v36, v32, 12, v59
	v_lshl_add_u64 v[10:11], v[30:31], 0, v[36:37]
	global_load_dwordx4 v[10:13], v[10:11], off nt
	v_mov_b32_e32 v48, 1.0
	s_and_b64 vcc, exec, s[2:3]
	v_mov_b32_e32 v50, 1.0
	s_cbranch_vccnz .LBB0_28
	global_load_dword v50, v43, s[24:25] offset:64
.LBB0_28:
	v_lshl_or_b32 v36, v32, 12, v60
	v_lshl_add_u64 v[14:15], v[30:31], 0, v[36:37]
	global_load_dwordx4 v[14:17], v[14:15], off nt
	s_and_b64 vcc, exec, s[2:3]
	s_cbranch_vccnz .LBB0_30
	global_load_dword v48, v43, s[24:25] offset:96
.LBB0_30:
	v_lshl_or_b32 v36, v32, 12, v61
	v_lshl_add_u64 v[18:19], v[30:31], 0, v[36:37]
	global_load_dwordx4 v[18:21], v[18:19], off nt
	v_mov_b32_e32 v52, 1.0
	s_and_b64 vcc, exec, s[2:3]
	v_mov_b32_e32 v56, 1.0
	s_cbranch_vccnz .LBB0_32
	global_load_dword v56, v43, s[24:25] offset:128
.LBB0_32:
	v_lshl_or_b32 v36, v32, 12, v62
	v_lshl_add_u64 v[22:23], v[30:31], 0, v[36:37]
	global_load_dwordx4 v[22:25], v[22:23], off nt
	s_and_b64 vcc, exec, s[2:3]
	s_cbranch_vccnz .LBB0_34
	global_load_dword v52, v43, s[24:25] offset:160
.LBB0_34:
	v_lshl_or_b32 v36, v32, 12, v63
	v_lshl_add_u64 v[26:27], v[30:31], 0, v[36:37]
	global_load_dwordx4 v[26:29], v[26:27], off nt
	v_mov_b32_e32 v54, 1.0
	s_and_b64 vcc, exec, s[2:3]
	v_mov_b32_e32 v58, 1.0
	s_cbranch_vccnz .LBB0_36
	global_load_dword v58, v43, s[24:25] offset:192
.LBB0_36:
	v_lshl_or_b32 v36, v32, 12, v64
	v_lshl_add_u64 v[30:31], v[30:31], 0, v[36:37]
	global_load_dwordx4 v[30:33], v[30:31], off nt
	s_and_b64 vcc, exec, s[2:3]
	s_cbranch_vccnz .LBB0_38
	global_load_dword v54, v43, s[24:25] offset:224
; #define LAS __attribute__((address_space(3)))
; __device__ __forceinline__ unsigned cvt_pk_bf16(float lo, float hi) { unsigned r; asm("v_cvt_pk_bf16_f32 %0, %1, %2" : "=v"(r) : "v"(lo), "v"(hi)); return r; }
; __device__ __forceinline__ void transpose_item(const float* W, int K, int N, const float* gain, bf16_t* WT, int dst_row0, LAS float* scr, int kb, int n0, int lane) {
;     ...
; #pragma unroll
;     for (int i = 0; i < 8; ++i) { LAS float* d = scr + (kr + 8 * i) * 33 + n4; d[0] = v[i][0] * g[i]; d[1] = v[i][1] * g[i]; d[2] = v[i][2] * g[i]; d[3] = v[i][3] * g[i]; }
;     asm volatile("s_waitcnt lgkmcnt(0)" ::: "memory");
;     const int c = lane & 7;
; #pragma unroll
;     for (int j = 0; j < 4; ++j) { const int n = (lane >> 3) + 8 * j; const LAS float* s = scr + (8 * c) * 33 + n;
;         u32x4 o; o.x = cvt_pk_bf16(s[0 * 33], s[1 * 33]); o.y = cvt_pk_bf16(s[2 * 33], s[3 * 33]); o.z = cvt_pk_bf16(s[4 * 33], s[5 * 33]); o.w = cvt_pk_bf16(s[6 * 33], s[7 * 33]);
;         *(u32x4*)(WT + (size_t)(dst_row0 + n) * K + k0 + 8 * c) = o; }
;     asm volatile("s_waitcnt lgkmcnt(0)" ::: "memory");
; __device__ __forceinline__ void weight_item(const Params& P, unsigned char* ws, LAS float* scr, int l, int r, int lane) {
;     ...
;             else if (q == 3) transpose_item(P.in[24] + oS, D, D, P.in[22] + l * D, (bf16_t*)(ws + WS_WKV), l * 2048 + n0, scr, kb, n0, lane);
;             else transpose_item(P.in[25] + oS, D, D, P.in[22] + l * D, (bf16_t*)(ws + WS_WKV), l * 2048 + 1024 + n0, scr, kb, n0, lane);
.LBB0_38:
	s_waitcnt vmcnt(7)
	v_pk_mul_f32 v[2:3], v[2:3], v[46:47] op_sel_hi:[1,0]
	v_add_u32_e32 v36, v35, v39
	ds_write2_b32 v36, v2, v3 offset1:1
	v_pk_mul_f32 v[2:3], v[4:5], v[46:47] op_sel_hi:[1,0]
	ds_write2_b32 v36, v2, v3 offset0:2 offset1:3
	s_waitcnt vmcnt(6)
	v_pk_mul_f32 v[2:3], v[6:7], v[44:45] op_sel_hi:[1,0]
	v_add_u32_e32 v4, 0x420, v36
	ds_write2_b32 v4, v2, v3 offset1:1
	v_pk_mul_f32 v[2:3], v[8:9], v[44:45] op_sel_hi:[1,0]
	v_add_u32_e32 v4, 0x428, v36
	ds_write2_b32 v4, v2, v3 offset1:1
	s_waitcnt vmcnt(5)
	v_pk_mul_f32 v[2:3], v[10:11], v[50:51] op_sel_hi:[1,0]
	v_add_u32_e32 v4, 0x840, v36
	ds_write2_b32 v4, v2, v3 offset1:1
	v_pk_mul_f32 v[2:3], v[12:13], v[50:51] op_sel_hi:[1,0]
	v_add_u32_e32 v4, 0x848, v36
	ds_write2_b32 v4, v2, v3 offset1:1
	s_waitcnt vmcnt(4)
	v_pk_mul_f32 v[2:3], v[14:15], v[48:49] op_sel_hi:[1,0]
	v_add_u32_e32 v4, 0xc60, v36
	ds_write2_b32 v4, v2, v3 offset1:1
	v_pk_mul_f32 v[2:3], v[16:17], v[48:49] op_sel_hi:[1,0]
	v_add_u32_e32 v4, 0xc68, v36
	ds_write2_b32 v4, v2, v3 offset1:1
	s_waitcnt vmcnt(3)
	v_pk_mul_f32 v[2:3], v[18:19], v[56:57] op_sel_hi:[1,0]
	v_add_u32_e32 v4, 0x1080, v36
	ds_write2_b32 v4, v2, v3 offset1:1
	v_pk_mul_f32 v[2:3], v[20:21], v[56:57] op_sel_hi:[1,0]
	v_add_u32_e32 v4, 0x1088, v36
	ds_write2_b32 v4, v2, v3 offset1:1
	s_waitcnt vmcnt(2)
	v_pk_mul_f32 v[2:3], v[22:23], v[52:53] op_sel_hi:[1,0]
	v_add_u32_e32 v4, 0x14a0, v36
	ds_write2_b32 v4, v2, v3 offset1:1
	v_pk_mul_f32 v[2:3], v[24:25], v[52:53] op_sel_hi:[1,0]
	v_add_u32_e32 v4, 0x14a8, v36
	ds_write2_b32 v4, v2, v3 offset1:1
	s_waitcnt vmcnt(1)
	v_pk_mul_f32 v[2:3], v[26:27], v[58:59] op_sel_hi:[1,0]
	v_add_u32_e32 v4, 0x18c0, v36
	ds_write2_b32 v4, v2, v3 offset1:1
	v_pk_mul_f32 v[2:3], v[28:29], v[58:59] op_sel_hi:[1,0]
	v_add_u32_e32 v4, 0x18c8, v36
	ds_write2_b32 v4, v2, v3 offset1:1
	s_waitcnt vmcnt(0)
	v_pk_mul_f32 v[2:3], v[30:31], v[54:55] op_sel_hi:[1,0]
	v_add_u32_e32 v4, 0x1ce0, v36
	ds_write2_b32 v4, v2, v3 offset1:1
	v_pk_mul_f32 v[2:3], v[32:33], v[54:55] op_sel_hi:[1,0]
	v_add_u32_e32 v4, 0x1ce8, v36
	s_lshl_b32 s24, s18, 11
	ds_write2_b32 v4, v2, v3 offset1:1
	s_or_b32 s24, s19, s24
	s_waitcnt lgkmcnt(0)
	s_bitset1_b32 s24, 10
	ds_read2_b32 v[6:7], v53 offset0:33 offset1:41
	ds_read2_b32 v[8:9], v53 offset1:8
	ds_read2_b32 v[10:11], v53 offset0:66 offset1:74
	ds_read2_b32 v[12:13], v53 offset0:99 offset1:107
	ds_read2_b32 v[14:15], v53 offset0:132 offset1:140
	ds_read2_b32 v[16:17], v53 offset0:165 offset1:173
	ds_read2_b32 v[18:19], v53 offset0:198 offset1:206
	ds_read2_b32 v[20:21], v53 offset0:231 offset1:239
	v_or_b32_e32 v24, s24, v1
	s_lshl_b32 s16, s16, 1
	v_ashrrev_i32_e32 v25, 31, v24
	v_lshl_add_u64 v[22:23], v[40:41], 0, s[16:17]
	v_lshlrev_b64 v[24:25], 11, v[24:25]
	s_waitcnt lgkmcnt(6)
	v_cvt_pk_bf16_f32 v2, v8, v6
	v_lshl_add_u64 v[24:25], v[22:23], 0, v[24:25]
	v_or_b32_e32 v6, s24, v45
	s_waitcnt lgkmcnt(4)
	v_cvt_pk_bf16_f32 v3, v10, v12
	s_waitcnt lgkmcnt(2)
	v_cvt_pk_bf16_f32 v4, v14, v16
	s_waitcnt lgkmcnt(0)
	v_cvt_pk_bf16_f32 v5, v18, v20
	global_store_dwordx4 v[24:25], v[2:5], off nt
	s_nop 1
	v_cvt_pk_bf16_f32 v2, v9, v7
	v_ashrrev_i32_e32 v7, 31, v6
	v_lshlrev_b64 v[6:7], 11, v[6:7]
	v_cvt_pk_bf16_f32 v3, v11, v13
	v_cvt_pk_bf16_f32 v4, v15, v17
	v_cvt_pk_bf16_f32 v5, v19, v21
	v_lshl_add_u64 v[6:7], v[22:23], 0, v[6:7]
	ds_read2_b32 v[8:9], v53 offset0:16 offset1:24
	ds_read2_b32 v[10:11], v53 offset0:49 offset1:57
	ds_read2_b32 v[12:13], v53 offset0:82 offset1:90
	ds_read2_b32 v[14:15], v53 offset0:115 offset1:123
	ds_read2_b32 v[16:17], v53 offset0:148 offset1:156
	ds_read2_b32 v[18:19], v53 offset0:181 offset1:189
	ds_read2_b32 v[20:21], v53 offset0:214 offset1:222
	ds_read2_b32 v[24:25], v53 offset0:247 offset1:255
	global_store_dwordx4 v[6:7], v[2:5], off nt
	v_or_b32_e32 v6, s24, v47
	v_ashrrev_i32_e32 v7, 31, v6
	v_lshlrev_b64 v[6:7], 11, v[6:7]
	v_lshl_add_u64 v[6:7], v[22:23], 0, v[6:7]
	s_waitcnt lgkmcnt(6)
	v_cvt_pk_bf16_f32 v2, v8, v10
	s_waitcnt lgkmcnt(4)
	v_cvt_pk_bf16_f32 v3, v12, v14
	s_waitcnt lgkmcnt(2)
	v_cvt_pk_bf16_f32 v4, v16, v18
	s_waitcnt lgkmcnt(0)
	v_cvt_pk_bf16_f32 v5, v20, v24
	global_store_dwordx4 v[6:7], v[2:5], off nt
	v_or_b32_e32 v6, s24, v51
	v_ashrrev_i32_e32 v7, 31, v6
	v_lshlrev_b64 v[6:7], 11, v[6:7]
	v_lshl_add_u64 v[6:7], v[22:23], 0, v[6:7]
	v_cvt_pk_bf16_f32 v2, v9, v11
	v_cvt_pk_bf16_f32 v3, v13, v15
	v_cvt_pk_bf16_f32 v4, v17, v19
	v_cvt_pk_bf16_f32 v5, v21, v25
	global_store_dwordx4 v[6:7], v[2:5], off nt
	s_waitcnt lgkmcnt(0)
	s_mov_b64 s[24:25], 0
.LBB0_39:
	s_and_b64 vcc, exec, s[24:25]
	s_cbranch_vccz .LBB0_57
	s_load_dwordx16 s[64:79], s[0:1], 0xc0
	s_lshl_b64 s[24:25], s[22:23], 2
	v_mov_b32_e32 v43, v37
	v_mov_b32_e32 v44, 1.0
	v_mov_b32_e32 v46, 1.0
	s_waitcnt lgkmcnt(0)
	s_add_u32 s57, s64, s24
	s_addc_u32 s59, s65, s25
	s_load_dwordx16 s[64:79], s[0:1], 0x80
	s_lshl_b32 s24, s18, 10
	s_ashr_i32 s25, s24, 31
	s_lshl_b64 s[24:25], s[24:25], 2
	s_waitcnt lgkmcnt(0)
	s_add_u32 s24, s76, s24
	s_addc_u32 s25, s77, s25
	s_lshl_b32 s16, s56, 6
	s_lshl_b32 s58, s19, 2
	s_add_u32 s58, s57, s58
	v_or_b32_e32 v32, s16, v1
	s_addc_u32 s59, s59, 0
	v_lshl_add_u64 v[30:31], s[58:59], 0, v[42:43]
	v_lshlrev_b32_e32 v36, 12, v32
	v_lshl_add_u64 v[2:3], v[30:31], 0, v[36:37]
	global_load_dwordx4 v[2:5], v[2:3], off nt
	s_and_b64 vcc, exec, s[2:3]
	v_lshlrev_b32_e32 v43, 2, v32
	s_cbranch_vccnz .LBB0_42
	global_load_dword v46, v43, s[24:25]

; #define LAS __attribute__((address_space(3)))
; __device__ __forceinline__ unsigned cvt_pk_bf16(float lo, float hi) { unsigned r; asm("v_cvt_pk_bf16_f32 %0, %1, %2" : "=v"(r) : "v"(lo), "v"(hi)); return r; }
; __device__ __forceinline__ void transpose_item(const float* W, int K, int N, const float* gain, bf16_t* WT, int dst_row0, LAS float* scr, int kb, int n0, int lane) {
;     ...
; #pragma unroll
;     for (int i = 0; i < 8; ++i) { LAS float* d = scr + (kr + 8 * i) * 33 + n4; d[0] = v[i][0] * g[i]; d[1] = v[i][1] * g[i]; d[2] = v[i][2] * g[i]; d[3] = v[i][3] * g[i]; }
;     asm volatile("s_waitcnt lgkmcnt(0)" ::: "memory");
;     const int c = lane & 7;
; #pragma unroll
;     for (int j = 0; j < 4; ++j) { const int n = (lane >> 3) + 8 * j; const LAS float* s = scr + (8 * c) * 33 + n;
;         u32x4 o; o.x = cvt_pk_bf16(s[0 * 33], s[1 * 33]); o.y = cvt_pk_bf16(s[2 * 33], s[3 * 33]); o.z = cvt_pk_bf16(s[4 * 33], s[5 * 33]); o.w = cvt_pk_bf16(s[6 * 33], s[7 * 33]);
;         *(u32x4*)(WT + (size_t)(dst_row0 + n) * K + k0 + 8 * c) = o; }
;     asm volatile("s_waitcnt lgkmcnt(0)" ::: "memory");
.LBB0_56:
	s_waitcnt vmcnt(7)
	v_pk_mul_f32 v[2:3], v[2:3], v[46:47] op_sel_hi:[1,0]
	v_add_u32_e32 v36, v35, v39
	ds_write2_b32 v36, v2, v3 offset1:1
	v_pk_mul_f32 v[2:3], v[4:5], v[46:47] op_sel_hi:[1,0]
	ds_write2_b32 v36, v2, v3 offset0:2 offset1:3
	s_waitcnt vmcnt(6)
	v_pk_mul_f32 v[2:3], v[6:7], v[44:45] op_sel_hi:[1,0]
	v_add_u32_e32 v4, 0x420, v36
	ds_write2_b32 v4, v2, v3 offset1:1
	v_pk_mul_f32 v[2:3], v[8:9], v[44:45] op_sel_hi:[1,0]
	v_add_u32_e32 v4, 0x428, v36
	ds_write2_b32 v4, v2, v3 offset1:1
	s_waitcnt vmcnt(5)
	v_pk_mul_f32 v[2:3], v[10:11], v[50:51] op_sel_hi:[1,0]
	v_add_u32_e32 v4, 0x840, v36
	ds_write2_b32 v4, v2, v3 offset1:1
	v_pk_mul_f32 v[2:3], v[12:13], v[50:51] op_sel_hi:[1,0]
	v_add_u32_e32 v4, 0x848, v36
	ds_write2_b32 v4, v2, v3 offset1:1
	s_waitcnt vmcnt(4)
	v_pk_mul_f32 v[2:3], v[14:15], v[48:49] op_sel_hi:[1,0]
	v_add_u32_e32 v4, 0xc60, v36
	ds_write2_b32 v4, v2, v3 offset1:1
	v_pk_mul_f32 v[2:3], v[16:17], v[48:49] op_sel_hi:[1,0]
	v_add_u32_e32 v4, 0xc68, v36
	ds_write2_b32 v4, v2, v3 offset1:1
	s_waitcnt vmcnt(3)
	v_pk_mul_f32 v[2:3], v[18:19], v[56:57] op_sel_hi:[1,0]
	v_add_u32_e32 v4, 0x1080, v36
	ds_write2_b32 v4, v2, v3 offset1:1
	v_pk_mul_f32 v[2:3], v[20:21], v[56:57] op_sel_hi:[1,0]
	v_add_u32_e32 v4, 0x1088, v36
	ds_write2_b32 v4, v2, v3 offset1:1
	s_waitcnt vmcnt(2)
	v_pk_mul_f32 v[2:3], v[22:23], v[52:53] op_sel_hi:[1,0]
	v_add_u32_e32 v4, 0x14a0, v36
	ds_write2_b32 v4, v2, v3 offset1:1
	v_pk_mul_f32 v[2:3], v[24:25], v[52:53] op_sel_hi:[1,0]
	v_add_u32_e32 v4, 0x14a8, v36
	ds_write2_b32 v4, v2, v3 offset1:1
	s_waitcnt vmcnt(1)
	v_pk_mul_f32 v[2:3], v[26:27], v[58:59] op_sel_hi:[1,0]
	v_add_u32_e32 v4, 0x18c0, v36
	ds_write2_b32 v4, v2, v3 offset1:1
	v_pk_mul_f32 v[2:3], v[28:29], v[58:59] op_sel_hi:[1,0]
	v_add_u32_e32 v4, 0x18c8, v36
	ds_write2_b32 v4, v2, v3 offset1:1
	s_waitcnt vmcnt(0)
	v_pk_mul_f32 v[2:3], v[30:31], v[54:55] op_sel_hi:[1,0]
	v_add_u32_e32 v4, 0x1ce0, v36
	ds_write2_b32 v4, v2, v3 offset1:1
	v_pk_mul_f32 v[2:3], v[32:33], v[54:55] op_sel_hi:[1,0]
	v_add_u32_e32 v4, 0x1ce8, v36
	ds_write2_b32 v4, v2, v3 offset1:1
	s_lshl_b32 s2, s18, 11
	s_waitcnt lgkmcnt(0)
	s_or_b32 s2, s19, s2
	ds_read2_b32 v[6:7], v53 offset0:33 offset1:41
	ds_read2_b32 v[8:9], v53 offset1:8
	ds_read2_b32 v[10:11], v53 offset0:66 offset1:74
	ds_read2_b32 v[12:13], v53 offset0:99 offset1:107
	ds_read2_b32 v[14:15], v53 offset0:132 offset1:140
	ds_read2_b32 v[16:17], v53 offset0:165 offset1:173
	ds_read2_b32 v[18:19], v53 offset0:198 offset1:206
	ds_read2_b32 v[20:21], v53 offset0:231 offset1:239
	v_or_b32_e32 v24, s2, v1
	s_lshl_b32 s16, s16, 1
	v_ashrrev_i32_e32 v25, 31, v24
	v_lshl_add_u64 v[22:23], v[40:41], 0, s[16:17]
	v_lshlrev_b64 v[24:25], 11, v[24:25]
	s_waitcnt lgkmcnt(6)
	v_cvt_pk_bf16_f32 v2, v8, v6
	v_lshl_add_u64 v[24:25], v[22:23], 0, v[24:25]
	v_or_b32_e32 v6, s2, v45
	s_waitcnt lgkmcnt(4)
	v_cvt_pk_bf16_f32 v3, v10, v12
	s_waitcnt lgkmcnt(2)
	v_cvt_pk_bf16_f32 v4, v14, v16
	s_waitcnt lgkmcnt(0)
	v_cvt_pk_bf16_f32 v5, v18, v20
	global_store_dwordx4 v[24:25], v[2:5], off nt
	s_nop 1
	v_cvt_pk_bf16_f32 v2, v9, v7
	v_ashrrev_i32_e32 v7, 31, v6
	v_lshlrev_b64 v[6:7], 11, v[6:7]
	v_cvt_pk_bf16_f32 v3, v11, v13
	v_cvt_pk_bf16_f32 v4, v15, v17
	v_cvt_pk_bf16_f32 v5, v19, v21
	v_lshl_add_u64 v[6:7], v[22:23], 0, v[6:7]
	ds_read2_b32 v[8:9], v53 offset0:16 offset1:24
	ds_read2_b32 v[10:11], v53 offset0:49 offset1:57
	ds_read2_b32 v[12:13], v53 offset0:82 offset1:90
	ds_read2_b32 v[14:15], v53 offset0:115 offset1:123
	ds_read2_b32 v[16:17], v53 offset0:148 offset1:156
	ds_read2_b32 v[18:19], v53 offset0:181 offset1:189
	ds_read2_b32 v[20:21], v53 offset0:214 offset1:222
	ds_read2_b32 v[24:25], v53 offset0:247 offset1:255
	global_store_dwordx4 v[6:7], v[2:5], off nt
	v_or_b32_e32 v6, s2, v47
	v_ashrrev_i32_e32 v7, 31, v6
	v_lshlrev_b64 v[6:7], 11, v[6:7]
	v_lshl_add_u64 v[6:7], v[22:23], 0, v[6:7]
	s_waitcnt lgkmcnt(6)
	v_cvt_pk_bf16_f32 v2, v8, v10
	s_waitcnt lgkmcnt(4)
	v_cvt_pk_bf16_f32 v3, v12, v14
	s_waitcnt lgkmcnt(2)
	v_cvt_pk_bf16_f32 v4, v16, v18
	s_waitcnt lgkmcnt(0)
	v_cvt_pk_bf16_f32 v5, v20, v24
	global_store_dwordx4 v[6:7], v[2:5], off nt
	v_or_b32_e32 v6, s2, v51
	v_ashrrev_i32_e32 v7, 31, v6
	v_lshlrev_b64 v[6:7], 11, v[6:7]
	v_lshl_add_u64 v[6:7], v[22:23], 0, v[6:7]
	v_cvt_pk_bf16_f32 v2, v9, v11
	v_cvt_pk_bf16_f32 v3, v13, v15
	v_cvt_pk_bf16_f32 v4, v17, v19
	v_cvt_pk_bf16_f32 v5, v21, v25
	global_store_dwordx4 v[6:7], v[2:5], off nt
	s_waitcnt lgkmcnt(0)

; #define LAS __attribute__((address_space(3)))
; __device__ __forceinline__ unsigned cvt_pk_bf16(float lo, float hi) { unsigned r; asm("v_cvt_pk_bf16_f32 %0, %1, %2" : "=v"(r) : "v"(lo), "v"(hi)); return r; }
; __device__ __forceinline__ void transpose_item(const float* W, int K, int N, const float* gain, bf16_t* WT, int dst_row0, LAS float* scr, int kb, int n0, int lane) {
;     const int k0 = 64 * kb, n4 = (lane & 7) * 4, kr = lane >> 3;
;     f32x4 v[8]; float g[8];
; #pragma unroll
;     for (int i = 0; i < 8; ++i) { v[i] = *(const f32x4*)(W + (size_t)(k0 + kr + 8 * i) * N + n0 + n4); g[i] = gain ? gain[k0 + kr + 8 * i] : 1.0f; }
; #pragma unroll
;     for (int i = 0; i < 8; ++i) { LAS float* d = scr + (kr + 8 * i) * 33 + n4; d[0] = v[i][0] * g[i]; d[1] = v[i][1] * g[i]; d[2] = v[i][2] * g[i]; d[3] = v[i][3] * g[i]; }
;     asm volatile("s_waitcnt lgkmcnt(0)" ::: "memory");
;     const int c = lane & 7;
; #pragma unroll
;     for (int j = 0; j < 4; ++j) { const int n = (lane >> 3) + 8 * j; const LAS float* s = scr + (8 * c) * 33 + n;
;         u32x4 o; o.x = cvt_pk_bf16(s[0 * 33], s[1 * 33]); o.y = cvt_pk_bf16(s[2 * 33], s[3 * 33]); o.z = cvt_pk_bf16(s[4 * 33], s[5 * 33]); o.w = cvt_pk_bf16(s[6 * 33], s[7 * 33]);
;         *(u32x4*)(WT + (size_t)(dst_row0 + n) * K + k0 + 8 * c) = o; }
;     asm volatile("s_waitcnt lgkmcnt(0)" ::: "memory");
; __device__ __forceinline__ void weight_item(const Params& P, unsigned char* ws, LAS float* scr, int l, int r, int lane) {
;     ...
;             if (q == 0) transpose_item(P.in[20] + oS, D, D, P.in[19] + l * D, (bf16_t*)(ws + WS_WOUT) + oS, n0, scr, kb, n0, lane);
;             else if (q == 1) transpose_item(P.in[23] + oS, D, D, P.in[21] + l * D, (bf16_t*)(ws + WS_WXQ) + oS, n0, scr, kb, n0, lane);
;             else if (q == 2) transpose_item(P.in[26] + oS, D, D, nullptr, (bf16_t*)(ws + WS_WXO) + oS, n0, scr, kb, n0, lane);
.LBB0_58:
	s_andn2_b64 vcc, exec, s[2:3]
	s_cbranch_vccnz .LBB0_60
	s_load_dwordx16 s[64:79], s[0:1], 0xc0
	s_lshl_b64 s[2:3], s[22:23], 2
	v_mov_b32_e32 v43, v37
	v_lshlrev_b32_e32 v4, 12, v1
	v_lshl_or_b32 v36, s56, 18, v4
	s_waitcnt lgkmcnt(0)
	s_add_u32 s16, s68, s2
	s_addc_u32 s24, s69, s3
	s_lshl_b64 s[2:3], s[22:23], 1
	s_add_u32 s25, s34, s2
	s_addc_u32 s57, s35, s3
	s_lshl_b32 s2, s19, 2
	s_add_u32 s2, s16, s2
	s_addc_u32 s3, s24, 0
	v_lshl_add_u64 v[2:3], s[2:3], 0, v[42:43]
	v_lshl_add_u64 v[30:31], v[2:3], 0, v[36:37]
	s_mov_b32 s2, 0x8000
	v_add_co_u32_e32 v6, vcc, s2, v30
	s_mov_b32 s2, 0x10000
	s_nop 0
	v_addc_co_u32_e32 v7, vcc, 0, v31, vcc
	v_add_co_u32_e32 v10, vcc, s2, v30
	s_mov_b32 s2, 0x18000
	s_nop 0
	v_addc_co_u32_e32 v11, vcc, 0, v31, vcc
	v_add_co_u32_e32 v14, vcc, s2, v30
	s_mov_b32 s2, 0x20000
	s_nop 0
	v_addc_co_u32_e32 v15, vcc, 0, v31, vcc
	v_add_co_u32_e32 v18, vcc, s2, v30
	s_mov_b32 s2, 0x28000
	s_nop 0
	v_addc_co_u32_e32 v19, vcc, 0, v31, vcc
	v_add_co_u32_e32 v22, vcc, s2, v30
	global_load_dwordx4 v[2:5], v[30:31], off nt
	s_nop 0
	global_load_dwordx4 v[6:9], v[6:7], off nt
	v_addc_co_u32_e32 v23, vcc, 0, v31, vcc
	global_load_dwordx4 v[10:13], v[10:11], off nt
	s_nop 0
	global_load_dwordx4 v[14:17], v[14:15], off nt
	s_nop 0
	global_load_dwordx4 v[18:21], v[18:19], off nt
	s_nop 0
	global_load_dwordx4 v[22:25], v[22:23], off nt
	s_mov_b32 s2, 0x30000
	v_add_co_u32_e32 v26, vcc, s2, v30
	s_mov_b32 s2, 0x38000
	s_nop 0
	v_addc_co_u32_e32 v27, vcc, 0, v31, vcc
	global_load_dwordx4 v[26:29], v[26:27], off nt
	v_add_co_u32_e32 v30, vcc, s2, v30
	v_add_u32_e32 v43, v35, v39
	s_nop 0
	v_addc_co_u32_e32 v31, vcc, 0, v31, vcc
	global_load_dwordx4 v[30:33], v[30:31], off nt
	v_add_u32_e32 v44, 0x420, v43
	v_add_u32_e32 v46, 0x428, v43
	v_add_u32_e32 v48, 0x840, v43
	v_add_u32_e32 v49, 0x848, v43
	v_add_u32_e32 v50, 0xc60, v43
	v_add_u32_e32 v52, 0xc68, v43
	v_add_u32_e32 v54, 0x1080, v43
	v_add_u32_e32 v56, 0x1088, v43
	v_add_u32_e32 v58, 0x14a0, v43
	v_add_u32_e32 v65, 0x14a8, v43
	v_add_u32_e32 v66, 0x18c0, v43
	v_add_u32_e32 v67, 0x18c8, v43
	v_add_u32_e32 v68, 0x1ce0, v43
	v_add_u32_e32 v69, 0x1ce8, v43
	s_lshl_b32 s2, s56, 7
	s_add_u32 s2, s25, s2
	s_addc_u32 s3, s57, 0
	v_lshlrev_b32_e32 v36, 1, v38
	s_waitcnt vmcnt(7)
	ds_write2_b32 v43, v2, v3 offset1:1
	ds_write2_b32 v43, v4, v5 offset0:2 offset1:3
	s_waitcnt vmcnt(6)
	ds_write2_b32 v44, v6, v7 offset1:1
	ds_write2_b32 v46, v8, v9 offset1:1
	s_waitcnt vmcnt(5)
	ds_write2_b32 v48, v10, v11 offset1:1
	ds_write2_b32 v49, v12, v13 offset1:1
	s_waitcnt vmcnt(4)
	ds_write2_b32 v50, v14, v15 offset1:1
	ds_write2_b32 v52, v16, v17 offset1:1
	s_waitcnt vmcnt(3)
	ds_write2_b32 v54, v18, v19 offset1:1
	ds_write2_b32 v56, v20, v21 offset1:1
	s_waitcnt vmcnt(2)
	ds_write2_b32 v58, v22, v23 offset1:1
	ds_write2_b32 v65, v24, v25 offset1:1
	s_waitcnt vmcnt(1)
	ds_write2_b32 v66, v26, v27 offset1:1
	ds_write2_b32 v67, v28, v29 offset1:1
	s_waitcnt vmcnt(0)
	ds_write2_b32 v68, v30, v31 offset1:1
	ds_write2_b32 v69, v32, v33 offset1:1
	s_waitcnt lgkmcnt(0)
	ds_read2_b32 v[6:7], v53 offset0:33 offset1:41
	ds_read2_b32 v[8:9], v53 offset1:8
	ds_read2_b32 v[10:11], v53 offset0:66 offset1:74
	ds_read2_b32 v[12:13], v53 offset0:99 offset1:107
	ds_read2_b32 v[14:15], v53 offset0:132 offset1:140
	ds_read2_b32 v[16:17], v53 offset0:165 offset1:173
	ds_read2_b32 v[18:19], v53 offset0:198 offset1:206
	ds_read2_b32 v[20:21], v53 offset0:231 offset1:239
	s_waitcnt lgkmcnt(6)
	v_cvt_pk_bf16_f32 v2, v8, v6
	v_or_b32_e32 v6, s19, v1
	v_lshl_add_u64 v[22:23], s[2:3], 0, v[36:37]
	v_lshlrev_b32_e32 v36, 11, v6
	v_lshl_add_u64 v[24:25], v[22:23], 0, v[36:37]
	s_waitcnt lgkmcnt(4)
	v_cvt_pk_bf16_f32 v3, v10, v12
	s_waitcnt lgkmcnt(2)
	v_cvt_pk_bf16_f32 v4, v14, v16
	s_waitcnt lgkmcnt(0)
	v_cvt_pk_bf16_f32 v5, v18, v20
	global_store_dwordx4 v[24:25], v[2:5], off nt
	v_or_b32_e32 v6, s19, v45
	v_lshlrev_b32_e32 v36, 11, v6
	v_cvt_pk_bf16_f32 v2, v9, v7
	v_cvt_pk_bf16_f32 v3, v11, v13
	v_cvt_pk_bf16_f32 v4, v15, v17
	v_cvt_pk_bf16_f32 v5, v19, v21
	ds_read2_b32 v[8:9], v53 offset0:16 offset1:24
	ds_read2_b32 v[10:11], v53 offset0:49 offset1:57
	ds_read2_b32 v[12:13], v53 offset0:82 offset1:90
	ds_read2_b32 v[14:15], v53 offset0:115 offset1:123
	ds_read2_b32 v[16:17], v53 offset0:148 offset1:156
	ds_read2_b32 v[18:19], v53 offset0:181 offset1:189
	ds_read2_b32 v[20:21], v53 offset0:214 offset1:222
	ds_read2_b32 v[24:25], v53 offset0:247 offset1:255
	v_lshl_add_u64 v[6:7], v[22:23], 0, v[36:37]
	global_store_dwordx4 v[6:7], v[2:5], off nt
	v_or_b32_e32 v6, s19, v47
	v_lshlrev_b32_e32 v36, 11, v6
	v_lshl_add_u64 v[6:7], v[22:23], 0, v[36:37]
	s_waitcnt lgkmcnt(6)
	v_cvt_pk_bf16_f32 v2, v8, v10
	s_waitcnt lgkmcnt(4)
	v_cvt_pk_bf16_f32 v3, v12, v14
	s_waitcnt lgkmcnt(2)
	v_cvt_pk_bf16_f32 v4, v16, v18
	s_waitcnt lgkmcnt(0)
	v_cvt_pk_bf16_f32 v5, v20, v24
	global_store_dwordx4 v[6:7], v[2:5], off nt
	v_or_b32_e32 v6, s19, v51
	v_lshlrev_b32_e32 v36, 11, v6
	v_lshl_add_u64 v[6:7], v[22:23], 0, v[36:37]
	v_cvt_pk_bf16_f32 v2, v9, v11
	v_cvt_pk_bf16_f32 v3, v13, v15
	v_cvt_pk_bf16_f32 v4, v17, v19
	v_cvt_pk_bf16_f32 v5, v21, v25
	global_store_dwordx4 v[6:7], v[2:5], off nt
	s_waitcnt lgkmcnt(0)

; #define LAS __attribute__((address_space(3)))
; __device__ __forceinline__ void transpose_item(const float* W, int K, int N, const float* gain, bf16_t* WT, int dst_row0, LAS float* scr, int kb, int n0, int lane) {
;     const int k0 = 64 * kb, n4 = (lane & 7) * 4, kr = lane >> 3;
;     f32x4 v[8]; float g[8];
; #pragma unroll
;     for (int i = 0; i < 8; ++i) { v[i] = *(const f32x4*)(W + (size_t)(k0 + kr + 8 * i) * N + n0 + n4); g[i] = gain ? gain[k0 + kr + 8 * i] : 1.0f; }
; __device__ __forceinline__ void weight_item(const Params& P, unsigned char* ws, LAS float* scr, int l, int r, int lane) {
;     ...
;             else if (q == 1) transpose_item(P.in[23] + oS, D, D, P.in[21] + l * D, (bf16_t*)(ws + WS_WXQ) + oS, n0, scr, kb, n0, lane);
.LBB0_61:
	s_andn2_b64 vcc, exec, s[2:3]
	s_cbranch_vccnz .LBB0_79
	s_load_dwordx16 s[64:79], s[0:1], 0x80
	s_lshl_b64 s[2:3], s[22:23], 2
	v_mov_b32_e32 v43, v37
	v_cndmask_b32_e64 v6, 0, 1, s[6:7]
	v_mov_b32_e32 v44, 1.0
	s_waitcnt lgkmcnt(0)
	s_add_u32 s57, s78, s2
	s_addc_u32 s58, s79, s3
	s_lshl_b32 s2, s18, 10
	s_ashr_i32 s3, s2, 31
	s_lshl_b64 s[2:3], s[2:3], 2
	s_add_u32 s24, s74, s2
	s_addc_u32 s25, s75, s3
	s_lshl_b32 s16, s56, 6
	s_lshl_b32 s2, s19, 2
	s_add_u32 s2, s57, s2
	v_or_b32_e32 v32, s16, v1
	s_addc_u32 s3, s58, 0
	v_lshl_add_u64 v[30:31], s[2:3], 0, v[42:43]
	v_lshlrev_b32_e32 v36, 12, v32
	v_lshl_add_u64 v[2:3], v[30:31], 0, v[36:37]
	global_load_dwordx4 v[2:5], v[2:3], off nt
	v_cmp_ne_u32_e64 s[2:3], 1, v6
	s_andn2_b64 vcc, exec, s[6:7]
	v_lshlrev_b32_e32 v43, 2, v32
	v_mov_b32_e32 v46, 1.0
	s_cbranch_vccnz .LBB0_64
	global_load_dword v46, v43, s[24:25]

; #define LAS __attribute__((address_space(3)))
; __device__ __forceinline__ unsigned cvt_pk_bf16(float lo, float hi) { unsigned r; asm("v_cvt_pk_bf16_f32 %0, %1, %2" : "=v"(r) : "v"(lo), "v"(hi)); return r; }
; __device__ __forceinline__ void transpose_item(const float* W, int K, int N, const float* gain, bf16_t* WT, int dst_row0, LAS float* scr, int kb, int n0, int lane) {
;     ...
; #pragma unroll
;     for (int i = 0; i < 8; ++i) { LAS float* d = scr + (kr + 8 * i) * 33 + n4; d[0] = v[i][0] * g[i]; d[1] = v[i][1] * g[i]; d[2] = v[i][2] * g[i]; d[3] = v[i][3] * g[i]; }
;     asm volatile("s_waitcnt lgkmcnt(0)" ::: "memory");
;     const int c = lane & 7;
; #pragma unroll
;     for (int j = 0; j < 4; ++j) { const int n = (lane >> 3) + 8 * j; const LAS float* s = scr + (8 * c) * 33 + n;
;         u32x4 o; o.x = cvt_pk_bf16(s[0 * 33], s[1 * 33]); o.y = cvt_pk_bf16(s[2 * 33], s[3 * 33]); o.z = cvt_pk_bf16(s[4 * 33], s[5 * 33]); o.w = cvt_pk_bf16(s[6 * 33], s[7 * 33]);
;         *(u32x4*)(WT + (size_t)(dst_row0 + n) * K + k0 + 8 * c) = o; }
;     asm volatile("s_waitcnt lgkmcnt(0)" ::: "memory");
; __device__ __forceinline__ void weight_item(const Params& P, unsigned char* ws, LAS float* scr, int l, int r, int lane) {
;     ...
;             else if (q == 1) transpose_item(P.in[23] + oS, D, D, P.in[21] + l * D, (bf16_t*)(ws + WS_WXQ) + oS, n0, scr, kb, n0, lane);
.LBB0_78:
	s_waitcnt vmcnt(7)
	v_pk_mul_f32 v[2:3], v[2:3], v[46:47] op_sel_hi:[1,0]
	v_add_u32_e32 v36, v35, v39
	ds_write2_b32 v36, v2, v3 offset1:1
	v_pk_mul_f32 v[2:3], v[4:5], v[46:47] op_sel_hi:[1,0]
	ds_write2_b32 v36, v2, v3 offset0:2 offset1:3
	s_waitcnt vmcnt(6)
	v_pk_mul_f32 v[2:3], v[6:7], v[44:45] op_sel_hi:[1,0]
	v_add_u32_e32 v4, 0x420, v36
	ds_write2_b32 v4, v2, v3 offset1:1
	v_pk_mul_f32 v[2:3], v[8:9], v[44:45] op_sel_hi:[1,0]
	v_add_u32_e32 v4, 0x428, v36
	ds_write2_b32 v4, v2, v3 offset1:1
	s_waitcnt vmcnt(5)
	v_pk_mul_f32 v[2:3], v[10:11], v[50:51] op_sel_hi:[1,0]
	v_add_u32_e32 v4, 0x840, v36
	ds_write2_b32 v4, v2, v3 offset1:1
	v_pk_mul_f32 v[2:3], v[12:13], v[50:51] op_sel_hi:[1,0]
	v_add_u32_e32 v4, 0x848, v36
	ds_write2_b32 v4, v2, v3 offset1:1
	s_waitcnt vmcnt(4)
	v_pk_mul_f32 v[2:3], v[14:15], v[48:49] op_sel_hi:[1,0]
	v_add_u32_e32 v4, 0xc60, v36
	ds_write2_b32 v4, v2, v3 offset1:1
	v_pk_mul_f32 v[2:3], v[16:17], v[48:49] op_sel_hi:[1,0]
	v_add_u32_e32 v4, 0xc68, v36
	ds_write2_b32 v4, v2, v3 offset1:1
	s_waitcnt vmcnt(3)
	v_pk_mul_f32 v[2:3], v[18:19], v[56:57] op_sel_hi:[1,0]
	v_add_u32_e32 v4, 0x1080, v36
	ds_write2_b32 v4, v2, v3 offset1:1
	v_pk_mul_f32 v[2:3], v[20:21], v[56:57] op_sel_hi:[1,0]
	v_add_u32_e32 v4, 0x1088, v36
	ds_write2_b32 v4, v2, v3 offset1:1
	s_waitcnt vmcnt(2)
	v_pk_mul_f32 v[2:3], v[22:23], v[52:53] op_sel_hi:[1,0]
	v_add_u32_e32 v4, 0x14a0, v36
	ds_write2_b32 v4, v2, v3 offset1:1
	v_pk_mul_f32 v[2:3], v[24:25], v[52:53] op_sel_hi:[1,0]
	v_add_u32_e32 v4, 0x14a8, v36
	ds_write2_b32 v4, v2, v3 offset1:1
	s_waitcnt vmcnt(1)
	v_pk_mul_f32 v[2:3], v[26:27], v[58:59] op_sel_hi:[1,0]
	v_add_u32_e32 v4, 0x18c0, v36
	ds_write2_b32 v4, v2, v3 offset1:1
	v_pk_mul_f32 v[2:3], v[28:29], v[58:59] op_sel_hi:[1,0]
	v_add_u32_e32 v4, 0x18c8, v36
	ds_write2_b32 v4, v2, v3 offset1:1
	s_waitcnt vmcnt(0)
	v_pk_mul_f32 v[2:3], v[30:31], v[54:55] op_sel_hi:[1,0]
	v_add_u32_e32 v4, 0x1ce0, v36
	ds_write2_b32 v4, v2, v3 offset1:1
	v_pk_mul_f32 v[2:3], v[32:33], v[54:55] op_sel_hi:[1,0]
	v_add_u32_e32 v4, 0x1ce8, v36
	s_lshl_b64 s[2:3], s[22:23], 1
	ds_write2_b32 v4, v2, v3 offset1:1
	s_add_u32 s2, s36, s2
	s_waitcnt lgkmcnt(0)
	s_addc_u32 s3, s37, s3
	s_lshl_b32 s16, s16, 1
	ds_read2_b32 v[6:7], v53 offset0:33 offset1:41
	ds_read2_b32 v[8:9], v53 offset1:8
	ds_read2_b32 v[10:11], v53 offset0:66 offset1:74
	ds_read2_b32 v[12:13], v53 offset0:99 offset1:107
	ds_read2_b32 v[14:15], v53 offset0:132 offset1:140
	ds_read2_b32 v[16:17], v53 offset0:165 offset1:173
	ds_read2_b32 v[18:19], v53 offset0:198 offset1:206
	ds_read2_b32 v[20:21], v53 offset0:231 offset1:239
	s_add_u32 s2, s2, s16
	s_addc_u32 s3, s3, 0
	v_lshlrev_b32_e32 v36, 1, v38
	s_waitcnt lgkmcnt(6)
	v_cvt_pk_bf16_f32 v2, v8, v6
	v_or_b32_e32 v6, s19, v1
	v_lshl_add_u64 v[22:23], s[2:3], 0, v[36:37]
	v_lshlrev_b32_e32 v36, 11, v6
	v_lshl_add_u64 v[24:25], v[22:23], 0, v[36:37]
	s_waitcnt lgkmcnt(4)
	v_cvt_pk_bf16_f32 v3, v10, v12
	s_waitcnt lgkmcnt(2)
	v_cvt_pk_bf16_f32 v4, v14, v16
	s_waitcnt lgkmcnt(0)
	v_cvt_pk_bf16_f32 v5, v18, v20
	global_store_dwordx4 v[24:25], v[2:5], off nt
	v_or_b32_e32 v6, s19, v45
	v_lshlrev_b32_e32 v36, 11, v6
	v_cvt_pk_bf16_f32 v2, v9, v7
	v_cvt_pk_bf16_f32 v3, v11, v13
	v_cvt_pk_bf16_f32 v4, v15, v17
	v_cvt_pk_bf16_f32 v5, v19, v21
	ds_read2_b32 v[8:9], v53 offset0:16 offset1:24
	ds_read2_b32 v[10:11], v53 offset0:49 offset1:57
	ds_read2_b32 v[12:13], v53 offset0:82 offset1:90
	ds_read2_b32 v[14:15], v53 offset0:115 offset1:123
	ds_read2_b32 v[16:17], v53 offset0:148 offset1:156
	ds_read2_b32 v[18:19], v53 offset0:181 offset1:189
	ds_read2_b32 v[20:21], v53 offset0:214 offset1:222
	ds_read2_b32 v[24:25], v53 offset0:247 offset1:255
	v_lshl_add_u64 v[6:7], v[22:23], 0, v[36:37]
	global_store_dwordx4 v[6:7], v[2:5], off nt
	v_or_b32_e32 v6, s19, v47
	v_lshlrev_b32_e32 v36, 11, v6
	v_lshl_add_u64 v[6:7], v[22:23], 0, v[36:37]
	s_waitcnt lgkmcnt(6)
	v_cvt_pk_bf16_f32 v2, v8, v10
	s_waitcnt lgkmcnt(4)
	v_cvt_pk_bf16_f32 v3, v12, v14
	s_waitcnt lgkmcnt(2)
	v_cvt_pk_bf16_f32 v4, v16, v18
	s_waitcnt lgkmcnt(0)
	v_cvt_pk_bf16_f32 v5, v20, v24
	global_store_dwordx4 v[6:7], v[2:5], off nt
	v_or_b32_e32 v6, s19, v51
	v_lshlrev_b32_e32 v36, 11, v6
	v_lshl_add_u64 v[6:7], v[22:23], 0, v[36:37]
	v_cvt_pk_bf16_f32 v2, v9, v11
	v_cvt_pk_bf16_f32 v3, v13, v15
	v_cvt_pk_bf16_f32 v4, v17, v19
	v_cvt_pk_bf16_f32 v5, v21, v25
	global_store_dwordx4 v[6:7], v[2:5], off nt
	s_waitcnt lgkmcnt(0)

; #define LAS __attribute__((address_space(3)))
; __device__ __forceinline__ void transpose_item(const float* W, int K, int N, const float* gain, bf16_t* WT, int dst_row0, LAS float* scr, int kb, int n0, int lane) {
;     const int k0 = 64 * kb, n4 = (lane & 7) * 4, kr = lane >> 3;
;     f32x4 v[8]; float g[8];
; #pragma unroll
;     for (int i = 0; i < 8; ++i) { v[i] = *(const f32x4*)(W + (size_t)(k0 + kr + 8 * i) * N + n0 + n4); g[i] = gain ? gain[k0 + kr + 8 * i] : 1.0f; }
; __device__ __forceinline__ void weight_item(const Params& P, unsigned char* ws, LAS float* scr, int l, int r, int lane) {
;     ...
;             if (q == 0) transpose_item(P.in[20] + oS, D, D, P.in[19] + l * D, (bf16_t*)(ws + WS_WOUT) + oS, n0, scr, kb, n0, lane);
.LBB0_80:
	s_and_b64 vcc, exec, s[2:3]
	s_cbranch_vccz .LBB0_197
	s_load_dwordx16 s[64:79], s[0:1], 0x80
	s_lshl_b64 s[2:3], s[22:23], 2
	v_mov_b32_e32 v43, v37
	v_cndmask_b32_e64 v6, 0, 1, s[8:9]
	v_mov_b32_e32 v44, 1.0
	s_waitcnt lgkmcnt(0)
	s_add_u32 s57, s72, s2
	s_addc_u32 s58, s73, s3
	s_lshl_b32 s2, s18, 10
	s_ashr_i32 s3, s2, 31
	s_lshl_b64 s[2:3], s[2:3], 2
	s_add_u32 s24, s70, s2
	s_addc_u32 s25, s71, s3
	s_lshl_b32 s16, s56, 6
	s_lshl_b32 s2, s19, 2
	s_add_u32 s2, s57, s2
	v_or_b32_e32 v32, s16, v1
	s_addc_u32 s3, s58, 0
	v_lshl_add_u64 v[30:31], s[2:3], 0, v[42:43]
	v_lshlrev_b32_e32 v36, 12, v32
	v_lshl_add_u64 v[2:3], v[30:31], 0, v[36:37]
	global_load_dwordx4 v[2:5], v[2:3], off nt
	v_cmp_ne_u32_e64 s[2:3], 1, v6
	s_andn2_b64 vcc, exec, s[8:9]
	v_lshlrev_b32_e32 v43, 2, v32
	v_mov_b32_e32 v46, 1.0
	s_cbranch_vccnz .LBB0_83
	global_load_dword v46, v43, s[24:25]

; #define LAS __attribute__((address_space(3)))
; __device__ __forceinline__ unsigned cvt_pk_bf16(float lo, float hi) { unsigned r; asm("v_cvt_pk_bf16_f32 %0, %1, %2" : "=v"(r) : "v"(lo), "v"(hi)); return r; }
; __device__ __forceinline__ void transpose_item(const float* W, int K, int N, const float* gain, bf16_t* WT, int dst_row0, LAS float* scr, int kb, int n0, int lane) {
;     ...
;     for (int i = 0; i < 8; ++i) { LAS float* d = scr + (kr + 8 * i) * 33 + n4; d[0] = v[i][0] * g[i]; d[1] = v[i][1] * g[i]; d[2] = v[i][2] * g[i]; d[3] = v[i][3] * g[i]; }
;     asm volatile("s_waitcnt lgkmcnt(0)" ::: "memory");
;     const int c = lane & 7;
; #pragma unroll
;     for (int j = 0; j < 4; ++j) { const int n = (lane >> 3) + 8 * j; const LAS float* s = scr + (8 * c) * 33 + n;
;         u32x4 o; o.x = cvt_pk_bf16(s[0 * 33], s[1 * 33]); o.y = cvt_pk_bf16(s[2 * 33], s[3 * 33]); o.z = cvt_pk_bf16(s[4 * 33], s[5 * 33]); o.w = cvt_pk_bf16(s[6 * 33], s[7 * 33]);
;         *(u32x4*)(WT + (size_t)(dst_row0 + n) * K + k0 + 8 * c) = o; }
.LBB0_97:
	s_waitcnt vmcnt(7)
	v_pk_mul_f32 v[2:3], v[2:3], v[46:47] op_sel_hi:[1,0]
	v_add_u32_e32 v36, v35, v39
	ds_write2_b32 v36, v2, v3 offset1:1
	v_pk_mul_f32 v[2:3], v[4:5], v[46:47] op_sel_hi:[1,0]
	ds_write2_b32 v36, v2, v3 offset0:2 offset1:3
	s_waitcnt vmcnt(6)
	v_pk_mul_f32 v[2:3], v[6:7], v[44:45] op_sel_hi:[1,0]
	v_add_u32_e32 v4, 0x420, v36
	ds_write2_b32 v4, v2, v3 offset1:1
	v_pk_mul_f32 v[2:3], v[8:9], v[44:45] op_sel_hi:[1,0]
	v_add_u32_e32 v4, 0x428, v36
	ds_write2_b32 v4, v2, v3 offset1:1
	s_waitcnt vmcnt(5)
	v_pk_mul_f32 v[2:3], v[10:11], v[50:51] op_sel_hi:[1,0]
	v_add_u32_e32 v4, 0x840, v36
	ds_write2_b32 v4, v2, v3 offset1:1
	v_pk_mul_f32 v[2:3], v[12:13], v[50:51] op_sel_hi:[1,0]
	v_add_u32_e32 v4, 0x848, v36
	ds_write2_b32 v4, v2, v3 offset1:1
	s_waitcnt vmcnt(4)
	v_pk_mul_f32 v[2:3], v[14:15], v[48:49] op_sel_hi:[1,0]
	v_add_u32_e32 v4, 0xc60, v36
	ds_write2_b32 v4, v2, v3 offset1:1
	v_pk_mul_f32 v[2:3], v[16:17], v[48:49] op_sel_hi:[1,0]
	v_add_u32_e32 v4, 0xc68, v36
	ds_write2_b32 v4, v2, v3 offset1:1
	s_waitcnt vmcnt(3)
	v_pk_mul_f32 v[2:3], v[18:19], v[56:57] op_sel_hi:[1,0]
	v_add_u32_e32 v4, 0x1080, v36
	ds_write2_b32 v4, v2, v3 offset1:1
	v_pk_mul_f32 v[2:3], v[20:21], v[56:57] op_sel_hi:[1,0]
	v_add_u32_e32 v4, 0x1088, v36
	ds_write2_b32 v4, v2, v3 offset1:1
	s_waitcnt vmcnt(2)
	v_pk_mul_f32 v[2:3], v[22:23], v[52:53] op_sel_hi:[1,0]
	v_add_u32_e32 v4, 0x14a0, v36
	ds_write2_b32 v4, v2, v3 offset1:1
	v_pk_mul_f32 v[2:3], v[24:25], v[52:53] op_sel_hi:[1,0]
	v_add_u32_e32 v4, 0x14a8, v36
	ds_write2_b32 v4, v2, v3 offset1:1
	s_waitcnt vmcnt(1)
	v_pk_mul_f32 v[2:3], v[26:27], v[58:59] op_sel_hi:[1,0]
	v_add_u32_e32 v4, 0x18c0, v36
	ds_write2_b32 v4, v2, v3 offset1:1
	v_pk_mul_f32 v[2:3], v[28:29], v[58:59] op_sel_hi:[1,0]
	v_add_u32_e32 v4, 0x18c8, v36
	ds_write2_b32 v4, v2, v3 offset1:1
	s_waitcnt vmcnt(0)
	v_pk_mul_f32 v[2:3], v[30:31], v[54:55] op_sel_hi:[1,0]
	v_add_u32_e32 v4, 0x1ce0, v36
	ds_write2_b32 v4, v2, v3 offset1:1
	v_pk_mul_f32 v[2:3], v[32:33], v[54:55] op_sel_hi:[1,0]
	v_add_u32_e32 v4, 0x1ce8, v36
	s_lshl_b64 s[2:3], s[22:23], 1
	ds_write2_b32 v4, v2, v3 offset1:1
	s_add_u32 s2, s38, s2
	s_waitcnt lgkmcnt(0)
	s_addc_u32 s3, s39, s3
	s_lshl_b32 s16, s16, 1
	ds_read2_b32 v[6:7], v53 offset0:33 offset1:41
	ds_read2_b32 v[8:9], v53 offset1:8
	ds_read2_b32 v[10:11], v53 offset0:66 offset1:74
	ds_read2_b32 v[12:13], v53 offset0:99 offset1:107
	ds_read2_b32 v[14:15], v53 offset0:132 offset1:140
	ds_read2_b32 v[16:17], v53 offset0:165 offset1:173
	ds_read2_b32 v[18:19], v53 offset0:198 offset1:206
	ds_read2_b32 v[20:21], v53 offset0:231 offset1:239
	s_add_u32 s2, s2, s16
	s_addc_u32 s3, s3, 0
	v_lshlrev_b32_e32 v36, 1, v38
	s_waitcnt lgkmcnt(6)
	v_cvt_pk_bf16_f32 v2, v8, v6
	v_or_b32_e32 v6, s19, v1
	v_lshl_add_u64 v[22:23], s[2:3], 0, v[36:37]
	v_lshlrev_b32_e32 v36, 11, v6
	v_lshl_add_u64 v[24:25], v[22:23], 0, v[36:37]
	s_waitcnt lgkmcnt(4)
	v_cvt_pk_bf16_f32 v3, v10, v12
	s_waitcnt lgkmcnt(2)
	v_cvt_pk_bf16_f32 v4, v14, v16
	s_waitcnt lgkmcnt(0)
	v_cvt_pk_bf16_f32 v5, v18, v20
	global_store_dwordx4 v[24:25], v[2:5], off nt
	v_or_b32_e32 v6, s19, v45
	v_lshlrev_b32_e32 v36, 11, v6
	v_cvt_pk_bf16_f32 v2, v9, v7
	v_cvt_pk_bf16_f32 v3, v11, v13
	v_cvt_pk_bf16_f32 v4, v15, v17
	v_cvt_pk_bf16_f32 v5, v19, v21
	ds_read2_b32 v[8:9], v53 offset0:16 offset1:24
	ds_read2_b32 v[10:11], v53 offset0:49 offset1:57
	ds_read2_b32 v[12:13], v53 offset0:82 offset1:90
	ds_read2_b32 v[14:15], v53 offset0:115 offset1:123
	ds_read2_b32 v[16:17], v53 offset0:148 offset1:156
	ds_read2_b32 v[18:19], v53 offset0:181 offset1:189
	ds_read2_b32 v[20:21], v53 offset0:214 offset1:222
	ds_read2_b32 v[24:25], v53 offset0:247 offset1:255
	v_lshl_add_u64 v[6:7], v[22:23], 0, v[36:37]
	global_store_dwordx4 v[6:7], v[2:5], off nt
	v_or_b32_e32 v6, s19, v47
	v_lshlrev_b32_e32 v36, 11, v6
	v_lshl_add_u64 v[6:7], v[22:23], 0, v[36:37]
	s_waitcnt lgkmcnt(6)
	v_cvt_pk_bf16_f32 v2, v8, v10
	s_waitcnt lgkmcnt(4)
	v_cvt_pk_bf16_f32 v3, v12, v14
	s_waitcnt lgkmcnt(2)
	v_cvt_pk_bf16_f32 v4, v16, v18
	s_waitcnt lgkmcnt(0)
	v_cvt_pk_bf16_f32 v5, v20, v24
	global_store_dwordx4 v[6:7], v[2:5], off nt
	v_or_b32_e32 v6, s19, v51
	v_lshlrev_b32_e32 v36, 11, v6
	v_lshl_add_u64 v[6:7], v[22:23], 0, v[36:37]
	v_cvt_pk_bf16_f32 v2, v9, v11
	v_cvt_pk_bf16_f32 v3, v13, v15
	v_cvt_pk_bf16_f32 v4, v17, v19
	v_cvt_pk_bf16_f32 v5, v21, v25
	global_store_dwordx4 v[6:7], v[2:5], off nt
	s_waitcnt lgkmcnt(0)
	s_mov_b64 s[2:3], 0

; __device__ __forceinline__ void transpose_item(const float* W, int K, int N, const float* gain, bf16_t* WT, int dst_row0, LAS float* scr, int kb, int n0, int lane) {
;     const int k0 = 64 * kb, n4 = (lane & 7) * 4, kr = lane >> 3;
;     f32x4 v[8]; float g[8];
; #pragma unroll
;     for (int i = 0; i < 8; ++i) { v[i] = *(const f32x4*)(W + (size_t)(k0 + kr + 8 * i) * N + n0 + n4); g[i] = gain ? gain[k0 + kr + 8 * i] : 1.0f; }
; __device__ __forceinline__ void weight_item(const Params& P, unsigned char* ws, LAS float* scr, int l, int r, int lane) {
;     ...
;         if (r < I_IN) { const int kb = r / 80, n0 = (r % 80) * 32; transpose_item(P.in[14] + (size_t)l * D * DIN, D, DIN, P.in[13] + l * D, (bf16_t*)(ws + WS_WIN) + (size_t)l * DIN * D, n0, scr, kb, n0, lane); return; }
.LBB0_99:
	s_add_i32 s2, s51, 0xdf00
	s_and_b32 s3, s2, 0xffff
	s_load_dwordx16 s[64:79], s[0:1], 0x40
	s_mul_i32 s3, s3, 0xcccd
	s_lshr_b32 s16, s3, 16
	s_lshr_b32 s3, s3, 22
	s_mulk_i32 s3, 0x50
	s_sub_i32 s19, s2, s3
	s_mul_i32 s3, s18, 0xa00000
	s_mul_hi_i32 s2, s18, 0xa00000
	s_waitcnt lgkmcnt(0)
	s_add_u32 s24, s76, s3
	s_addc_u32 s25, s77, s2
	s_lshl_b32 s2, s18, 10
	s_ashr_i32 s3, s2, 31
	s_lshl_b64 s[2:3], s[2:3], 2
	s_add_u32 s22, s74, s2
	s_addc_u32 s23, s75, s3
	s_lshl_b32 s2, s19, 7
	s_and_b32 s16, s16, 0xffc0
	s_and_b32 s2, s2, 0x3ff80
	s_add_u32 s2, s24, s2
	s_addc_u32 s3, s25, 0
	v_mov_b32_e32 v43, v37
	v_or_b32_e32 v32, s16, v1
	v_lshl_add_u64 v[30:31], s[2:3], 0, v[42:43]
	v_mad_u64_u32 v[2:3], s[2:3], v32, s46, v[30:31]
	global_load_dwordx4 v[2:5], v[2:3], off nt
	v_cndmask_b32_e64 v6, 0, 1, s[10:11]
	v_mov_b32_e32 v36, 1.0
	v_cmp_ne_u32_e64 s[2:3], 1, v6
	s_andn2_b64 vcc, exec, s[10:11]
	v_lshlrev_b32_e32 v43, 2, v32
	v_mov_b32_e32 v46, 1.0
	s_cbranch_vccnz .LBB0_101
	global_load_dword v46, v43, s[22:23]
.LBB0_101:
	v_or_b32_e32 v6, 8, v32
	v_mad_u64_u32 v[6:7], s[24:25], v6, s46, v[30:31]
	global_load_dwordx4 v[6:9], v[6:7], off nt
	s_and_b64 vcc, exec, s[2:3]
	s_cbranch_vccnz .LBB0_103
	global_load_dword v36, v43, s[22:23] offset:32
.LBB0_103:
	v_or_b32_e32 v10, 16, v32
	v_mad_u64_u32 v[10:11], s[24:25], v10, s46, v[30:31]
	global_load_dwordx4 v[10:13], v[10:11], off nt
	v_mov_b32_e32 v44, 1.0
	s_and_b64 vcc, exec, s[2:3]
	v_mov_b32_e32 v50, 1.0
	s_cbranch_vccnz .LBB0_105
	global_load_dword v50, v43, s[22:23] offset:64
.LBB0_105:
	v_or_b32_e32 v14, 24, v32
	v_mad_u64_u32 v[14:15], s[24:25], v14, s46, v[30:31]
	global_load_dwordx4 v[14:17], v[14:15], off nt
	s_and_b64 vcc, exec, s[2:3]
	s_cbranch_vccnz .LBB0_107
	global_load_dword v44, v43, s[22:23] offset:96
.LBB0_107:
	v_or_b32_e32 v18, 32, v32
	v_mad_u64_u32 v[18:19], s[24:25], v18, s46, v[30:31]
	global_load_dwordx4 v[18:21], v[18:19], off nt
	v_mov_b32_e32 v48, 1.0
	s_and_b64 vcc, exec, s[2:3]
	v_mov_b32_e32 v54, 1.0
	s_cbranch_vccnz .LBB0_109
	global_load_dword v54, v43, s[22:23] offset:128
.LBB0_109:
	v_or_b32_e32 v22, 40, v32
	v_mad_u64_u32 v[22:23], s[24:25], v22, s46, v[30:31]
	global_load_dwordx4 v[22:25], v[22:23], off nt
	s_and_b64 vcc, exec, s[2:3]
	s_cbranch_vccnz .LBB0_111
	global_load_dword v48, v43, s[22:23] offset:160
.LBB0_111:
	v_or_b32_e32 v26, 48, v32
	v_mad_u64_u32 v[26:27], s[24:25], v26, s46, v[30:31]
	global_load_dwordx4 v[26:29], v[26:27], off nt
	v_mov_b32_e32 v52, 1.0
	s_and_b64 vcc, exec, s[2:3]
	v_mov_b32_e32 v56, 1.0
	s_cbranch_vccnz .LBB0_113
	global_load_dword v56, v43, s[22:23] offset:192
.LBB0_113:
	v_or_b32_e32 v32, 56, v32
	v_mad_u64_u32 v[30:31], s[24:25], v32, s46, v[30:31]
	global_load_dwordx4 v[30:33], v[30:31], off nt
	s_and_b64 vcc, exec, s[2:3]
	s_lshl_b32 s2, s19, 5
	s_cbranch_vccnz .LBB0_115
	global_load_dword v52, v43, s[22:23] offset:224
; #define LAS __attribute__((address_space(3)))
; __device__ __forceinline__ unsigned cvt_pk_bf16(float lo, float hi) { unsigned r; asm("v_cvt_pk_bf16_f32 %0, %1, %2" : "=v"(r) : "v"(lo), "v"(hi)); return r; }
; __device__ __forceinline__ void transpose_item(const float* W, int K, int N, const float* gain, bf16_t* WT, int dst_row0, LAS float* scr, int kb, int n0, int lane) {
;     ...
;     for (int i = 0; i < 8; ++i) { LAS float* d = scr + (kr + 8 * i) * 33 + n4; d[0] = v[i][0] * g[i]; d[1] = v[i][1] * g[i]; d[2] = v[i][2] * g[i]; d[3] = v[i][3] * g[i]; }
;     asm volatile("s_waitcnt lgkmcnt(0)" ::: "memory");
;     const int c = lane & 7;
; #pragma unroll
;     for (int j = 0; j < 4; ++j) { const int n = (lane >> 3) + 8 * j; const LAS float* s = scr + (8 * c) * 33 + n;
;         u32x4 o; o.x = cvt_pk_bf16(s[0 * 33], s[1 * 33]); o.y = cvt_pk_bf16(s[2 * 33], s[3 * 33]); o.z = cvt_pk_bf16(s[4 * 33], s[5 * 33]); o.w = cvt_pk_bf16(s[6 * 33], s[7 * 33]);
;         *(u32x4*)(WT + (size_t)(dst_row0 + n) * K + k0 + 8 * c) = o; }
; __device__ __forceinline__ void weight_item(const Params& P, unsigned char* ws, LAS float* scr, int l, int r, int lane) {
;     ...
;         if (r < I_IN) { const int kb = r / 80, n0 = (r % 80) * 32; transpose_item(P.in[14] + (size_t)l * D * DIN, D, DIN, P.in[13] + l * D, (bf16_t*)(ws + WS_WIN) + (size_t)l * DIN * D, n0, scr, kb, n0, lane); return; }
.LBB0_115:
	s_waitcnt vmcnt(7)
	v_pk_mul_f32 v[2:3], v[2:3], v[46:47] op_sel_hi:[1,0]
	v_add_u32_e32 v43, v35, v39
	ds_write2_b32 v43, v2, v3 offset1:1
	v_pk_mul_f32 v[2:3], v[4:5], v[46:47] op_sel_hi:[1,0]
	ds_write2_b32 v43, v2, v3 offset0:2 offset1:3
	s_waitcnt vmcnt(6)
	v_pk_mul_f32 v[2:3], v[6:7], v[36:37] op_sel_hi:[1,0]
	v_add_u32_e32 v4, 0x420, v43
	ds_write2_b32 v4, v2, v3 offset1:1
	v_pk_mul_f32 v[2:3], v[8:9], v[36:37] op_sel_hi:[1,0]
	v_add_u32_e32 v4, 0x428, v43
	ds_write2_b32 v4, v2, v3 offset1:1
	s_waitcnt vmcnt(5)
	v_pk_mul_f32 v[2:3], v[10:11], v[50:51] op_sel_hi:[1,0]
	v_add_u32_e32 v4, 0x840, v43
	ds_write2_b32 v4, v2, v3 offset1:1
	v_pk_mul_f32 v[2:3], v[12:13], v[50:51] op_sel_hi:[1,0]
	v_add_u32_e32 v4, 0x848, v43
	ds_write2_b32 v4, v2, v3 offset1:1
	s_waitcnt vmcnt(4)
	v_pk_mul_f32 v[2:3], v[14:15], v[44:45] op_sel_hi:[1,0]
	v_add_u32_e32 v4, 0xc60, v43
	ds_write2_b32 v4, v2, v3 offset1:1
	v_pk_mul_f32 v[2:3], v[16:17], v[44:45] op_sel_hi:[1,0]
	v_add_u32_e32 v4, 0xc68, v43
	ds_write2_b32 v4, v2, v3 offset1:1
	s_waitcnt vmcnt(3)
	v_pk_mul_f32 v[2:3], v[18:19], v[54:55] op_sel_hi:[1,0]
	v_add_u32_e32 v4, 0x1080, v43
	ds_write2_b32 v4, v2, v3 offset1:1
	v_pk_mul_f32 v[2:3], v[20:21], v[54:55] op_sel_hi:[1,0]
	v_add_u32_e32 v4, 0x1088, v43
	ds_write2_b32 v4, v2, v3 offset1:1
	s_waitcnt vmcnt(2)
	v_pk_mul_f32 v[2:3], v[22:23], v[48:49] op_sel_hi:[1,0]
	v_add_u32_e32 v4, 0x14a0, v43
	ds_write2_b32 v4, v2, v3 offset1:1
	v_pk_mul_f32 v[2:3], v[24:25], v[48:49] op_sel_hi:[1,0]
	v_add_u32_e32 v4, 0x14a8, v43
	ds_write2_b32 v4, v2, v3 offset1:1
	s_waitcnt vmcnt(1)
	v_pk_mul_f32 v[2:3], v[26:27], v[56:57] op_sel_hi:[1,0]
	v_add_u32_e32 v4, 0x18c0, v43
	ds_write2_b32 v4, v2, v3 offset1:1
	v_pk_mul_f32 v[2:3], v[28:29], v[56:57] op_sel_hi:[1,0]
	v_add_u32_e32 v4, 0x18c8, v43
	ds_write2_b32 v4, v2, v3 offset1:1
	s_waitcnt vmcnt(0)
	v_pk_mul_f32 v[2:3], v[30:31], v[52:53] op_sel_hi:[1,0]
	v_add_u32_e32 v4, 0x1ce0, v43
	s_and_b32 s19, 0xffff, s2
	s_mul_i32 s3, s18, 0x500000
	ds_write2_b32 v4, v2, v3 offset1:1
	v_pk_mul_f32 v[2:3], v[32:33], v[52:53] op_sel_hi:[1,0]
	v_add_u32_e32 v4, 0x1ce8, v43
	s_mul_hi_i32 s2, s18, 0x500000
	s_add_u32 s3, s40, s3
	ds_write2_b32 v4, v2, v3 offset1:1
	s_addc_u32 s22, s41, s2
	s_waitcnt lgkmcnt(0)
	s_and_b32 s2, 0xffff, s16
	s_lshl_b32 s2, s2, 1
	ds_read2_b32 v[6:7], v53 offset0:33 offset1:41
	ds_read2_b32 v[8:9], v53 offset1:8
	ds_read2_b32 v[10:11], v53 offset0:66 offset1:74
	ds_read2_b32 v[12:13], v53 offset0:99 offset1:107
	ds_read2_b32 v[14:15], v53 offset0:132 offset1:140
	ds_read2_b32 v[16:17], v53 offset0:165 offset1:173
	ds_read2_b32 v[18:19], v53 offset0:198 offset1:206
	ds_read2_b32 v[20:21], v53 offset0:231 offset1:239
	s_add_u32 s2, s3, s2
	s_addc_u32 s3, s22, 0
	v_lshlrev_b32_e32 v36, 1, v38
	s_waitcnt lgkmcnt(6)
	v_cvt_pk_bf16_f32 v2, v8, v6
	v_or_b32_e32 v6, s19, v1
	v_lshl_add_u64 v[22:23], s[2:3], 0, v[36:37]
	v_lshlrev_b32_e32 v36, 11, v6
	v_lshl_add_u64 v[24:25], v[22:23], 0, v[36:37]
	s_waitcnt lgkmcnt(4)
	v_cvt_pk_bf16_f32 v3, v10, v12
	s_waitcnt lgkmcnt(2)
	v_cvt_pk_bf16_f32 v4, v14, v16
	s_waitcnt lgkmcnt(0)
	v_cvt_pk_bf16_f32 v5, v18, v20
	global_store_dwordx4 v[24:25], v[2:5], off nt
	v_or_b32_e32 v6, s19, v45
	v_lshlrev_b32_e32 v36, 11, v6
	v_cvt_pk_bf16_f32 v2, v9, v7
	v_cvt_pk_bf16_f32 v3, v11, v13
	v_cvt_pk_bf16_f32 v4, v15, v17
	v_cvt_pk_bf16_f32 v5, v19, v21
	ds_read2_b32 v[8:9], v53 offset0:16 offset1:24
	ds_read2_b32 v[10:11], v53 offset0:49 offset1:57
	ds_read2_b32 v[12:13], v53 offset0:82 offset1:90
	ds_read2_b32 v[14:15], v53 offset0:115 offset1:123
	ds_read2_b32 v[16:17], v53 offset0:148 offset1:156
	ds_read2_b32 v[18:19], v53 offset0:181 offset1:189
	ds_read2_b32 v[20:21], v53 offset0:214 offset1:222
	ds_read2_b32 v[24:25], v53 offset0:247 offset1:255
	v_lshl_add_u64 v[6:7], v[22:23], 0, v[36:37]
	global_store_dwordx4 v[6:7], v[2:5], off nt
	v_or_b32_e32 v6, s19, v47
	v_lshlrev_b32_e32 v36, 11, v6
	v_lshl_add_u64 v[6:7], v[22:23], 0, v[36:37]
	s_waitcnt lgkmcnt(6)
	v_cvt_pk_bf16_f32 v2, v8, v10
	s_waitcnt lgkmcnt(4)
	v_cvt_pk_bf16_f32 v3, v12, v14
	s_waitcnt lgkmcnt(2)
	v_cvt_pk_bf16_f32 v4, v16, v18
	s_waitcnt lgkmcnt(0)
	v_cvt_pk_bf16_f32 v5, v20, v24
	global_store_dwordx4 v[6:7], v[2:5], off nt
	v_or_b32_e32 v6, s19, v51
	v_lshlrev_b32_e32 v36, 11, v6
	v_lshl_add_u64 v[6:7], v[22:23], 0, v[36:37]
	v_cvt_pk_bf16_f32 v2, v9, v11
	v_cvt_pk_bf16_f32 v3, v13, v15
	v_cvt_pk_bf16_f32 v4, v17, v19
	v_cvt_pk_bf16_f32 v5, v21, v25
	global_store_dwordx4 v[6:7], v[2:5], off nt
	s_waitcnt lgkmcnt(0)

; #define LAS __attribute__((address_space(3)))
; __device__ __forceinline__ unsigned cvt_pk_bf16(float lo, float hi) { unsigned r; asm("v_cvt_pk_bf16_f32 %0, %1, %2" : "=v"(r) : "v"(lo), "v"(hi)); return r; }
; __device__ __forceinline__ void transpose_item(const float* W, int K, int N, const float* gain, bf16_t* WT, int dst_row0, LAS float* scr, int kb, int n0, int lane) {
;     const int k0 = 64 * kb, n4 = (lane & 7) * 4, kr = lane >> 3;
;     f32x4 v[8]; float g[8];
; #pragma unroll
;     for (int i = 0; i < 8; ++i) { v[i] = *(const f32x4*)(W + (size_t)(k0 + kr + 8 * i) * N + n0 + n4); g[i] = gain ? gain[k0 + kr + 8 * i] : 1.0f; }
; #pragma unroll
;     for (int i = 0; i < 8; ++i) { LAS float* d = scr + (kr + 8 * i) * 33 + n4; d[0] = v[i][0] * g[i]; d[1] = v[i][1] * g[i]; d[2] = v[i][2] * g[i]; d[3] = v[i][3] * g[i]; }
;     asm volatile("s_waitcnt lgkmcnt(0)" ::: "memory");
;     const int c = lane & 7;
; #pragma unroll
;     for (int j = 0; j < 4; ++j) { const int n = (lane >> 3) + 8 * j; const LAS float* s = scr + (8 * c) * 33 + n;
;         u32x4 o; o.x = cvt_pk_bf16(s[0 * 33], s[1 * 33]); o.y = cvt_pk_bf16(s[2 * 33], s[3 * 33]); o.z = cvt_pk_bf16(s[4 * 33], s[5 * 33]); o.w = cvt_pk_bf16(s[6 * 33], s[7 * 33]);
;         *(u32x4*)(WT + (size_t)(dst_row0 + n) * K + k0 + 8 * c) = o; }
; __device__ __forceinline__ void weight_item(const Params& P, unsigned char* ws, LAS float* scr, int l, int r, int lane) {
;     ...
;         if (r < I_DN) { const int kb = r / 32, n0 = (r % 32) * 32; transpose_item(P.in[30] + oU, DFF, D, nullptr, WDb, n0, scr, kb, n0, lane); return; }
.LBB0_117:
	s_andn2_b64 vcc, exec, s[2:3]
	s_cbranch_vccnz .LBB0_119
	s_load_dwordx16 s[64:79], s[0:1], 0xc0
	s_and_b32 s2, s44, 0x3e0
	s_lshl_b64 s[22:23], s[20:21], 2
	s_mul_i32 s16, s18, 0xffffa000
	v_mov_b32_e32 v43, v37
	s_waitcnt lgkmcnt(0)
	s_add_u32 s3, s76, s22
	s_addc_u32 s19, s77, s23
	s_add_i32 s16, s42, s16
	s_and_b32 s16, s16, 0x7fc0
	s_addk_i32 s16, 0xc900
	s_lshl_b32 s22, s2, 2
	v_or_b32_e32 v36, s16, v1
	s_add_u32 s22, s3, s22
	s_addc_u32 s23, s19, 0
	v_or_b32_e32 v4, 8, v36
	v_mov_b32_e32 v5, v37
	v_or_b32_e32 v10, 16, v36
	v_mov_b32_e32 v11, v37
	v_or_b32_e32 v12, 24, v36
	v_mov_b32_e32 v13, v37
	v_or_b32_e32 v18, 32, v36
	v_mov_b32_e32 v19, v37
	v_or_b32_e32 v20, 40, v36
	v_mov_b32_e32 v21, v37
	v_lshl_add_u64 v[30:31], s[22:23], 0, v[42:43]
	v_lshlrev_b64 v[2:3], 12, v[36:37]
	v_lshlrev_b64 v[4:5], 12, v[4:5]
	v_lshlrev_b64 v[10:11], 12, v[10:11]
	v_lshlrev_b64 v[12:13], 12, v[12:13]
	v_lshlrev_b64 v[18:19], 12, v[18:19]
	v_lshlrev_b64 v[20:21], 12, v[20:21]
	v_lshl_add_u64 v[2:3], v[30:31], 0, v[2:3]
	v_lshl_add_u64 v[6:7], v[30:31], 0, v[4:5]
	v_lshl_add_u64 v[10:11], v[30:31], 0, v[10:11]
	v_lshl_add_u64 v[14:15], v[30:31], 0, v[12:13]
	v_lshl_add_u64 v[18:19], v[30:31], 0, v[18:19]
	v_lshl_add_u64 v[22:23], v[30:31], 0, v[20:21]
	global_load_dwordx4 v[2:5], v[2:3], off nt
	s_nop 0
	global_load_dwordx4 v[6:9], v[6:7], off nt
	s_nop 0
	global_load_dwordx4 v[10:13], v[10:11], off nt
	s_nop 0
	global_load_dwordx4 v[14:17], v[14:15], off nt
	s_nop 0
	global_load_dwordx4 v[18:21], v[18:19], off nt
	s_nop 0
	global_load_dwordx4 v[22:25], v[22:23], off nt
	v_or_b32_e32 v26, 48, v36
	v_mov_b32_e32 v27, v37
	v_lshlrev_b64 v[26:27], 12, v[26:27]
	v_lshl_add_u64 v[26:27], v[30:31], 0, v[26:27]
	v_or_b32_e32 v36, 56, v36
	global_load_dwordx4 v[26:29], v[26:27], off nt
	v_lshlrev_b64 v[32:33], 12, v[36:37]
	v_lshl_add_u64 v[30:31], v[30:31], 0, v[32:33]
	global_load_dwordx4 v[30:33], v[30:31], off nt
	v_add_u32_e32 v43, v35, v39
	v_add_u32_e32 v44, 0x420, v43
	v_add_u32_e32 v46, 0x428, v43
	v_add_u32_e32 v50, 0x840, v43
	v_add_u32_e32 v52, 0x848, v43
	v_add_u32_e32 v54, 0xc60, v43
	v_add_u32_e32 v56, 0xc68, v43
	v_add_u32_e32 v58, 0x1080, v43
	v_add_u32_e32 v65, 0x1088, v43
	v_add_u32_e32 v66, 0x14a0, v43
	v_add_u32_e32 v67, 0x14a8, v43
	v_add_u32_e32 v68, 0x18c0, v43
	v_add_u32_e32 v69, 0x18c8, v43
	v_add_u32_e32 v70, 0x1ce0, v43
	v_add_u32_e32 v71, 0x1ce8, v43
	s_lshl_b64 s[22:23], s[16:17], 1
	s_add_u32 s22, s55, s22
	v_lshlrev_b32_e32 v36, 1, v38
	s_addc_u32 s23, s54, s23
	v_lshl_add_u64 v[48:49], s[22:23], 0, v[36:37]
	s_mov_b64 s[22:23], 0x580000
	s_waitcnt vmcnt(7)
	ds_write2_b32 v43, v2, v3 offset1:1
	ds_write2_b32 v43, v4, v5 offset0:2 offset1:3
	s_waitcnt vmcnt(6)
	ds_write2_b32 v44, v6, v7 offset1:1
	ds_write2_b32 v46, v8, v9 offset1:1
	s_waitcnt vmcnt(5)
	ds_write2_b32 v50, v10, v11 offset1:1
	ds_write2_b32 v52, v12, v13 offset1:1
	s_waitcnt vmcnt(4)
	ds_write2_b32 v54, v14, v15 offset1:1
	ds_write2_b32 v56, v16, v17 offset1:1
	s_waitcnt vmcnt(3)
	ds_write2_b32 v58, v18, v19 offset1:1
	ds_write2_b32 v65, v20, v21 offset1:1
	s_waitcnt vmcnt(2)
	ds_write2_b32 v66, v22, v23 offset1:1
	ds_write2_b32 v67, v24, v25 offset1:1
	s_waitcnt vmcnt(1)
	ds_write2_b32 v68, v26, v27 offset1:1
	ds_write2_b32 v69, v28, v29 offset1:1
	s_waitcnt vmcnt(0)
	ds_write2_b32 v70, v30, v31 offset1:1
	ds_write2_b32 v71, v32, v33 offset1:1
	s_waitcnt lgkmcnt(0)
	ds_read2_b32 v[6:7], v53 offset0:33 offset1:41
	ds_read2_b32 v[8:9], v53 offset1:8
	ds_read2_b32 v[10:11], v53 offset0:66 offset1:74
	ds_read2_b32 v[12:13], v53 offset0:99 offset1:107
	ds_read2_b32 v[14:15], v53 offset0:132 offset1:140
	ds_read2_b32 v[16:17], v53 offset0:165 offset1:173
	ds_read2_b32 v[18:19], v53 offset0:198 offset1:206
	ds_read2_b32 v[20:21], v53 offset0:231 offset1:239
	s_waitcnt lgkmcnt(6)
	v_cvt_pk_bf16_f32 v2, v8, v6
	v_or_b32_e32 v6, s2, v1
	v_mul_u32_u24_e32 v6, 0xb00, v6
	v_lshl_add_u64 v[22:23], v[48:49], 0, s[22:23]
	v_lshlrev_b32_e32 v36, 1, v6
	v_or_b32_e32 v6, s2, v45
	v_lshl_add_u64 v[24:25], v[22:23], 0, v[36:37]
	v_mul_u32_u24_e32 v6, 0xb00, v6
	s_waitcnt lgkmcnt(4)
	v_cvt_pk_bf16_f32 v3, v10, v12
	s_waitcnt lgkmcnt(2)
	v_cvt_pk_bf16_f32 v4, v14, v16
	s_waitcnt lgkmcnt(0)
	v_cvt_pk_bf16_f32 v5, v18, v20
	global_store_dwordx4 v[24:25], v[2:5], off nt
	v_lshlrev_b32_e32 v36, 1, v6
	s_nop 0
	v_cvt_pk_bf16_f32 v2, v9, v7
	v_cvt_pk_bf16_f32 v3, v11, v13
	v_cvt_pk_bf16_f32 v4, v15, v17
	v_cvt_pk_bf16_f32 v5, v19, v21
	v_lshl_add_u64 v[6:7], v[22:23], 0, v[36:37]
	ds_read2_b32 v[8:9], v53 offset0:16 offset1:24
	ds_read2_b32 v[10:11], v53 offset0:49 offset1:57
	ds_read2_b32 v[12:13], v53 offset0:82 offset1:90
	ds_read2_b32 v[14:15], v53 offset0:115 offset1:123
	ds_read2_b32 v[16:17], v53 offset0:148 offset1:156
	ds_read2_b32 v[18:19], v53 offset0:181 offset1:189
	ds_read2_b32 v[20:21], v53 offset0:214 offset1:222
	ds_read2_b32 v[24:25], v53 offset0:247 offset1:255
	global_store_dwordx4 v[6:7], v[2:5], off nt
	v_or_b32_e32 v6, s2, v47
	v_mul_u32_u24_e32 v6, 0xb00, v6
	v_lshlrev_b32_e32 v36, 1, v6
	v_lshl_add_u64 v[6:7], v[22:23], 0, v[36:37]
	s_waitcnt lgkmcnt(6)
	v_cvt_pk_bf16_f32 v2, v8, v10
	s_waitcnt lgkmcnt(4)
	v_cvt_pk_bf16_f32 v3, v12, v14
	s_waitcnt lgkmcnt(2)
	v_cvt_pk_bf16_f32 v4, v16, v18
	s_waitcnt lgkmcnt(0)
	v_cvt_pk_bf16_f32 v5, v20, v24
	global_store_dwordx4 v[6:7], v[2:5], off nt
	v_or_b32_e32 v6, s2, v51
	v_mul_u32_u24_e32 v6, 0xb00, v6
	v_lshlrev_b32_e32 v36, 1, v6
	v_lshl_add_u64 v[6:7], v[22:23], 0, v[36:37]
	v_cvt_pk_bf16_f32 v2, v9, v11
	v_cvt_pk_bf16_f32 v3, v13, v15
	v_cvt_pk_bf16_f32 v4, v17, v19
	v_cvt_pk_bf16_f32 v5, v21, v25
	global_store_dwordx4 v[6:7], v[2:5], off nt
	s_waitcnt lgkmcnt(0)

; #define LAS __attribute__((address_space(3)))
; __device__ __forceinline__ unsigned cvt_pk_bf16(float lo, float hi) { unsigned r; asm("v_cvt_pk_bf16_f32 %0, %1, %2" : "=v"(r) : "v"(lo), "v"(hi)); return r; }
; __device__ __forceinline__ void transpose_item(const float* W, int K, int N, const float* gain, bf16_t* WT, int dst_row0, LAS float* scr, int kb, int n0, int lane) {
;     const int k0 = 64 * kb, n4 = (lane & 7) * 4, kr = lane >> 3;
;     f32x4 v[8]; float g[8];
; #pragma unroll
;     for (int i = 0; i < 8; ++i) { v[i] = *(const f32x4*)(W + (size_t)(k0 + kr + 8 * i) * N + n0 + n4); g[i] = gain ? gain[k0 + kr + 8 * i] : 1.0f; }
; #pragma unroll
;     for (int i = 0; i < 8; ++i) { LAS float* d = scr + (kr + 8 * i) * 33 + n4; d[0] = v[i][0] * g[i]; d[1] = v[i][1] * g[i]; d[2] = v[i][2] * g[i]; d[3] = v[i][3] * g[i]; }
;     asm volatile("s_waitcnt lgkmcnt(0)" ::: "memory");
;     const int c = lane & 7;
; #pragma unroll
;     for (int j = 0; j < 4; ++j) { const int n = (lane >> 3) + 8 * j; const LAS float* s = scr + (8 * c) * 33 + n;
;         u32x4 o; o.x = cvt_pk_bf16(s[0 * 33], s[1 * 33]); o.y = cvt_pk_bf16(s[2 * 33], s[3 * 33]); o.z = cvt_pk_bf16(s[4 * 33], s[5 * 33]); o.w = cvt_pk_bf16(s[6 * 33], s[7 * 33]);
;         *(u32x4*)(WT + (size_t)(dst_row0 + n) * K + k0 + 8 * c) = o; }
; __device__ __forceinline__ void weight_item(const Params& P, unsigned char* ws, LAS float* scr, int l, int r, int lane) {
;     ...
;         if (r < I_DN) { const int kb = r / 32, n0 = (r % 32) * 32; transpose_item(P.in[12] + oU, DFF, D, nullptr, WDa, n0, scr, kb, n0, lane); return; }
.LBB0_120:
	s_andn2_b64 vcc, exec, s[2:3]
	s_cbranch_vccnz .LBB0_122
	s_load_dwordx16 s[64:79], s[0:1], 0x40
	s_and_b32 s2, s44, 0x3e0
	s_lshl_b64 s[22:23], s[20:21], 2
	v_mov_b32_e32 v43, v37
	v_mov_b32_e32 v5, v37
	s_waitcnt lgkmcnt(0)
	s_add_u32 s3, s72, s22
	s_addc_u32 s19, s73, s23
	s_lshl_b32 s16, s18, 13
	s_sub_i32 s16, s42, s16
	s_and_b32 s16, s16, 0x3fc0
	s_addk_i32 s16, 0xd400
	s_lshl_b32 s22, s2, 2
	v_or_b32_e32 v36, s16, v1
	s_add_u32 s22, s3, s22
	s_addc_u32 s23, s19, 0
	v_or_b32_e32 v4, 8, v36
	v_or_b32_e32 v10, 16, v36
	v_mov_b32_e32 v11, v37
	v_or_b32_e32 v12, 24, v36
	v_mov_b32_e32 v13, v37
	v_or_b32_e32 v18, 32, v36
	v_mov_b32_e32 v19, v37
	v_or_b32_e32 v20, 40, v36
	v_mov_b32_e32 v21, v37
	v_lshl_add_u64 v[30:31], s[22:23], 0, v[42:43]
	v_lshlrev_b64 v[2:3], 12, v[36:37]
	v_lshlrev_b64 v[4:5], 12, v[4:5]
	v_lshlrev_b64 v[10:11], 12, v[10:11]
	v_lshlrev_b64 v[12:13], 12, v[12:13]
	v_lshlrev_b64 v[18:19], 12, v[18:19]
	v_lshlrev_b64 v[20:21], 12, v[20:21]
	v_lshl_add_u64 v[2:3], v[30:31], 0, v[2:3]
	v_lshl_add_u64 v[6:7], v[30:31], 0, v[4:5]
	v_lshl_add_u64 v[10:11], v[30:31], 0, v[10:11]
	v_lshl_add_u64 v[14:15], v[30:31], 0, v[12:13]
	v_lshl_add_u64 v[18:19], v[30:31], 0, v[18:19]
	v_lshl_add_u64 v[22:23], v[30:31], 0, v[20:21]
	global_load_dwordx4 v[2:5], v[2:3], off nt
	s_nop 0
	global_load_dwordx4 v[6:9], v[6:7], off nt
	s_nop 0
	global_load_dwordx4 v[10:13], v[10:11], off nt
	s_nop 0
	global_load_dwordx4 v[14:17], v[14:15], off nt
	s_nop 0
	global_load_dwordx4 v[18:21], v[18:19], off nt
	s_nop 0
	global_load_dwordx4 v[22:25], v[22:23], off nt
	v_or_b32_e32 v26, 48, v36
	v_mov_b32_e32 v27, v37
	v_lshlrev_b64 v[26:27], 12, v[26:27]
	v_lshl_add_u64 v[26:27], v[30:31], 0, v[26:27]
	v_or_b32_e32 v36, 56, v36
	global_load_dwordx4 v[26:29], v[26:27], off nt
	v_lshlrev_b64 v[32:33], 12, v[36:37]
	v_lshl_add_u64 v[30:31], v[30:31], 0, v[32:33]
	global_load_dwordx4 v[30:33], v[30:31], off nt
	v_add_u32_e32 v43, v35, v39
	v_add_u32_e32 v44, 0x420, v43
	v_add_u32_e32 v46, 0x428, v43
	v_add_u32_e32 v48, 0x840, v43
	v_add_u32_e32 v49, 0x848, v43
	v_add_u32_e32 v50, 0xc60, v43
	v_add_u32_e32 v52, 0xc68, v43
	v_add_u32_e32 v54, 0x1080, v43
	v_add_u32_e32 v56, 0x1088, v43
	v_add_u32_e32 v58, 0x14a0, v43
	v_add_u32_e32 v65, 0x14a8, v43
	v_add_u32_e32 v66, 0x18c0, v43
	v_add_u32_e32 v67, 0x18c8, v43
	v_add_u32_e32 v68, 0x1ce0, v43
	v_add_u32_e32 v69, 0x1ce8, v43
	s_lshl_b64 s[22:23], s[16:17], 1
	s_add_u32 s22, s55, s22
	v_lshlrev_b32_e32 v36, 1, v38
	s_addc_u32 s23, s54, s23
	s_waitcnt vmcnt(7)
	ds_write2_b32 v43, v2, v3 offset1:1
	ds_write2_b32 v43, v4, v5 offset0:2 offset1:3
	s_waitcnt vmcnt(6)
	ds_write2_b32 v44, v6, v7 offset1:1
	ds_write2_b32 v46, v8, v9 offset1:1
	s_waitcnt vmcnt(5)
	ds_write2_b32 v48, v10, v11 offset1:1
	ds_write2_b32 v49, v12, v13 offset1:1
	s_waitcnt vmcnt(4)
	ds_write2_b32 v50, v14, v15 offset1:1
	ds_write2_b32 v52, v16, v17 offset1:1
	s_waitcnt vmcnt(3)
	ds_write2_b32 v54, v18, v19 offset1:1
	ds_write2_b32 v56, v20, v21 offset1:1
	s_waitcnt vmcnt(2)
	ds_write2_b32 v58, v22, v23 offset1:1
	ds_write2_b32 v65, v24, v25 offset1:1
	s_waitcnt vmcnt(1)
	ds_write2_b32 v66, v26, v27 offset1:1
	ds_write2_b32 v67, v28, v29 offset1:1
	s_waitcnt vmcnt(0)
	ds_write2_b32 v68, v30, v31 offset1:1
	ds_write2_b32 v69, v32, v33 offset1:1
	s_waitcnt lgkmcnt(0)
	ds_read2_b32 v[6:7], v53 offset0:33 offset1:41
	ds_read2_b32 v[8:9], v53 offset1:8
	ds_read2_b32 v[10:11], v53 offset0:66 offset1:74
	ds_read2_b32 v[12:13], v53 offset0:99 offset1:107
	ds_read2_b32 v[14:15], v53 offset0:132 offset1:140
	ds_read2_b32 v[16:17], v53 offset0:165 offset1:173
	ds_read2_b32 v[18:19], v53 offset0:198 offset1:206
	ds_read2_b32 v[20:21], v53 offset0:231 offset1:239
	s_waitcnt lgkmcnt(6)
	v_cvt_pk_bf16_f32 v2, v8, v6
	v_or_b32_e32 v6, s2, v1
	v_mul_u32_u24_e32 v6, 0xb00, v6
	v_lshl_add_u64 v[22:23], s[22:23], 0, v[36:37]
	v_lshlrev_b32_e32 v36, 1, v6
	v_or_b32_e32 v6, s2, v45
	v_lshl_add_u64 v[24:25], v[22:23], 0, v[36:37]
	v_mul_u32_u24_e32 v6, 0xb00, v6
	s_waitcnt lgkmcnt(4)
	v_cvt_pk_bf16_f32 v3, v10, v12
	s_waitcnt lgkmcnt(2)
	v_cvt_pk_bf16_f32 v4, v14, v16
	s_waitcnt lgkmcnt(0)
	v_cvt_pk_bf16_f32 v5, v18, v20
	global_store_dwordx4 v[24:25], v[2:5], off nt
	v_lshlrev_b32_e32 v36, 1, v6
	s_nop 0
	v_cvt_pk_bf16_f32 v2, v9, v7
	v_cvt_pk_bf16_f32 v3, v11, v13
	v_cvt_pk_bf16_f32 v4, v15, v17
	v_cvt_pk_bf16_f32 v5, v19, v21
	v_lshl_add_u64 v[6:7], v[22:23], 0, v[36:37]
	ds_read2_b32 v[8:9], v53 offset0:16 offset1:24
	ds_read2_b32 v[10:11], v53 offset0:49 offset1:57
	ds_read2_b32 v[12:13], v53 offset0:82 offset1:90
	ds_read2_b32 v[14:15], v53 offset0:115 offset1:123
	ds_read2_b32 v[16:17], v53 offset0:148 offset1:156
	ds_read2_b32 v[18:19], v53 offset0:181 offset1:189
	ds_read2_b32 v[20:21], v53 offset0:214 offset1:222
	ds_read2_b32 v[24:25], v53 offset0:247 offset1:255
	global_store_dwordx4 v[6:7], v[2:5], off nt
	v_or_b32_e32 v6, s2, v47
	v_mul_u32_u24_e32 v6, 0xb00, v6
	v_lshlrev_b32_e32 v36, 1, v6
	v_lshl_add_u64 v[6:7], v[22:23], 0, v[36:37]
	s_waitcnt lgkmcnt(6)
	v_cvt_pk_bf16_f32 v2, v8, v10
	s_waitcnt lgkmcnt(4)
	v_cvt_pk_bf16_f32 v3, v12, v14
	s_waitcnt lgkmcnt(2)
	v_cvt_pk_bf16_f32 v4, v16, v18
	s_waitcnt lgkmcnt(0)
	v_cvt_pk_bf16_f32 v5, v20, v24
	global_store_dwordx4 v[6:7], v[2:5], off nt
	v_or_b32_e32 v6, s2, v51
	v_mul_u32_u24_e32 v6, 0xb00, v6
	v_lshlrev_b32_e32 v36, 1, v6
	v_lshl_add_u64 v[6:7], v[22:23], 0, v[36:37]
	v_cvt_pk_bf16_f32 v2, v9, v11
	v_cvt_pk_bf16_f32 v3, v13, v15
	v_cvt_pk_bf16_f32 v4, v17, v19
	v_cvt_pk_bf16_f32 v5, v21, v25
	global_store_dwordx4 v[6:7], v[2:5], off nt
	s_waitcnt lgkmcnt(0)

; #define TR_UP(IDX, GIDX, WT, ISUP) { const int kb = r / 88, n0 = (r % 88) * 32; transpose_item(P.in[IDX] + oU, D, DFF, P.in[GIDX] + l * D, WT, (n0 >> 7) * 256 + (n0 & 127) + (ISUP) * 128, scr, kb, n0, lane); return; }
; __device__ __forceinline__ void transpose_item(const float* W, int K, int N, const float* gain, bf16_t* WT, int dst_row0, LAS float* scr, int kb, int n0, int lane) {
;     const int k0 = 64 * kb, n4 = (lane & 7) * 4, kr = lane >> 3;
;     f32x4 v[8]; float g[8];
; #pragma unroll
;     for (int i = 0; i < 8; ++i) { v[i] = *(const f32x4*)(W + (size_t)(k0 + kr + 8 * i) * N + n0 + n4); g[i] = gain ? gain[k0 + kr + 8 * i] : 1.0f; }
; __device__ __forceinline__ void weight_item(const Params& P, unsigned char* ws, LAS float* scr, int l, int r, int lane) {
;     ...
;         if (r < I_UP) TR_UP(10, 9, W1a, 0)
;         r -= I_UP;
;         if (r < I_UP) TR_UP(11, 9, W1a, 1)
;         r -= I_UP;
;         if (r < I_UP) TR_UP(28, 27, W1b, 0)
;         r -= I_UP;
;         if (r < I_UP) TR_UP(29, 27, W1b, 1)
.LBB0_123:
	s_andn2_b64 vcc, exec, s[2:3]
	s_cbranch_vccnz .LBB0_141
	s_add_i32 s2, s51, 0xef80
	s_and_b32 s3, s2, 0xffff
	s_mul_i32 s3, s3, 0xba2f
	s_load_dwordx16 s[64:79], s[0:1], 0xc0
	s_lshr_b32 s16, s3, 16
	s_lshr_b32 s3, s3, 22
	s_mulk_i32 s3, 0x58
	s_sub_i32 s2, s2, s3
	s_and_b32 s19, s2, 0xffff
	s_lshl_b64 s[2:3], s[20:21], 2
	s_waitcnt lgkmcnt(0)
	s_add_u32 s24, s74, s2
	s_addc_u32 s25, s75, s3
	s_lshl_b32 s2, s18, 10
	s_ashr_i32 s3, s2, 31
	s_lshl_b64 s[2:3], s[2:3], 2
	s_add_u32 s22, s70, s2
	s_addc_u32 s23, s71, s3
	s_and_b32 s16, s16, 0xffc0
	s_lshl_b32 s2, s19, 7
	s_add_u32 s2, s24, s2
	s_addc_u32 s3, s25, 0
	v_mov_b32_e32 v43, v37
	v_or_b32_e32 v32, s16, v1
	v_lshl_add_u64 v[30:31], s[2:3], 0, v[42:43]
	v_mad_u64_u32 v[2:3], s[2:3], v32, s47, v[30:31]
	global_load_dwordx4 v[2:5], v[2:3], off nt
	v_cndmask_b32_e64 v6, 0, 1, s[12:13]
	v_mov_b32_e32 v36, 1.0
	v_cmp_ne_u32_e64 s[2:3], 1, v6
	s_andn2_b64 vcc, exec, s[12:13]
	v_lshlrev_b32_e32 v43, 2, v32
	v_mov_b32_e32 v46, 1.0
	s_cbranch_vccnz .LBB0_126
	global_load_dword v46, v43, s[22:23]
.LBB0_126:
	v_or_b32_e32 v6, 8, v32
	v_mad_u64_u32 v[6:7], s[24:25], v6, s47, v[30:31]
	global_load_dwordx4 v[6:9], v[6:7], off nt
	s_and_b64 vcc, exec, s[2:3]
	s_cbranch_vccnz .LBB0_128
	global_load_dword v36, v43, s[22:23] offset:32
.LBB0_128:
	v_or_b32_e32 v10, 16, v32
	v_mad_u64_u32 v[10:11], s[24:25], v10, s47, v[30:31]
	global_load_dwordx4 v[10:13], v[10:11], off nt
	v_mov_b32_e32 v44, 1.0
	s_and_b64 vcc, exec, s[2:3]
	v_mov_b32_e32 v50, 1.0
	s_cbranch_vccnz .LBB0_130
	global_load_dword v50, v43, s[22:23] offset:64
.LBB0_130:
	v_or_b32_e32 v14, 24, v32
	v_mad_u64_u32 v[14:15], s[24:25], v14, s47, v[30:31]
	global_load_dwordx4 v[14:17], v[14:15], off nt
	s_and_b64 vcc, exec, s[2:3]
	s_cbranch_vccnz .LBB0_132
	global_load_dword v44, v43, s[22:23] offset:96
.LBB0_132:
	v_or_b32_e32 v18, 32, v32
	v_mad_u64_u32 v[18:19], s[24:25], v18, s47, v[30:31]
	global_load_dwordx4 v[18:21], v[18:19], off nt
	v_mov_b32_e32 v48, 1.0
	s_and_b64 vcc, exec, s[2:3]
	v_mov_b32_e32 v54, 1.0
	s_cbranch_vccnz .LBB0_134
	global_load_dword v54, v43, s[22:23] offset:128
.LBB0_134:
	v_or_b32_e32 v22, 40, v32
	v_mad_u64_u32 v[22:23], s[24:25], v22, s47, v[30:31]
	global_load_dwordx4 v[22:25], v[22:23], off nt
	s_and_b64 vcc, exec, s[2:3]
	s_cbranch_vccnz .LBB0_136
	global_load_dword v48, v43, s[22:23] offset:160
.LBB0_136:
	v_or_b32_e32 v26, 48, v32
	v_mad_u64_u32 v[26:27], s[24:25], v26, s47, v[30:31]
	global_load_dwordx4 v[26:29], v[26:27], off nt
	v_mov_b32_e32 v52, 1.0
	s_and_b64 vcc, exec, s[2:3]
	v_mov_b32_e32 v56, 1.0
	s_cbranch_vccnz .LBB0_138
	global_load_dword v56, v43, s[22:23] offset:192
.LBB0_138:
	v_or_b32_e32 v32, 56, v32
	v_mad_u64_u32 v[30:31], s[24:25], v32, s47, v[30:31]
	global_load_dwordx4 v[30:33], v[30:31], off nt
	s_and_b64 vcc, exec, s[2:3]
	s_lshl_b32 s2, s19, 5
	s_cbranch_vccnz .LBB0_140
	global_load_dword v52, v43, s[22:23] offset:224
; #define LAS __attribute__((address_space(3)))
; __device__ __forceinline__ unsigned cvt_pk_bf16(float lo, float hi) { unsigned r; asm("v_cvt_pk_bf16_f32 %0, %1, %2" : "=v"(r) : "v"(lo), "v"(hi)); return r; }
; #define TR_UP(IDX, GIDX, WT, ISUP) { const int kb = r / 88, n0 = (r % 88) * 32; transpose_item(P.in[IDX] + oU, D, DFF, P.in[GIDX] + l * D, WT, (n0 >> 7) * 256 + (n0 & 127) + (ISUP) * 128, scr, kb, n0, lane); return; }
; __device__ __forceinline__ void transpose_item(const float* W, int K, int N, const float* gain, bf16_t* WT, int dst_row0, LAS float* scr, int kb, int n0, int lane) {
;     ...
;     for (int i = 0; i < 8; ++i) { LAS float* d = scr + (kr + 8 * i) * 33 + n4; d[0] = v[i][0] * g[i]; d[1] = v[i][1] * g[i]; d[2] = v[i][2] * g[i]; d[3] = v[i][3] * g[i]; }
;     asm volatile("s_waitcnt lgkmcnt(0)" ::: "memory");
;     const int c = lane & 7;
; #pragma unroll
;     for (int j = 0; j < 4; ++j) { const int n = (lane >> 3) + 8 * j; const LAS float* s = scr + (8 * c) * 33 + n;
;         u32x4 o; o.x = cvt_pk_bf16(s[0 * 33], s[1 * 33]); o.y = cvt_pk_bf16(s[2 * 33], s[3 * 33]); o.z = cvt_pk_bf16(s[4 * 33], s[5 * 33]); o.w = cvt_pk_bf16(s[6 * 33], s[7 * 33]);
;         *(u32x4*)(WT + (size_t)(dst_row0 + n) * K + k0 + 8 * c) = o; }
; __device__ __forceinline__ void weight_item(const Params& P, unsigned char* ws, LAS float* scr, int l, int r, int lane) {
;     ...
;         if (r < I_UP) TR_UP(10, 9, W1a, 0)
;         r -= I_UP;
;         if (r < I_UP) TR_UP(11, 9, W1a, 1)
;         r -= I_UP;
;         if (r < I_UP) TR_UP(28, 27, W1b, 0)
;         r -= I_UP;
;         if (r < I_UP) TR_UP(29, 27, W1b, 1)
.LBB0_140:
	s_waitcnt vmcnt(7)
	v_pk_mul_f32 v[2:3], v[2:3], v[46:47] op_sel_hi:[1,0]
	v_add_u32_e32 v43, v35, v39
	ds_write2_b32 v43, v2, v3 offset1:1
	v_pk_mul_f32 v[2:3], v[4:5], v[46:47] op_sel_hi:[1,0]
	ds_write2_b32 v43, v2, v3 offset0:2 offset1:3
	s_waitcnt vmcnt(6)
	v_pk_mul_f32 v[2:3], v[6:7], v[36:37] op_sel_hi:[1,0]
	v_add_u32_e32 v4, 0x420, v43
	ds_write2_b32 v4, v2, v3 offset1:1
	v_pk_mul_f32 v[2:3], v[8:9], v[36:37] op_sel_hi:[1,0]
	v_add_u32_e32 v4, 0x428, v43
	ds_write2_b32 v4, v2, v3 offset1:1
	s_waitcnt vmcnt(5)
	v_pk_mul_f32 v[2:3], v[10:11], v[50:51] op_sel_hi:[1,0]
	v_add_u32_e32 v4, 0x840, v43
	ds_write2_b32 v4, v2, v3 offset1:1
	v_pk_mul_f32 v[2:3], v[12:13], v[50:51] op_sel_hi:[1,0]
	v_add_u32_e32 v4, 0x848, v43
	ds_write2_b32 v4, v2, v3 offset1:1
	s_waitcnt vmcnt(4)
	v_pk_mul_f32 v[2:3], v[14:15], v[44:45] op_sel_hi:[1,0]
	v_add_u32_e32 v4, 0xc60, v43
	ds_write2_b32 v4, v2, v3 offset1:1
	v_pk_mul_f32 v[2:3], v[16:17], v[44:45] op_sel_hi:[1,0]
	v_add_u32_e32 v4, 0xc68, v43
	ds_write2_b32 v4, v2, v3 offset1:1
	s_waitcnt vmcnt(3)
	v_pk_mul_f32 v[2:3], v[18:19], v[54:55] op_sel_hi:[1,0]
	v_add_u32_e32 v4, 0x1080, v43
	ds_write2_b32 v4, v2, v3 offset1:1
	v_pk_mul_f32 v[2:3], v[20:21], v[54:55] op_sel_hi:[1,0]
	v_add_u32_e32 v4, 0x1088, v43
	ds_write2_b32 v4, v2, v3 offset1:1
	s_waitcnt vmcnt(2)
	v_pk_mul_f32 v[2:3], v[22:23], v[48:49] op_sel_hi:[1,0]
	v_add_u32_e32 v4, 0x14a0, v43
	ds_write2_b32 v4, v2, v3 offset1:1
	v_pk_mul_f32 v[2:3], v[24:25], v[48:49] op_sel_hi:[1,0]
	v_add_u32_e32 v4, 0x14a8, v43
	ds_write2_b32 v4, v2, v3 offset1:1
	s_waitcnt vmcnt(1)
	v_pk_mul_f32 v[2:3], v[26:27], v[56:57] op_sel_hi:[1,0]
	v_add_u32_e32 v4, 0x18c0, v43
	ds_write2_b32 v4, v2, v3 offset1:1
	v_pk_mul_f32 v[2:3], v[28:29], v[56:57] op_sel_hi:[1,0]
	v_add_u32_e32 v4, 0x18c8, v43
	s_lshl_b32 s3, s19, 6
	ds_write2_b32 v4, v2, v3 offset1:1
	s_waitcnt vmcnt(0)
	v_pk_mul_f32 v[2:3], v[30:31], v[52:53] op_sel_hi:[1,0]
	v_add_u32_e32 v4, 0x1ce0, v43
	s_and_b32 s3, s3, 0x1f00
	s_and_b32 s2, s2, 0x60
	ds_write2_b32 v4, v2, v3 offset1:1
	v_pk_mul_f32 v[2:3], v[32:33], v[52:53] op_sel_hi:[1,0]
	v_add_u32_e32 v4, 0x1ce8, v43
	s_or_b32 s2, s2, s3
	ds_write2_b32 v4, v2, v3 offset1:1
	s_or_b32 s19, s2, 0x80
	s_waitcnt lgkmcnt(0)
	s_and_b32 s2, 0xffff, s16
	s_lshl_b32 s2, s2, 1
	ds_read2_b32 v[6:7], v53 offset0:33 offset1:41
	ds_read2_b32 v[8:9], v53 offset1:8
	ds_read2_b32 v[10:11], v53 offset0:66 offset1:74
	ds_read2_b32 v[12:13], v53 offset0:99 offset1:107
	ds_read2_b32 v[14:15], v53 offset0:132 offset1:140
	ds_read2_b32 v[16:17], v53 offset0:165 offset1:173
	ds_read2_b32 v[18:19], v53 offset0:198 offset1:206
	ds_read2_b32 v[20:21], v53 offset0:231 offset1:239
	s_add_u32 s2, s52, s2
	s_addc_u32 s3, s53, 0
	v_lshlrev_b32_e32 v36, 1, v38
	s_waitcnt lgkmcnt(6)
	v_cvt_pk_bf16_f32 v2, v8, v6
	v_or_b32_e32 v6, s19, v1
	v_lshl_add_u64 v[22:23], s[2:3], 0, v[36:37]
	v_lshlrev_b32_e32 v36, 11, v6
	v_lshl_add_u64 v[24:25], v[22:23], 0, v[36:37]
	s_waitcnt lgkmcnt(4)
	v_cvt_pk_bf16_f32 v3, v10, v12
	s_waitcnt lgkmcnt(2)
	v_cvt_pk_bf16_f32 v4, v14, v16
	s_waitcnt lgkmcnt(0)
	v_cvt_pk_bf16_f32 v5, v18, v20
	global_store_dwordx4 v[24:25], v[2:5], off nt
	v_or_b32_e32 v6, s19, v45
	v_lshlrev_b32_e32 v36, 11, v6
	v_cvt_pk_bf16_f32 v2, v9, v7
	v_cvt_pk_bf16_f32 v3, v11, v13
	v_cvt_pk_bf16_f32 v4, v15, v17
	v_cvt_pk_bf16_f32 v5, v19, v21
	ds_read2_b32 v[8:9], v53 offset0:16 offset1:24
	ds_read2_b32 v[10:11], v53 offset0:49 offset1:57
	ds_read2_b32 v[12:13], v53 offset0:82 offset1:90
	ds_read2_b32 v[14:15], v53 offset0:115 offset1:123
	ds_read2_b32 v[16:17], v53 offset0:148 offset1:156
	ds_read2_b32 v[18:19], v53 offset0:181 offset1:189
	ds_read2_b32 v[20:21], v53 offset0:214 offset1:222
	ds_read2_b32 v[24:25], v53 offset0:247 offset1:255
	v_lshl_add_u64 v[6:7], v[22:23], 0, v[36:37]
	global_store_dwordx4 v[6:7], v[2:5], off nt
	v_or_b32_e32 v6, s19, v47
	v_lshlrev_b32_e32 v36, 11, v6
	v_lshl_add_u64 v[6:7], v[22:23], 0, v[36:37]
	s_waitcnt lgkmcnt(6)
	v_cvt_pk_bf16_f32 v2, v8, v10
	s_waitcnt lgkmcnt(4)
	v_cvt_pk_bf16_f32 v3, v12, v14
	s_waitcnt lgkmcnt(2)
	v_cvt_pk_bf16_f32 v4, v16, v18
	s_waitcnt lgkmcnt(0)
	v_cvt_pk_bf16_f32 v5, v20, v24
	global_store_dwordx4 v[6:7], v[2:5], off nt
	v_or_b32_e32 v6, s19, v51
	v_lshlrev_b32_e32 v36, 11, v6
	v_lshl_add_u64 v[6:7], v[22:23], 0, v[36:37]
	v_cvt_pk_bf16_f32 v2, v9, v11
	v_cvt_pk_bf16_f32 v3, v13, v15
	v_cvt_pk_bf16_f32 v4, v17, v19
	v_cvt_pk_bf16_f32 v5, v21, v25
	global_store_dwordx4 v[6:7], v[2:5], off nt
	s_waitcnt lgkmcnt(0)

; #define TR_UP(IDX, GIDX, WT, ISUP) { const int kb = r / 88, n0 = (r % 88) * 32; transpose_item(P.in[IDX] + oU, D, DFF, P.in[GIDX] + l * D, WT, (n0 >> 7) * 256 + (n0 & 127) + (ISUP) * 128, scr, kb, n0, lane); return; }
; __device__ __forceinline__ void transpose_item(const float* W, int K, int N, const float* gain, bf16_t* WT, int dst_row0, LAS float* scr, int kb, int n0, int lane) {
;     const int k0 = 64 * kb, n4 = (lane & 7) * 4, kr = lane >> 3;
;     f32x4 v[8]; float g[8];
; #pragma unroll
;     for (int i = 0; i < 8; ++i) { v[i] = *(const f32x4*)(W + (size_t)(k0 + kr + 8 * i) * N + n0 + n4); g[i] = gain ? gain[k0 + kr + 8 * i] : 1.0f; }
; __device__ __forceinline__ void weight_item(const Params& P, unsigned char* ws, LAS float* scr, int l, int r, int lane) {
;     ...
;         if (r < I_UP) TR_UP(10, 9, W1a, 0)
;         r -= I_UP;
;         if (r < I_UP) TR_UP(11, 9, W1a, 1)
;         r -= I_UP;
;         if (r < I_UP) TR_UP(28, 27, W1b, 0)
.LBB0_142:
	s_andn2_b64 vcc, exec, s[2:3]
	s_cbranch_vccnz .LBB0_160
	s_add_i32 s2, s51, 0xf500
	s_and_b32 s3, s2, 0xffff
	s_mul_i32 s3, s3, 0xba2f
	s_load_dwordx16 s[64:79], s[0:1], 0xc0
	s_lshr_b32 s16, s3, 16
	s_lshr_b32 s3, s3, 22
	s_mulk_i32 s3, 0x58
	s_sub_i32 s2, s2, s3
	s_and_b32 s19, s2, 0xffff
	s_lshl_b64 s[2:3], s[20:21], 2
	s_waitcnt lgkmcnt(0)
	s_add_u32 s24, s72, s2
	s_addc_u32 s25, s73, s3
	s_lshl_b32 s2, s18, 10
	s_ashr_i32 s3, s2, 31
	s_lshl_b64 s[2:3], s[2:3], 2
	s_add_u32 s22, s70, s2
	s_addc_u32 s23, s71, s3
	s_and_b32 s16, s16, 0xffc0
	s_lshl_b32 s2, s19, 7
	s_add_u32 s2, s24, s2
	s_addc_u32 s3, s25, 0
	v_mov_b32_e32 v43, v37
	v_or_b32_e32 v32, s16, v1
	v_lshl_add_u64 v[30:31], s[2:3], 0, v[42:43]
	v_mad_u64_u32 v[2:3], s[2:3], v32, s47, v[30:31]
	global_load_dwordx4 v[2:5], v[2:3], off nt
	v_cndmask_b32_e64 v6, 0, 1, s[12:13]
	v_mov_b32_e32 v36, 1.0
	v_cmp_ne_u32_e64 s[2:3], 1, v6
	s_andn2_b64 vcc, exec, s[12:13]
	v_lshlrev_b32_e32 v43, 2, v32
	v_mov_b32_e32 v46, 1.0
	s_cbranch_vccnz .LBB0_145
	global_load_dword v46, v43, s[22:23]

; #define LAS __attribute__((address_space(3)))
; __device__ __forceinline__ unsigned cvt_pk_bf16(float lo, float hi) { unsigned r; asm("v_cvt_pk_bf16_f32 %0, %1, %2" : "=v"(r) : "v"(lo), "v"(hi)); return r; }
; #define TR_UP(IDX, GIDX, WT, ISUP) { const int kb = r / 88, n0 = (r % 88) * 32; transpose_item(P.in[IDX] + oU, D, DFF, P.in[GIDX] + l * D, WT, (n0 >> 7) * 256 + (n0 & 127) + (ISUP) * 128, scr, kb, n0, lane); return; }
; __device__ __forceinline__ void transpose_item(const float* W, int K, int N, const float* gain, bf16_t* WT, int dst_row0, LAS float* scr, int kb, int n0, int lane) {
;     ...
;     for (int i = 0; i < 8; ++i) { LAS float* d = scr + (kr + 8 * i) * 33 + n4; d[0] = v[i][0] * g[i]; d[1] = v[i][1] * g[i]; d[2] = v[i][2] * g[i]; d[3] = v[i][3] * g[i]; }
;     asm volatile("s_waitcnt lgkmcnt(0)" ::: "memory");
;     const int c = lane & 7;
; #pragma unroll
;     for (int j = 0; j < 4; ++j) { const int n = (lane >> 3) + 8 * j; const LAS float* s = scr + (8 * c) * 33 + n;
;         u32x4 o; o.x = cvt_pk_bf16(s[0 * 33], s[1 * 33]); o.y = cvt_pk_bf16(s[2 * 33], s[3 * 33]); o.z = cvt_pk_bf16(s[4 * 33], s[5 * 33]); o.w = cvt_pk_bf16(s[6 * 33], s[7 * 33]);
;         *(u32x4*)(WT + (size_t)(dst_row0 + n) * K + k0 + 8 * c) = o; }
; __device__ __forceinline__ void weight_item(const Params& P, unsigned char* ws, LAS float* scr, int l, int r, int lane) {
;     ...
;         if (r < I_UP) TR_UP(10, 9, W1a, 0)
;         r -= I_UP;
;         if (r < I_UP) TR_UP(11, 9, W1a, 1)
;         r -= I_UP;
;         if (r < I_UP) TR_UP(28, 27, W1b, 0)
.LBB0_159:
	s_waitcnt vmcnt(7)
	v_pk_mul_f32 v[2:3], v[2:3], v[46:47] op_sel_hi:[1,0]
	v_add_u32_e32 v43, v35, v39
	ds_write2_b32 v43, v2, v3 offset1:1
	v_pk_mul_f32 v[2:3], v[4:5], v[46:47] op_sel_hi:[1,0]
	ds_write2_b32 v43, v2, v3 offset0:2 offset1:3
	s_waitcnt vmcnt(6)
	v_pk_mul_f32 v[2:3], v[6:7], v[36:37] op_sel_hi:[1,0]
	v_add_u32_e32 v4, 0x420, v43
	ds_write2_b32 v4, v2, v3 offset1:1
	v_pk_mul_f32 v[2:3], v[8:9], v[36:37] op_sel_hi:[1,0]
	v_add_u32_e32 v4, 0x428, v43
	ds_write2_b32 v4, v2, v3 offset1:1
	s_waitcnt vmcnt(5)
	v_pk_mul_f32 v[2:3], v[10:11], v[50:51] op_sel_hi:[1,0]
	v_add_u32_e32 v4, 0x840, v43
	ds_write2_b32 v4, v2, v3 offset1:1
	v_pk_mul_f32 v[2:3], v[12:13], v[50:51] op_sel_hi:[1,0]
	v_add_u32_e32 v4, 0x848, v43
	ds_write2_b32 v4, v2, v3 offset1:1
	s_waitcnt vmcnt(4)
	v_pk_mul_f32 v[2:3], v[14:15], v[44:45] op_sel_hi:[1,0]
	v_add_u32_e32 v4, 0xc60, v43
	ds_write2_b32 v4, v2, v3 offset1:1
	v_pk_mul_f32 v[2:3], v[16:17], v[44:45] op_sel_hi:[1,0]
	v_add_u32_e32 v4, 0xc68, v43
	ds_write2_b32 v4, v2, v3 offset1:1
	s_waitcnt vmcnt(3)
	v_pk_mul_f32 v[2:3], v[18:19], v[54:55] op_sel_hi:[1,0]
	v_add_u32_e32 v4, 0x1080, v43
	ds_write2_b32 v4, v2, v3 offset1:1
	v_pk_mul_f32 v[2:3], v[20:21], v[54:55] op_sel_hi:[1,0]
	v_add_u32_e32 v4, 0x1088, v43
	ds_write2_b32 v4, v2, v3 offset1:1
	s_waitcnt vmcnt(2)
	v_pk_mul_f32 v[2:3], v[22:23], v[48:49] op_sel_hi:[1,0]
	v_add_u32_e32 v4, 0x14a0, v43
	ds_write2_b32 v4, v2, v3 offset1:1
	v_pk_mul_f32 v[2:3], v[24:25], v[48:49] op_sel_hi:[1,0]
	v_add_u32_e32 v4, 0x14a8, v43
	ds_write2_b32 v4, v2, v3 offset1:1
	s_waitcnt vmcnt(1)
	v_pk_mul_f32 v[2:3], v[26:27], v[56:57] op_sel_hi:[1,0]
	v_add_u32_e32 v4, 0x18c0, v43
	ds_write2_b32 v4, v2, v3 offset1:1
	v_pk_mul_f32 v[2:3], v[28:29], v[56:57] op_sel_hi:[1,0]
	v_add_u32_e32 v4, 0x18c8, v43
	ds_write2_b32 v4, v2, v3 offset1:1
	s_waitcnt vmcnt(0)
	v_pk_mul_f32 v[2:3], v[30:31], v[52:53] op_sel_hi:[1,0]
	v_add_u32_e32 v4, 0x1ce0, v43
	s_lshl_b32 s3, s19, 6
	ds_write2_b32 v4, v2, v3 offset1:1
	v_pk_mul_f32 v[2:3], v[32:33], v[52:53] op_sel_hi:[1,0]
	v_add_u32_e32 v4, 0x1ce8, v43
	s_and_b32 s3, s3, 0x1f00
	s_and_b32 s2, s2, 0x60
	ds_write2_b32 v4, v2, v3 offset1:1
	s_or_b32 s19, s3, s2
	s_waitcnt lgkmcnt(0)
	s_and_b32 s2, 0xffff, s16
	s_lshl_b32 s2, s2, 1
	ds_read2_b32 v[6:7], v53 offset0:33 offset1:41
	ds_read2_b32 v[8:9], v53 offset1:8
	ds_read2_b32 v[10:11], v53 offset0:66 offset1:74
	ds_read2_b32 v[12:13], v53 offset0:99 offset1:107
	ds_read2_b32 v[14:15], v53 offset0:132 offset1:140
	ds_read2_b32 v[16:17], v53 offset0:165 offset1:173
	ds_read2_b32 v[18:19], v53 offset0:198 offset1:206
	ds_read2_b32 v[20:21], v53 offset0:231 offset1:239
	s_add_u32 s2, s52, s2
	s_addc_u32 s3, s53, 0
	v_lshlrev_b32_e32 v36, 1, v38
	s_waitcnt lgkmcnt(6)
	v_cvt_pk_bf16_f32 v2, v8, v6
	v_or_b32_e32 v6, s19, v1
	v_lshl_add_u64 v[22:23], s[2:3], 0, v[36:37]
	v_lshlrev_b32_e32 v36, 11, v6
	v_lshl_add_u64 v[24:25], v[22:23], 0, v[36:37]
	s_waitcnt lgkmcnt(4)
	v_cvt_pk_bf16_f32 v3, v10, v12
	s_waitcnt lgkmcnt(2)
	v_cvt_pk_bf16_f32 v4, v14, v16
	s_waitcnt lgkmcnt(0)
	v_cvt_pk_bf16_f32 v5, v18, v20
	global_store_dwordx4 v[24:25], v[2:5], off nt
	v_or_b32_e32 v6, s19, v45
	v_lshlrev_b32_e32 v36, 11, v6
	v_cvt_pk_bf16_f32 v2, v9, v7
	v_cvt_pk_bf16_f32 v3, v11, v13
	v_cvt_pk_bf16_f32 v4, v15, v17
	v_cvt_pk_bf16_f32 v5, v19, v21
	ds_read2_b32 v[8:9], v53 offset0:16 offset1:24
	ds_read2_b32 v[10:11], v53 offset0:49 offset1:57
	ds_read2_b32 v[12:13], v53 offset0:82 offset1:90
	ds_read2_b32 v[14:15], v53 offset0:115 offset1:123
	ds_read2_b32 v[16:17], v53 offset0:148 offset1:156
	ds_read2_b32 v[18:19], v53 offset0:181 offset1:189
	ds_read2_b32 v[20:21], v53 offset0:214 offset1:222
	ds_read2_b32 v[24:25], v53 offset0:247 offset1:255
	v_lshl_add_u64 v[6:7], v[22:23], 0, v[36:37]
	global_store_dwordx4 v[6:7], v[2:5], off nt
	v_or_b32_e32 v6, s19, v47
	v_lshlrev_b32_e32 v36, 11, v6
	v_lshl_add_u64 v[6:7], v[22:23], 0, v[36:37]
	s_waitcnt lgkmcnt(6)
	v_cvt_pk_bf16_f32 v2, v8, v10
	s_waitcnt lgkmcnt(4)
	v_cvt_pk_bf16_f32 v3, v12, v14
	s_waitcnt lgkmcnt(2)
	v_cvt_pk_bf16_f32 v4, v16, v18
	s_waitcnt lgkmcnt(0)
	v_cvt_pk_bf16_f32 v5, v20, v24
	global_store_dwordx4 v[6:7], v[2:5], off nt
	v_or_b32_e32 v6, s19, v51
	v_lshlrev_b32_e32 v36, 11, v6
	v_lshl_add_u64 v[6:7], v[22:23], 0, v[36:37]
	v_cvt_pk_bf16_f32 v2, v9, v11
	v_cvt_pk_bf16_f32 v3, v13, v15
	v_cvt_pk_bf16_f32 v4, v17, v19
	v_cvt_pk_bf16_f32 v5, v21, v25
	global_store_dwordx4 v[6:7], v[2:5], off nt
	s_waitcnt lgkmcnt(0)

; #define TR_UP(IDX, GIDX, WT, ISUP) { const int kb = r / 88, n0 = (r % 88) * 32; transpose_item(P.in[IDX] + oU, D, DFF, P.in[GIDX] + l * D, WT, (n0 >> 7) * 256 + (n0 & 127) + (ISUP) * 128, scr, kb, n0, lane); return; }
; __device__ __forceinline__ void transpose_item(const float* W, int K, int N, const float* gain, bf16_t* WT, int dst_row0, LAS float* scr, int kb, int n0, int lane) {
;     const int k0 = 64 * kb, n4 = (lane & 7) * 4, kr = lane >> 3;
;     f32x4 v[8]; float g[8];
; #pragma unroll
;     for (int i = 0; i < 8; ++i) { v[i] = *(const f32x4*)(W + (size_t)(k0 + kr + 8 * i) * N + n0 + n4); g[i] = gain ? gain[k0 + kr + 8 * i] : 1.0f; }
; __device__ __forceinline__ void weight_item(const Params& P, unsigned char* ws, LAS float* scr, int l, int r, int lane) {
;     ...
;         if (r < I_UP) TR_UP(10, 9, W1a, 0)
;         r -= I_UP;
;         if (r < I_UP) TR_UP(11, 9, W1a, 1)
.LBB0_161:
	s_andn2_b64 vcc, exec, s[2:3]
	s_cbranch_vccnz .LBB0_179
	s_add_i32 s2, s51, 0xfa80
	s_and_b32 s3, s2, 0xffff
	s_mul_i32 s3, s3, 0xba2f
	s_load_dwordx16 s[64:79], s[0:1], 0x40
	s_lshr_b32 s16, s3, 16
	s_lshr_b32 s3, s3, 22
	s_mulk_i32 s3, 0x58
	s_sub_i32 s2, s2, s3
	s_and_b32 s19, s2, 0xffff
	s_lshl_b64 s[2:3], s[20:21], 2
	s_waitcnt lgkmcnt(0)
	s_add_u32 s24, s70, s2
	s_addc_u32 s25, s71, s3
	s_lshl_b32 s2, s18, 10
	s_ashr_i32 s3, s2, 31
	s_lshl_b64 s[2:3], s[2:3], 2
	s_add_u32 s22, s66, s2
	s_addc_u32 s23, s67, s3
	s_and_b32 s16, s16, 0xffc0
	s_lshl_b32 s2, s19, 7
	s_add_u32 s2, s24, s2
	s_addc_u32 s3, s25, 0
	v_mov_b32_e32 v43, v37
	v_or_b32_e32 v32, s16, v1
	v_lshl_add_u64 v[30:31], s[2:3], 0, v[42:43]
	v_mad_u64_u32 v[2:3], s[2:3], v32, s47, v[30:31]
	global_load_dwordx4 v[2:5], v[2:3], off nt
	v_cndmask_b32_e64 v6, 0, 1, s[14:15]
	v_mov_b32_e32 v36, 1.0
	v_cmp_ne_u32_e64 s[2:3], 1, v6
	s_andn2_b64 vcc, exec, s[14:15]
	v_lshlrev_b32_e32 v43, 2, v32
	v_mov_b32_e32 v46, 1.0
	s_cbranch_vccnz .LBB0_164
	global_load_dword v46, v43, s[22:23]

; #define LAS __attribute__((address_space(3)))
; __device__ __forceinline__ unsigned cvt_pk_bf16(float lo, float hi) { unsigned r; asm("v_cvt_pk_bf16_f32 %0, %1, %2" : "=v"(r) : "v"(lo), "v"(hi)); return r; }
; #define TR_UP(IDX, GIDX, WT, ISUP) { const int kb = r / 88, n0 = (r % 88) * 32; transpose_item(P.in[IDX] + oU, D, DFF, P.in[GIDX] + l * D, WT, (n0 >> 7) * 256 + (n0 & 127) + (ISUP) * 128, scr, kb, n0, lane); return; }
; __device__ __forceinline__ void transpose_item(const float* W, int K, int N, const float* gain, bf16_t* WT, int dst_row0, LAS float* scr, int kb, int n0, int lane) {
;     ...
;     for (int i = 0; i < 8; ++i) { LAS float* d = scr + (kr + 8 * i) * 33 + n4; d[0] = v[i][0] * g[i]; d[1] = v[i][1] * g[i]; d[2] = v[i][2] * g[i]; d[3] = v[i][3] * g[i]; }
;     asm volatile("s_waitcnt lgkmcnt(0)" ::: "memory");
;     const int c = lane & 7;
; #pragma unroll
;     for (int j = 0; j < 4; ++j) { const int n = (lane >> 3) + 8 * j; const LAS float* s = scr + (8 * c) * 33 + n;
;         u32x4 o; o.x = cvt_pk_bf16(s[0 * 33], s[1 * 33]); o.y = cvt_pk_bf16(s[2 * 33], s[3 * 33]); o.z = cvt_pk_bf16(s[4 * 33], s[5 * 33]); o.w = cvt_pk_bf16(s[6 * 33], s[7 * 33]);
;         *(u32x4*)(WT + (size_t)(dst_row0 + n) * K + k0 + 8 * c) = o; }
; __device__ __forceinline__ void weight_item(const Params& P, unsigned char* ws, LAS float* scr, int l, int r, int lane) {
;     ...
;         if (r < I_UP) TR_UP(10, 9, W1a, 0)
;         r -= I_UP;
;         if (r < I_UP) TR_UP(11, 9, W1a, 1)
.LBB0_178:
	s_waitcnt vmcnt(7)
	v_pk_mul_f32 v[2:3], v[2:3], v[46:47] op_sel_hi:[1,0]
	v_add_u32_e32 v43, v35, v39
	ds_write2_b32 v43, v2, v3 offset1:1
	v_pk_mul_f32 v[2:3], v[4:5], v[46:47] op_sel_hi:[1,0]
	ds_write2_b32 v43, v2, v3 offset0:2 offset1:3
	s_waitcnt vmcnt(6)
	v_pk_mul_f32 v[2:3], v[6:7], v[36:37] op_sel_hi:[1,0]
	v_add_u32_e32 v4, 0x420, v43
	ds_write2_b32 v4, v2, v3 offset1:1
	v_pk_mul_f32 v[2:3], v[8:9], v[36:37] op_sel_hi:[1,0]
	v_add_u32_e32 v4, 0x428, v43
	ds_write2_b32 v4, v2, v3 offset1:1
	s_waitcnt vmcnt(5)
	v_pk_mul_f32 v[2:3], v[10:11], v[50:51] op_sel_hi:[1,0]
	v_add_u32_e32 v4, 0x840, v43
	ds_write2_b32 v4, v2, v3 offset1:1
	v_pk_mul_f32 v[2:3], v[12:13], v[50:51] op_sel_hi:[1,0]
	v_add_u32_e32 v4, 0x848, v43
	ds_write2_b32 v4, v2, v3 offset1:1
	s_waitcnt vmcnt(4)
	v_pk_mul_f32 v[2:3], v[14:15], v[44:45] op_sel_hi:[1,0]
	v_add_u32_e32 v4, 0xc60, v43
	ds_write2_b32 v4, v2, v3 offset1:1
	v_pk_mul_f32 v[2:3], v[16:17], v[44:45] op_sel_hi:[1,0]
	v_add_u32_e32 v4, 0xc68, v43
	ds_write2_b32 v4, v2, v3 offset1:1
	s_waitcnt vmcnt(3)
	v_pk_mul_f32 v[2:3], v[18:19], v[54:55] op_sel_hi:[1,0]
	v_add_u32_e32 v4, 0x1080, v43
	ds_write2_b32 v4, v2, v3 offset1:1
	v_pk_mul_f32 v[2:3], v[20:21], v[54:55] op_sel_hi:[1,0]
	v_add_u32_e32 v4, 0x1088, v43
	ds_write2_b32 v4, v2, v3 offset1:1
	s_waitcnt vmcnt(2)
	v_pk_mul_f32 v[2:3], v[22:23], v[48:49] op_sel_hi:[1,0]
	v_add_u32_e32 v4, 0x14a0, v43
	ds_write2_b32 v4, v2, v3 offset1:1
	v_pk_mul_f32 v[2:3], v[24:25], v[48:49] op_sel_hi:[1,0]
	v_add_u32_e32 v4, 0x14a8, v43
	ds_write2_b32 v4, v2, v3 offset1:1
	s_waitcnt vmcnt(1)
	v_pk_mul_f32 v[2:3], v[26:27], v[56:57] op_sel_hi:[1,0]
	v_add_u32_e32 v4, 0x18c0, v43
	ds_write2_b32 v4, v2, v3 offset1:1
	v_pk_mul_f32 v[2:3], v[28:29], v[56:57] op_sel_hi:[1,0]
	v_add_u32_e32 v4, 0x18c8, v43
	s_lshl_b32 s3, s19, 6
	ds_write2_b32 v4, v2, v3 offset1:1
	s_waitcnt vmcnt(0)
	v_pk_mul_f32 v[2:3], v[30:31], v[52:53] op_sel_hi:[1,0]
	v_add_u32_e32 v4, 0x1ce0, v43
	s_and_b32 s3, s3, 0x1f00
	s_and_b32 s2, s2, 0x60
	ds_write2_b32 v4, v2, v3 offset1:1
	v_pk_mul_f32 v[2:3], v[32:33], v[52:53] op_sel_hi:[1,0]
	v_add_u32_e32 v4, 0x1ce8, v43
	s_or_b32 s2, s2, s3
	ds_write2_b32 v4, v2, v3 offset1:1
	s_or_b32 s19, s2, 0x80
	s_waitcnt lgkmcnt(0)
	s_and_b32 s2, 0xffff, s16
	s_lshl_b32 s2, s2, 1
	ds_read2_b32 v[6:7], v53 offset0:33 offset1:41
	ds_read2_b32 v[8:9], v53 offset1:8
	ds_read2_b32 v[10:11], v53 offset0:66 offset1:74
	ds_read2_b32 v[12:13], v53 offset0:99 offset1:107
	ds_read2_b32 v[14:15], v53 offset0:132 offset1:140
	ds_read2_b32 v[16:17], v53 offset0:165 offset1:173
	ds_read2_b32 v[18:19], v53 offset0:198 offset1:206
	ds_read2_b32 v[20:21], v53 offset0:231 offset1:239
	s_add_u32 s2, s49, s2
	s_addc_u32 s3, s50, 0
	v_lshlrev_b32_e32 v36, 1, v38
	s_waitcnt lgkmcnt(6)
	v_cvt_pk_bf16_f32 v2, v8, v6
	v_or_b32_e32 v6, s19, v1
	v_lshl_add_u64 v[22:23], s[2:3], 0, v[36:37]
	v_lshlrev_b32_e32 v36, 11, v6
	v_lshl_add_u64 v[24:25], v[22:23], 0, v[36:37]
	s_waitcnt lgkmcnt(4)
	v_cvt_pk_bf16_f32 v3, v10, v12
	s_waitcnt lgkmcnt(2)
	v_cvt_pk_bf16_f32 v4, v14, v16
	s_waitcnt lgkmcnt(0)
	v_cvt_pk_bf16_f32 v5, v18, v20
	global_store_dwordx4 v[24:25], v[2:5], off nt
	v_or_b32_e32 v6, s19, v45
	v_lshlrev_b32_e32 v36, 11, v6
	v_cvt_pk_bf16_f32 v2, v9, v7
	v_cvt_pk_bf16_f32 v3, v11, v13
	v_cvt_pk_bf16_f32 v4, v15, v17
	v_cvt_pk_bf16_f32 v5, v19, v21
	ds_read2_b32 v[8:9], v53 offset0:16 offset1:24
	ds_read2_b32 v[10:11], v53 offset0:49 offset1:57
	ds_read2_b32 v[12:13], v53 offset0:82 offset1:90
	ds_read2_b32 v[14:15], v53 offset0:115 offset1:123
	ds_read2_b32 v[16:17], v53 offset0:148 offset1:156
	ds_read2_b32 v[18:19], v53 offset0:181 offset1:189
	ds_read2_b32 v[20:21], v53 offset0:214 offset1:222
	ds_read2_b32 v[24:25], v53 offset0:247 offset1:255
	v_lshl_add_u64 v[6:7], v[22:23], 0, v[36:37]
	global_store_dwordx4 v[6:7], v[2:5], off nt
	v_or_b32_e32 v6, s19, v47
	v_lshlrev_b32_e32 v36, 11, v6
	v_lshl_add_u64 v[6:7], v[22:23], 0, v[36:37]
	s_waitcnt lgkmcnt(6)
	v_cvt_pk_bf16_f32 v2, v8, v10
	s_waitcnt lgkmcnt(4)
	v_cvt_pk_bf16_f32 v3, v12, v14
	s_waitcnt lgkmcnt(2)
	v_cvt_pk_bf16_f32 v4, v16, v18
	s_waitcnt lgkmcnt(0)
	v_cvt_pk_bf16_f32 v5, v20, v24
	global_store_dwordx4 v[6:7], v[2:5], off nt
	v_or_b32_e32 v6, s19, v51
	v_lshlrev_b32_e32 v36, 11, v6
	v_lshl_add_u64 v[6:7], v[22:23], 0, v[36:37]
	v_cvt_pk_bf16_f32 v2, v9, v11
	v_cvt_pk_bf16_f32 v3, v13, v15
	v_cvt_pk_bf16_f32 v4, v17, v19
	v_cvt_pk_bf16_f32 v5, v21, v25
	global_store_dwordx4 v[6:7], v[2:5], off nt
	s_waitcnt lgkmcnt(0)

; #define TR_UP(IDX, GIDX, WT, ISUP) { const int kb = r / 88, n0 = (r % 88) * 32; transpose_item(P.in[IDX] + oU, D, DFF, P.in[GIDX] + l * D, WT, (n0 >> 7) * 256 + (n0 & 127) + (ISUP) * 128, scr, kb, n0, lane); return; }
; __device__ __forceinline__ void transpose_item(const float* W, int K, int N, const float* gain, bf16_t* WT, int dst_row0, LAS float* scr, int kb, int n0, int lane) {
;     const int k0 = 64 * kb, n4 = (lane & 7) * 4, kr = lane >> 3;
;     f32x4 v[8]; float g[8];
; #pragma unroll
;     for (int i = 0; i < 8; ++i) { v[i] = *(const f32x4*)(W + (size_t)(k0 + kr + 8 * i) * N + n0 + n4); g[i] = gain ? gain[k0 + kr + 8 * i] : 1.0f; }
; __device__ __forceinline__ void weight_item(const Params& P, unsigned char* ws, LAS float* scr, int l, int r, int lane) {
;     ...
;         if (r < I_UP) TR_UP(10, 9, W1a, 0)
.LBB0_180:
	s_andn2_b64 vcc, exec, s[2:3]
	s_cbranch_vccnz .LBB0_10
	s_mul_i32 s2, s51, 0xba3
	s_lshr_b32 s3, s2, 31
	s_ashr_i32 s2, s2, 18
	s_add_i32 s19, s2, s3
	s_load_dwordx16 s[64:79], s[0:1], 0x40
	s_mul_i32 s2, s19, 0x58
	s_sub_i32 s2, s51, s2
	s_sext_i32_i16 s16, s2
	s_lshl_b32 s22, s16, 5
	s_lshl_b64 s[2:3], s[20:21], 2
	s_waitcnt lgkmcnt(0)
	s_add_u32 s24, s68, s2
	s_addc_u32 s25, s69, s3
	s_lshl_b32 s2, s18, 10
	s_ashr_i32 s3, s2, 31
	s_lshl_b64 s[2:3], s[2:3], 2
	s_add_u32 s20, s66, s2
	s_addc_u32 s21, s67, s3
	s_ashr_i32 s23, s22, 31
	s_lshl_b32 s18, s19, 6
	s_lshl_b64 s[2:3], s[22:23], 2
	s_add_u32 s2, s24, s2
	v_or_b32_e32 v30, s18, v1
	s_addc_u32 s3, s25, s3
	v_mov_b32_e32 v43, v37
	v_lshl_add_u64 v[32:33], s[2:3], 0, v[42:43]
	v_mul_hi_i32_i24_e32 v3, 0x2c00, v30
	v_mul_i32_i24_e32 v2, 0x2c00, v30
	v_lshl_add_u64 v[2:3], v[32:33], 0, v[2:3]
	global_load_dwordx4 v[2:5], v[2:3], off nt
	v_ashrrev_i32_e32 v31, 31, v30
	v_cndmask_b32_e64 v6, 0, 1, s[14:15]
	v_mov_b32_e32 v36, 1.0
	v_cmp_ne_u32_e64 s[2:3], 1, v6
	s_andn2_b64 vcc, exec, s[14:15]
	v_lshl_add_u64 v[48:49], v[30:31], 2, s[20:21]
	v_mov_b32_e32 v44, 1.0
	s_cbranch_vccnz .LBB0_183
	global_load_dword v44, v[48:49], off
.LBB0_183:
	v_or_b32_e32 v6, 8, v30
	v_mul_hi_i32_i24_e32 v7, 0x2c00, v6
	v_mul_i32_i24_e32 v6, 0x2c00, v6
	v_lshl_add_u64 v[6:7], v[32:33], 0, v[6:7]
	global_load_dwordx4 v[6:9], v[6:7], off nt
	s_and_b64 vcc, exec, s[2:3]
	s_cbranch_vccnz .LBB0_185
	global_load_dword v36, v[48:49], off offset:32
.LBB0_185:
	v_or_b32_e32 v10, 16, v30
	v_mul_hi_i32_i24_e32 v11, 0x2c00, v10
	v_mul_i32_i24_e32 v10, 0x2c00, v10
	v_lshl_add_u64 v[10:11], v[32:33], 0, v[10:11]
	global_load_dwordx4 v[10:13], v[10:11], off nt
	v_mov_b32_e32 v46, 1.0
	s_and_b64 vcc, exec, s[2:3]
	v_mov_b32_e32 v50, 1.0
	s_cbranch_vccnz .LBB0_187
	global_load_dword v50, v[48:49], off offset:64
.LBB0_187:
	v_or_b32_e32 v14, 24, v30
	v_mul_hi_i32_i24_e32 v15, 0x2c00, v14
	v_mul_i32_i24_e32 v14, 0x2c00, v14
	v_lshl_add_u64 v[14:15], v[32:33], 0, v[14:15]
	global_load_dwordx4 v[14:17], v[14:15], off nt
	s_and_b64 vcc, exec, s[2:3]
	s_cbranch_vccnz .LBB0_189
	global_load_dword v46, v[48:49], off offset:96
.LBB0_189:
	v_or_b32_e32 v18, 32, v30
	v_mul_hi_i32_i24_e32 v19, 0x2c00, v18
	v_mul_i32_i24_e32 v18, 0x2c00, v18
	v_lshl_add_u64 v[18:19], v[32:33], 0, v[18:19]
	global_load_dwordx4 v[18:21], v[18:19], off nt
	v_mov_b32_e32 v52, 1.0
	s_and_b64 vcc, exec, s[2:3]
	v_mov_b32_e32 v54, 1.0
	s_cbranch_vccnz .LBB0_191
	global_load_dword v54, v[48:49], off offset:128
.LBB0_191:
	v_or_b32_e32 v22, 40, v30
	v_mul_hi_i32_i24_e32 v23, 0x2c00, v22
	v_mul_i32_i24_e32 v22, 0x2c00, v22
	v_lshl_add_u64 v[22:23], v[32:33], 0, v[22:23]
	global_load_dwordx4 v[22:25], v[22:23], off nt
	s_and_b64 vcc, exec, s[2:3]
	s_cbranch_vccnz .LBB0_193
	global_load_dword v52, v[48:49], off offset:160
.LBB0_193:
	v_or_b32_e32 v26, 48, v30
	v_mul_hi_i32_i24_e32 v27, 0x2c00, v26
	v_mul_i32_i24_e32 v26, 0x2c00, v26
	v_lshl_add_u64 v[26:27], v[32:33], 0, v[26:27]
	global_load_dwordx4 v[26:29], v[26:27], off nt
	v_mov_b32_e32 v56, 1.0
	s_and_b64 vcc, exec, s[2:3]
	v_mov_b32_e32 v58, 1.0
	s_cbranch_vccnz .LBB0_195
	global_load_dword v58, v[48:49], off offset:192
.LBB0_195:
	v_or_b32_e32 v30, 56, v30
	v_mul_hi_i32_i24_e32 v31, 0x2c00, v30
	v_mul_i32_i24_e32 v30, 0x2c00, v30
	v_lshl_add_u64 v[30:31], v[32:33], 0, v[30:31]
	global_load_dwordx4 v[30:33], v[30:31], off nt
	s_and_b64 vcc, exec, s[2:3]
	s_cbranch_vccnz .LBB0_9
	global_load_dword v56, v[48:49], off offset:224
	s_branch .LBB0_9

; __device__ __forceinline__ unsigned cvt_pk_bf16(float lo, float hi) { unsigned r; asm("v_cvt_pk_bf16_f32 %0, %1, %2" : "=v"(r) : "v"(lo), "v"(hi)); return r; }
; __device__ __forceinline__ void prologue(const Params& P, LAS unsigned char* lds, int G, int vcu) {
;     ...
;     for (int m = gw; m < T + 512; m += NGW) {
;         const bool ismem = m >= T;
;         const float* xp0 = P.in[0]; const float* xs0 = P.in[1]; const float* mp0 = P.in[2];
;         const float* src = ismem ? mp0 + (size_t)(m - T) * D : (m < TP ? xp0 + (size_t)m * D : xs0 + (size_t)(m - TP) * D);
;         f32x4 v[4]; float ss = 0.f;
; #pragma unroll
;         for (int j = 0; j < 4; ++j) { v[j] = ((const f32x4*)src)[lane + 64 * j]; ss += (v[j][0] * v[j][0] + v[j][1] * v[j][1]) + (v[j][2] * v[j][2] + v[j][3] * v[j][3]); }
;         ss = wave_sum(ss);
;         bf16_t* xb = ismem ? (bf16_t*)(ws + WS_MEMB) + (size_t)(m - T) * D : XB + (size_t)m * D;
;         float* ssp = ismem ? (float*)(ws + WS_SSM) + (size_t)(m - T) * 16 : SS + (size_t)m * 16;
; #pragma unroll
;         for (int j = 0; j < 4; ++j) {
;             u32x2 w; w.x = cvt_pk_bf16(v[j][0], v[j][1]); w.y = cvt_pk_bf16(v[j][2], v[j][3]);
;             ((u32x2*)xb)[lane + 64 * j] = w;
;         }
;         if (lane < 16) ssp[lane] = lane == 0 ? ss : 0.f;
.LBB0_201:
	s_add_i32 s10, s8, s60
	s_cmpk_lt_i32 s10, 0x4000
	s_cbranch_scc0 .Lxc_slow
	v_readlane_b32 s36, v253, 55
	v_readlane_b32 s37, v253, 56
	s_ashr_i32 s11, s10, 31
	s_lshl_b64 s[16:17], s[8:9], 12
	s_lshl_b64 s[18:19], s[10:11], 12
	s_add_u32 s16, s36, s16
	s_addc_u32 s17, s37, s17
	s_add_u32 s18, s36, s18
	s_addc_u32 s19, s37, s19
	global_load_dwordx4 v[12:15], v7, s[16:17] nt
	global_load_dwordx4 v[16:19], v7, s[16:17] offset:1024 nt
	global_load_dwordx4 v[20:23], v7, s[16:17] offset:2048 nt
	global_load_dwordx4 v[24:27], v7, s[16:17] offset:3072 nt
	global_load_dwordx4 v[40:43], v7, s[18:19] nt
	global_load_dwordx4 v[44:47], v7, s[18:19] offset:1024 nt
	global_load_dwordx4 v[48:51], v7, s[18:19] offset:2048 nt
	global_load_dwordx4 v[52:55], v7, s[18:19] offset:3072 nt
	s_lshl_b64 s[12:13], s[8:9], 11
	s_add_u32 s12, s12, 0x4200000
	s_addc_u32 s13, s13, 0
	s_add_u32 s12, s12, s94
	s_addc_u32 s13, s13, s95
	s_lshl_b64 s[14:15], s[10:11], 11
	s_add_u32 s14, s14, 0x4200000
	s_addc_u32 s15, s15, 0
	s_add_u32 s14, s14, s94
	s_addc_u32 s15, s15, s95
	s_lshl_b64 s[38:39], s[8:9], 6
	s_add_u32 s38, s38, 0x6300000
	s_addc_u32 s39, s39, 0
	s_add_u32 s38, s38, s94
	s_addc_u32 s39, s39, s95
	s_lshl_b64 s[40:41], s[10:11], 6
	s_add_u32 s40, s40, 0x6300000
	s_addc_u32 s41, s41, 0
	s_add_u32 s40, s40, s94
	s_addc_u32 s41, s41, s95
	s_waitcnt vmcnt(7)
	v_mul_f32_e32 v11, v13, v13
	v_mul_f32_e32 v28, v15, v15
	s_waitcnt vmcnt(6)
	v_mul_f32_e32 v29, v17, v17
	v_mul_f32_e32 v30, v19, v19
	s_waitcnt vmcnt(5)
	v_mul_f32_e32 v31, v21, v21
	v_mul_f32_e32 v32, v23, v23
	v_fmac_f32_e32 v11, v12, v12
	v_fmac_f32_e32 v28, v14, v14
	v_fmac_f32_e32 v29, v16, v16
	v_fmac_f32_e32 v30, v18, v18
	s_waitcnt vmcnt(4)
	v_mul_f32_e32 v33, v25, v25
	v_mul_f32_e32 v35, v27, v27
	v_fmac_f32_e32 v31, v20, v20
	v_fmac_f32_e32 v32, v22, v22
	v_add_f32_e32 v11, v11, v28
	v_add_f32_e32 v28, v29, v30
	v_fmac_f32_e32 v33, v24, v24
	v_fmac_f32_e32 v35, v26, v26
	v_add_f32_e32 v29, v31, v32
	v_add_f32_e32 v11, v11, v28
	v_add_f32_e32 v30, v33, v35
	v_add_f32_e32 v11, v11, v29
	v_add_f32_e32 v11, v11, v30
	ds_bpermute_b32 v28, v1, v11
	v_cvt_pk_bf16_f32 v12, v12, v13
	v_cvt_pk_bf16_f32 v13, v14, v15
	v_cvt_pk_bf16_f32 v14, v16, v17
	v_cvt_pk_bf16_f32 v15, v18, v19
	v_cvt_pk_bf16_f32 v16, v20, v21
	v_cvt_pk_bf16_f32 v17, v22, v23
	v_cvt_pk_bf16_f32 v18, v24, v25
	v_cvt_pk_bf16_f32 v19, v26, v27
	global_store_dwordx2 v8, v[12:13], s[12:13]
	global_store_dwordx2 v8, v[14:15], s[12:13] offset:512
	global_store_dwordx2 v8, v[16:17], s[12:13] offset:1024
	global_store_dwordx2 v8, v[18:19], s[12:13] offset:1536
	s_waitcnt vmcnt(7)
	v_mul_f32_e32 v56, v41, v41
	v_mul_f32_e32 v57, v43, v43
	s_waitcnt vmcnt(6)
	v_mul_f32_e32 v58, v45, v45
	v_mul_f32_e32 v59, v47, v47
	s_waitcnt vmcnt(5)
	v_mul_f32_e32 v60, v49, v49
	v_mul_f32_e32 v61, v51, v51
	v_fmac_f32_e32 v56, v40, v40
	v_fmac_f32_e32 v57, v42, v42
	v_fmac_f32_e32 v58, v44, v44
	v_fmac_f32_e32 v59, v46, v46
	s_waitcnt vmcnt(4)
	v_mul_f32_e32 v62, v53, v53
	v_mul_f32_e32 v63, v55, v55
	v_fmac_f32_e32 v60, v48, v48
	v_fmac_f32_e32 v61, v50, v50
	v_add_f32_e32 v56, v56, v57
	v_add_f32_e32 v57, v58, v59
	v_fmac_f32_e32 v62, v52, v52
	v_fmac_f32_e32 v63, v54, v54
	v_add_f32_e32 v58, v60, v61
	v_add_f32_e32 v56, v56, v57
	v_add_f32_e32 v59, v62, v63
	v_add_f32_e32 v56, v56, v58
	v_add_f32_e32 v56, v56, v59
	ds_bpermute_b32 v57, v1, v56
	v_cvt_pk_bf16_f32 v40, v40, v41
	v_cvt_pk_bf16_f32 v41, v42, v43
	v_cvt_pk_bf16_f32 v42, v44, v45
	v_cvt_pk_bf16_f32 v43, v46, v47
	v_cvt_pk_bf16_f32 v44, v48, v49
	v_cvt_pk_bf16_f32 v45, v50, v51
	v_cvt_pk_bf16_f32 v46, v52, v53
	v_cvt_pk_bf16_f32 v47, v54, v55
	global_store_dwordx2 v8, v[40:41], s[14:15]
	global_store_dwordx2 v8, v[42:43], s[14:15] offset:512
	global_store_dwordx2 v8, v[44:45], s[14:15] offset:1024
	global_store_dwordx2 v8, v[46:47], s[14:15] offset:1536
	s_waitcnt lgkmcnt(1)
	v_add_f32_e32 v11, v11, v28
	ds_bpermute_b32 v28, v2, v11
	s_waitcnt lgkmcnt(1)
	v_add_f32_e32 v56, v56, v57
	ds_bpermute_b32 v57, v2, v56
	s_waitcnt lgkmcnt(1)
	v_add_f32_e32 v11, v11, v28
	ds_bpermute_b32 v28, v3, v11
	s_waitcnt lgkmcnt(1)
	v_add_f32_e32 v56, v56, v57
	ds_bpermute_b32 v57, v3, v56
	s_waitcnt lgkmcnt(1)
	v_add_f32_e32 v11, v11, v28
	ds_bpermute_b32 v28, v4, v11
	s_waitcnt lgkmcnt(1)
	v_add_f32_e32 v56, v56, v57
	ds_bpermute_b32 v57, v4, v56
	s_waitcnt lgkmcnt(1)
	v_add_f32_e32 v11, v11, v28
	ds_bpermute_b32 v28, v5, v11
	s_waitcnt lgkmcnt(1)
	v_add_f32_e32 v56, v56, v57
	ds_bpermute_b32 v57, v5, v56
	s_waitcnt lgkmcnt(1)
	v_add_f32_e32 v11, v11, v28
	ds_bpermute_b32 v28, v6, v11
	s_waitcnt lgkmcnt(1)
	v_add_f32_e32 v56, v56, v57
	ds_bpermute_b32 v57, v6, v56
	s_waitcnt lgkmcnt(1)
	v_add_f32_e32 v11, v11, v28
	s_waitcnt lgkmcnt(0)
	v_add_f32_e32 v56, v56, v57
	s_and_saveexec_b64 s[42:43], s[0:1]
	v_cndmask_b32_e64 v11, 0, v11, s[2:3]
	v_cndmask_b32_e64 v56, 0, v56, s[2:3]
	global_store_dword v9, v11, s[38:39]
	global_store_dword v9, v56, s[40:41]
	s_or_b64 exec, exec, s[42:43]
	s_add_u32 s8, s8, s60
	s_addc_u32 s9, s9, s20
	s_mov_b64 s[14:15], exec
	s_branch .LBB0_200

; __device__ __forceinline__ unsigned cvt_pk_bf16(float lo, float hi) { unsigned r; asm("v_cvt_pk_bf16_f32 %0, %1, %2" : "=v"(r) : "v"(lo), "v"(hi)); return r; }
; __device__ __forceinline__ void prologue(const Params& P, LAS unsigned char* lds, int G, int vcu) {
;     ...
;     for (int m = gw; m < T + 512; m += NGW) {
;         const bool ismem = m >= T;
;         const float* xp0 = P.in[0]; const float* xs0 = P.in[1]; const float* mp0 = P.in[2];
;         const float* src = ismem ? mp0 + (size_t)(m - T) * D : (m < TP ? xp0 + (size_t)m * D : xs0 + (size_t)(m - TP) * D);
;         f32x4 v[4]; float ss = 0.f;
; #pragma unroll
;         for (int j = 0; j < 4; ++j) { v[j] = ((const f32x4*)src)[lane + 64 * j]; ss += (v[j][0] * v[j][0] + v[j][1] * v[j][1]) + (v[j][2] * v[j][2] + v[j][3] * v[j][3]); }
;         ss = wave_sum(ss);
;         bf16_t* xb = ismem ? (bf16_t*)(ws + WS_MEMB) + (size_t)(m - T) * D : XB + (size_t)m * D;
;         float* ssp = ismem ? (float*)(ws + WS_SSM) + (size_t)(m - T) * 16 : SS + (size_t)m * 16;
; #pragma unroll
;         for (int j = 0; j < 4; ++j) {
;             u32x2 w; w.x = cvt_pk_bf16(v[j][0], v[j][1]); w.y = cvt_pk_bf16(v[j][2], v[j][3]);
;             ((u32x2*)xb)[lane + 64 * j] = w;
;         }
;         if (lane < 16) ssp[lane] = lane == 0 ? ss : 0.f;
.LBB0_208:
	s_lshl_b64 s[18:19], s[18:19], 12
	s_add_u32 s16, s16, s18
	s_addc_u32 s17, s17, s19
	s_waitcnt lgkmcnt(0)
	global_load_dwordx4 v[12:15], v7, s[16:17] nt
	global_load_dwordx4 v[16:19], v7, s[16:17] offset:1024 nt
	global_load_dwordx4 v[20:23], v7, s[16:17] offset:2048 nt
	global_load_dwordx4 v[24:27], v7, s[16:17] offset:3072 nt
	s_add_i32 s6, s8, 0xffffbe00
	s_and_b64 s[12:13], s[12:13], exec
	s_cselect_b32 s13, 0, s9
	s_cselect_b32 s12, s6, s8
	s_add_u32 s6, s94, s14
	s_addc_u32 s16, s95, s15
	s_lshl_b64 s[14:15], s[12:13], 11
	s_add_u32 s14, s6, s14
	s_addc_u32 s15, s16, s15
	s_waitcnt vmcnt(3)
	v_mul_f32_e32 v11, v13, v13
	v_mul_f32_e32 v28, v15, v15
	s_waitcnt vmcnt(2)
	v_mul_f32_e32 v29, v17, v17
	v_mul_f32_e32 v30, v19, v19
	s_waitcnt vmcnt(1)
	v_mul_f32_e32 v31, v21, v21
	v_mul_f32_e32 v32, v23, v23
	v_fmac_f32_e32 v11, v12, v12
	v_fmac_f32_e32 v28, v14, v14
	v_fmac_f32_e32 v29, v16, v16
	v_fmac_f32_e32 v30, v18, v18
	s_waitcnt vmcnt(0)
	v_mul_f32_e32 v33, v25, v25
	v_mul_f32_e32 v35, v27, v27
	v_fmac_f32_e32 v31, v20, v20
	v_fmac_f32_e32 v32, v22, v22
	v_add_f32_e32 v11, v11, v28
	v_add_f32_e32 v28, v29, v30
	v_fmac_f32_e32 v33, v24, v24
	v_fmac_f32_e32 v35, v26, v26
	v_add_f32_e32 v29, v31, v32
	v_add_f32_e32 v11, v11, v28
	v_add_f32_e32 v30, v33, v35
	v_add_f32_e32 v11, v11, v29
	v_add_f32_e32 v11, v11, v30
	ds_bpermute_b32 v28, v1, v11
	v_cvt_pk_bf16_f32 v12, v12, v13
	v_cvt_pk_bf16_f32 v13, v14, v15
	v_cvt_pk_bf16_f32 v14, v16, v17
	v_cvt_pk_bf16_f32 v15, v18, v19
	s_waitcnt lgkmcnt(0)
	v_add_f32_e32 v11, v11, v28
	ds_bpermute_b32 v28, v2, v11
	global_store_dwordx2 v8, v[12:13], s[14:15]
	global_store_dwordx2 v8, v[14:15], s[14:15] offset:512
	v_cvt_pk_bf16_f32 v16, v20, v21
	v_cvt_pk_bf16_f32 v14, v24, v25
	v_cvt_pk_bf16_f32 v15, v26, v27
	s_waitcnt lgkmcnt(0)
	v_add_f32_e32 v11, v11, v28
	ds_bpermute_b32 v28, v3, v11
	global_store_dwordx2 v8, v[14:15], s[14:15] offset:1536
	s_waitcnt lgkmcnt(0)
	v_add_f32_e32 v11, v11, v28
	ds_bpermute_b32 v28, v4, v11
	s_waitcnt lgkmcnt(0)
	v_add_f32_e32 v11, v11, v28
	ds_bpermute_b32 v17, v5, v11
	s_waitcnt lgkmcnt(0)
	v_add_f32_e32 v11, v11, v17
	ds_bpermute_b32 v12, v6, v11
	v_cvt_pk_bf16_f32 v17, v22, v23
	global_store_dwordx2 v8, v[16:17], s[14:15] offset:1024
	s_and_saveexec_b64 s[14:15], s[0:1]
	s_cbranch_execz .LBB0_200
	s_add_u32 s6, s94, s10
	s_addc_u32 s16, s95, s11
	s_lshl_b64 s[10:11], s[12:13], 6
	s_waitcnt lgkmcnt(0)
	v_add_f32_e32 v11, v11, v12
	s_add_u32 s10, s6, s10
	v_cndmask_b32_e64 v11, 0, v11, s[2:3]
	s_addc_u32 s11, s16, s11
	global_store_dword v9, v11, s[10:11]
	s_branch .LBB0_200

; #define LAS __attribute__((address_space(3)))
; __device__ __forceinline__ void small_gemm_q256(LAS unsigned char* lds, const bf16_t* A, const bf16_t* Bt, int unit, const float* SS, float sc, bf16_t* OUT) {
;     int tid = threadIdx.x; asm volatile("" : "+v"(tid));
;     const int wave = __builtin_amdgcn_readfirstlane(tid >> 6), lane = tid & 63, li = lane & 15, g4 = lane >> 4;
;     const int rt = unit >> 2, ct = unit & 3, row0 = TP + 16 * rt, col0 = 256 * ct;
;     constexpr int K = D, KS = 4;
;     const int row = tid >> 5;
;     f32x4 sv[4];
; #pragma unroll
;     for (int q = 0; q < 4; ++q) sv[q] = ((const f32x4*)(SS + (size_t)(row0 + row) * 16))[q];
;     f32x4 acc[16];
; #pragma unroll
;     for (int t = 0; t < 16; ++t) acc[t] = (f32x4){0.f, 0.f, 0.f, 0.f};
;     const bf16_t* ap = A + (size_t)(row0 + li) * K + 8 * g4 + 32 * wave * KS;
;     const bf16_t* bp = Bt + (size_t)(col0 + li) * K + 8 * g4 + 32 * wave * KS;
.LBB0_586:
	v_mov_b32_e32 v112, v208
	s_and_b32 s4, s12, -16
	v_readfirstlane_b32 s0, v112
	s_ashr_i32 s3, s0, 6
	s_lshl_b32 s0, s14, 2
	s_and_b32 s0, s0, -16
	s_addk_i32 s0, 0x4000
	v_ashrrev_i32_e32 v113, 5, v112
	v_add_u32_e32 v82, s0, v113
	v_ashrrev_i32_e32 v83, 31, v82
	v_lshlrev_b64 v[2:3], 6, v[82:83]
	v_lshl_add_u64 v[2:3], s[10:11], 0, v[2:3]
	global_load_dwordx4 v[14:17], v[2:3], off
	global_load_dwordx4 v[10:13], v[2:3], off offset:16
	global_load_dwordx4 v[6:9], v[2:3], off offset:32
	s_nop 0
	global_load_dwordx4 v[2:5], v[2:3], off offset:48
	v_and_b32_e32 v0, 15, v112
	s_lshl_b32 s0, s3, 7
	s_addk_i32 s4, 0x4000
	s_ashr_i32 s1, s0, 31
	v_or_b32_e32 v18, s4, v0
	s_lshr_b32 s2, s13, 8
	v_ashrrev_i32_e32 v19, 31, v18
	s_lshl_b64 s[0:1], s[0:1], 1
	v_lshlrev_b64 v[18:19], 11, v[18:19]
	v_and_b32_e32 v20, 48, v112
	s_add_u32 s4, s22, s0
	v_or_b32_e32 v18, v18, v20
	s_addc_u32 s5, s23, s1
	v_lshl_add_u64 v[84:85], s[4:5], 0, v[18:19]
	v_or_b32_e32 v18, s0, v20
	s_lshl_b32 s0, s13, 11
	s_and_b32 s0, s0, 0x180000
	v_mov_b32_e32 v19, s1
	v_lshlrev_b32_e32 v115, 10, v0
	v_lshl_or_b32 v0, v0, 11, s0
	v_lshl_add_u64 v[18:19], v[18:19], 0, v[0:1]
	v_lshl_add_u64 v[86:87], s[20:21], 0, v[18:19]
	v_mov_b32_e32 v18, 0
	s_mov_b32 s19, s47
	s_mov_b32 s18, s45
	v_lshrrev_b32_e32 v114, 4, v112
	s_mov_b64 s[0:1], 0
	v_mov_b32_e32 v19, v18
	v_mov_b32_e32 v20, v18
	v_mov_b32_e32 v21, v18
	v_mov_b32_e32 v22, v18
	v_mov_b32_e32 v23, v18
	v_mov_b32_e32 v24, v18
	v_mov_b32_e32 v25, v18
	v_mov_b32_e32 v26, v18
	v_mov_b32_e32 v27, v18
	v_mov_b32_e32 v28, v18
	v_mov_b32_e32 v29, v18
	v_mov_b32_e32 v30, v18
	v_mov_b32_e32 v31, v18
	v_mov_b32_e32 v32, v18
	v_mov_b32_e32 v33, v18
	v_mov_b32_e32 v34, v18
	v_mov_b32_e32 v35, v18
	v_mov_b32_e32 v36, v18
	v_mov_b32_e32 v37, v18
	v_mov_b32_e32 v38, v18
	v_mov_b32_e32 v39, v18
	v_mov_b32_e32 v40, v18
	v_mov_b32_e32 v41, v18
	v_mov_b32_e32 v42, v18
	v_mov_b32_e32 v43, v18
	v_mov_b32_e32 v44, v18
	v_mov_b32_e32 v45, v18
	v_mov_b32_e32 v50, v18
	v_mov_b32_e32 v51, v18
	v_mov_b32_e32 v52, v18
	v_mov_b32_e32 v53, v18
	v_mov_b32_e32 v54, v18
	v_mov_b32_e32 v55, v18
	v_mov_b32_e32 v56, v18
	v_mov_b32_e32 v57, v18
	v_mov_b32_e32 v58, v18
	v_mov_b32_e32 v59, v18
	v_mov_b32_e32 v60, v18
	v_mov_b32_e32 v61, v18
	v_mov_b32_e32 v62, v18
	v_mov_b32_e32 v63, v18
	v_mov_b32_e32 v64, v18
	v_mov_b32_e32 v65, v18
	v_mov_b32_e32 v66, v18
	v_mov_b32_e32 v67, v18
	v_mov_b32_e32 v68, v18
	v_mov_b32_e32 v69, v18
	v_mov_b32_e32 v70, v18
	v_mov_b32_e32 v71, v18
	v_mov_b32_e32 v72, v18
	v_mov_b32_e32 v73, v18
	v_mov_b32_e32 v74, v18
	v_mov_b32_e32 v75, v18
	v_mov_b32_e32 v76, v18
	v_mov_b32_e32 v77, v18
	v_mov_b32_e32 v78, v18
	v_mov_b32_e32 v79, v18
	v_mov_b32_e32 v80, v18
	v_mov_b32_e32 v81, v18
	v_mov_b32_e32 v46, v18
	v_mov_b32_e32 v47, v18
	v_mov_b32_e32 v48, v18
	v_mov_b32_e32 v49, v18
	v_bfe_u32 v132, v112, 2, 4
	v_and_b32_e32 v133, 15, v112
	v_sub_u32_e32 v132, v132, v133
	v_lshlrev_b32_e32 v132, 11, v132
	v_and_b32_e32 v134, 3, v112
	v_lshlrev_b32_e32 v134, 4, v134
	v_and_b32_e32 v135, 48, v112
	v_sub_u32_e32 v134, v134, v135
	v_add_u32_e32 v132, v132, v134
	v_ashrrev_i32_e32 v133, 31, v132
	v_lshl_add_u64 v[84:85], v[84:85], 0, v[132:133]
	v_lshl_add_u64 v[86:87], v[86:87], 0, v[132:133]
	s_lshl_b32 s4, s3, 14
	v_and_b32_e32 v136, 15, v112
	v_lshl_add_u32 v136, v136, 6, v135
	v_add_u32_e32 v136, s4, v136
	s_mov_b64 s[0:1], 0x8000
	s_add_i32 m0, s4, 0x0
	s_nop 0
	global_load_lds_dwordx4 v[84:85], off
	v_lshl_add_u64 v[84:85], v[84:85], 0, 64
	s_add_i32 m0, s4, 0x400
	s_nop 0
	global_load_lds_dwordx4 v[86:87], off
	s_add_i32 m0, s4, 0x800
	v_lshl_add_u64 v[144:145], v[86:87], 0, s[0:1]
	global_load_lds_dwordx4 v[144:145], off
	s_add_i32 m0, s4, 0xc00
	v_lshl_add_u64 v[146:147], v[144:145], 0, s[0:1]
	global_load_lds_dwordx4 v[146:147], off
	s_add_i32 m0, s4, 0x1000
	v_lshl_add_u64 v[144:145], v[146:147], 0, s[0:1]
	global_load_lds_dwordx4 v[144:145], off
	s_add_i32 m0, s4, 0x1400
	v_lshl_add_u64 v[146:147], v[144:145], 0, s[0:1]
	global_load_lds_dwordx4 v[146:147], off
	s_add_i32 m0, s4, 0x1800
	v_lshl_add_u64 v[144:145], v[146:147], 0, s[0:1]
	global_load_lds_dwordx4 v[144:145], off
	s_add_i32 m0, s4, 0x1c00
	v_lshl_add_u64 v[146:147], v[144:145], 0, s[0:1]
	global_load_lds_dwordx4 v[146:147], off
	s_add_i32 m0, s4, 0x2000
	v_lshl_add_u64 v[144:145], v[146:147], 0, s[0:1]
	global_load_lds_dwordx4 v[144:145], off
	s_add_i32 m0, s4, 0x2400
	v_lshl_add_u64 v[146:147], v[144:145], 0, s[0:1]
	global_load_lds_dwordx4 v[146:147], off
	s_add_i32 m0, s4, 0x2800
	v_lshl_add_u64 v[144:145], v[146:147], 0, s[0:1]
	global_load_lds_dwordx4 v[144:145], off
	s_add_i32 m0, s4, 0x2c00
	v_lshl_add_u64 v[146:147], v[144:145], 0, s[0:1]
	global_load_lds_dwordx4 v[146:147], off
	s_add_i32 m0, s4, 0x3000
	v_lshl_add_u64 v[144:145], v[146:147], 0, s[0:1]
	global_load_lds_dwordx4 v[144:145], off
	s_add_i32 m0, s4, 0x3400
	v_lshl_add_u64 v[146:147], v[144:145], 0, s[0:1]
	global_load_lds_dwordx4 v[146:147], off
	s_add_i32 m0, s4, 0x3800
	v_lshl_add_u64 v[144:145], v[146:147], 0, s[0:1]
	global_load_lds_dwordx4 v[144:145], off
	s_add_i32 m0, s4, 0x3c00
	v_lshl_add_u64 v[146:147], v[144:145], 0, s[0:1]
	global_load_lds_dwordx4 v[146:147], off
	s_waitcnt vmcnt(11)
	ds_read_b128 v[88:91], v136 offset:0
	ds_read_b128 v[96:99], v136 offset:1024
	ds_read_b128 v[100:103], v136 offset:2048
	ds_read_b128 v[104:107], v136 offset:3072
	ds_read_b128 v[108:111], v136 offset:4096
	s_waitcnt vmcnt(7)
	ds_read_b128 v[116:119], v136 offset:5120
	ds_read_b128 v[120:123], v136 offset:6144
	ds_read_b128 v[124:127], v136 offset:7168
	ds_read_b128 v[128:131], v136 offset:8192
	s_waitcnt lgkmcnt(4)
; __device__ __forceinline__ void small_gemm_q256(LAS unsigned char* lds, const bf16_t* A, const bf16_t* Bt, int unit, const float* SS, float sc, bf16_t* OUT) {
;     ...
; #pragma unroll 2
;     for (int ks = 0; ks < KS; ++ks) {
;         const bf16x8 a = *(const bf16x8*)(ap + 32 * ks);
; #pragma unroll
;         for (int t = 0; t < 16; ++t) { const bf16x8 b = *(const bf16x8*)(bp + (size_t)16 * t * K + 32 * ks); acc[t] = __builtin_amdgcn_mfma_f32_16x16x32_bf16(b, a, acc[t], 0, 0, 0); }
;     }
	v_mfma_f32_16x16x32_bf16 v[46:49], v[96:99], v[88:91], v[46:49]
	v_mfma_f32_16x16x32_bf16 v[78:81], v[100:103], v[88:91], v[78:81]
	v_mfma_f32_16x16x32_bf16 v[74:77], v[104:107], v[88:91], v[74:77]
	v_mfma_f32_16x16x32_bf16 v[70:73], v[108:111], v[88:91], v[70:73]
	s_add_i32 m0, s4, 0x0
	v_lshl_add_u64 v[144:145], v[146:147], 0, s[0:1]
	global_load_lds_dwordx4 v[144:145], off
	v_lshl_add_u64 v[86:87], v[86:87], 0, 64
	s_add_i32 m0, s4, 0x400
	s_nop 0
	global_load_lds_dwordx4 v[84:85], off
	v_lshl_add_u64 v[84:85], v[84:85], 0, 64
	s_add_i32 m0, s4, 0x800
	s_nop 0
	global_load_lds_dwordx4 v[86:87], off
	s_add_i32 m0, s4, 0xc00
	v_lshl_add_u64 v[144:145], v[86:87], 0, s[0:1]
	global_load_lds_dwordx4 v[144:145], off
	s_add_i32 m0, s4, 0x1000
	v_lshl_add_u64 v[146:147], v[144:145], 0, s[0:1]
	global_load_lds_dwordx4 v[146:147], off
	s_waitcnt vmcnt(8)
	ds_read_b128 v[96:99], v136 offset:9216
	ds_read_b128 v[100:103], v136 offset:10240
	ds_read_b128 v[104:107], v136 offset:11264
	ds_read_b128 v[108:111], v136 offset:12288
	s_waitcnt lgkmcnt(4)
	v_mfma_f32_16x16x32_bf16 v[66:69], v[116:119], v[88:91], v[66:69]
	v_mfma_f32_16x16x32_bf16 v[62:65], v[120:123], v[88:91], v[62:65]
	v_mfma_f32_16x16x32_bf16 v[58:61], v[124:127], v[88:91], v[58:61]
	v_mfma_f32_16x16x32_bf16 v[54:57], v[128:131], v[88:91], v[54:57]
	s_add_i32 m0, s4, 0x1400
	v_lshl_add_u64 v[144:145], v[146:147], 0, s[0:1]
	global_load_lds_dwordx4 v[144:145], off
	s_add_i32 m0, s4, 0x1800
	v_lshl_add_u64 v[146:147], v[144:145], 0, s[0:1]
	global_load_lds_dwordx4 v[146:147], off
	s_add_i32 m0, s4, 0x1c00
	v_lshl_add_u64 v[144:145], v[146:147], 0, s[0:1]
	global_load_lds_dwordx4 v[144:145], off
	s_add_i32 m0, s4, 0x2000
	v_lshl_add_u64 v[146:147], v[144:145], 0, s[0:1]
	global_load_lds_dwordx4 v[146:147], off
	s_waitcnt vmcnt(8)
	ds_read_b128 v[116:119], v136 offset:13312
	ds_read_b128 v[120:123], v136 offset:14336
	ds_read_b128 v[124:127], v136 offset:15360
	ds_read_b128 v[128:131], v136 offset:0
	s_waitcnt lgkmcnt(4)
	v_mfma_f32_16x16x32_bf16 v[50:53], v[96:99], v[88:91], v[50:53]
	v_mfma_f32_16x16x32_bf16 v[42:45], v[100:103], v[88:91], v[42:45]
	v_mfma_f32_16x16x32_bf16 v[38:41], v[104:107], v[88:91], v[38:41]
	v_mfma_f32_16x16x32_bf16 v[34:37], v[108:111], v[88:91], v[34:37]
	s_add_i32 m0, s4, 0x2400
	v_lshl_add_u64 v[144:145], v[146:147], 0, s[0:1]
	global_load_lds_dwordx4 v[144:145], off
	s_add_i32 m0, s4, 0x2800
	v_lshl_add_u64 v[146:147], v[144:145], 0, s[0:1]
	global_load_lds_dwordx4 v[146:147], off
	s_add_i32 m0, s4, 0x2c00
	v_lshl_add_u64 v[144:145], v[146:147], 0, s[0:1]
	global_load_lds_dwordx4 v[144:145], off
	s_add_i32 m0, s4, 0x3000
	v_lshl_add_u64 v[146:147], v[144:145], 0, s[0:1]
	global_load_lds_dwordx4 v[146:147], off
	s_waitcnt vmcnt(7)
	ds_read_b128 v[92:95], v136 offset:1024
	ds_read_b128 v[96:99], v136 offset:2048
	ds_read_b128 v[100:103], v136 offset:3072
	ds_read_b128 v[104:107], v136 offset:4096
	ds_read_b128 v[108:111], v136 offset:5120
	s_waitcnt lgkmcnt(5)
	v_mfma_f32_16x16x32_bf16 v[30:33], v[116:119], v[88:91], v[30:33]
	v_mfma_f32_16x16x32_bf16 v[26:29], v[120:123], v[88:91], v[26:29]
	v_mfma_f32_16x16x32_bf16 v[22:25], v[124:127], v[88:91], v[22:25]
	v_mfma_f32_16x16x32_bf16 v[18:21], v[128:131], v[88:91], v[18:21]
	s_add_i32 m0, s4, 0x3400
	v_lshl_add_u64 v[144:145], v[146:147], 0, s[0:1]
	global_load_lds_dwordx4 v[144:145], off
	s_add_i32 m0, s4, 0x3800
	v_lshl_add_u64 v[146:147], v[144:145], 0, s[0:1]
	global_load_lds_dwordx4 v[146:147], off
	s_add_i32 m0, s4, 0x3c00
	v_lshl_add_u64 v[144:145], v[146:147], 0, s[0:1]
	global_load_lds_dwordx4 v[144:145], off
	s_add_i32 m0, s4, 0x0
	v_lshl_add_u64 v[146:147], v[144:145], 0, s[0:1]
	global_load_lds_dwordx4 v[146:147], off
	s_waitcnt vmcnt(7)
	ds_read_b128 v[116:119], v136 offset:6144
	ds_read_b128 v[120:123], v136 offset:7168
	ds_read_b128 v[124:127], v136 offset:8192
	ds_read_b128 v[128:131], v136 offset:9216
	s_waitcnt lgkmcnt(4)
	v_mfma_f32_16x16x32_bf16 v[46:49], v[96:99], v[92:95], v[46:49]
	v_mfma_f32_16x16x32_bf16 v[78:81], v[100:103], v[92:95], v[78:81]
	v_mfma_f32_16x16x32_bf16 v[74:77], v[104:107], v[92:95], v[74:77]
	v_mfma_f32_16x16x32_bf16 v[70:73], v[108:111], v[92:95], v[70:73]
	s_add_i32 m0, s4, 0x400
	v_lshl_add_u64 v[144:145], v[146:147], 0, s[0:1]
	global_load_lds_dwordx4 v[144:145], off
	v_lshl_add_u64 v[86:87], v[86:87], 0, 64
	s_add_i32 m0, s4, 0x800
	s_nop 0
	global_load_lds_dwordx4 v[84:85], off
	v_lshl_add_u64 v[84:85], v[84:85], 0, 64
	s_add_i32 m0, s4, 0xc00
	s_nop 0
	global_load_lds_dwordx4 v[86:87], off
	s_add_i32 m0, s4, 0x1000
	v_lshl_add_u64 v[144:145], v[86:87], 0, s[0:1]
	global_load_lds_dwordx4 v[144:145], off
	s_add_i32 m0, s4, 0x1400
	v_lshl_add_u64 v[146:147], v[144:145], 0, s[0:1]
	global_load_lds_dwordx4 v[146:147], off
	s_waitcnt vmcnt(8)
	ds_read_b128 v[96:99], v136 offset:10240
	ds_read_b128 v[100:103], v136 offset:11264
	ds_read_b128 v[104:107], v136 offset:12288
	ds_read_b128 v[108:111], v136 offset:13312
	s_waitcnt lgkmcnt(4)
	v_mfma_f32_16x16x32_bf16 v[66:69], v[116:119], v[92:95], v[66:69]
	v_mfma_f32_16x16x32_bf16 v[62:65], v[120:123], v[92:95], v[62:65]
	v_mfma_f32_16x16x32_bf16 v[58:61], v[124:127], v[92:95], v[58:61]
	v_mfma_f32_16x16x32_bf16 v[54:57], v[128:131], v[92:95], v[54:57]
	s_add_i32 m0, s4, 0x1800
	v_lshl_add_u64 v[144:145], v[146:147], 0, s[0:1]
	global_load_lds_dwordx4 v[144:145], off
	s_add_i32 m0, s4, 0x1c00
	v_lshl_add_u64 v[146:147], v[144:145], 0, s[0:1]
	global_load_lds_dwordx4 v[146:147], off
	s_add_i32 m0, s4, 0x2000
	v_lshl_add_u64 v[144:145], v[146:147], 0, s[0:1]
	global_load_lds_dwordx4 v[144:145], off
	s_add_i32 m0, s4, 0x2400
	v_lshl_add_u64 v[146:147], v[144:145], 0, s[0:1]
	global_load_lds_dwordx4 v[146:147], off
	s_waitcnt vmcnt(8)
; __device__ __forceinline__ void small_gemm_q256(LAS unsigned char* lds, const bf16_t* A, const bf16_t* Bt, int unit, const float* SS, float sc, bf16_t* OUT) {
;     ...
; #pragma unroll 2
;     for (int ks = 0; ks < KS; ++ks) {
;         const bf16x8 a = *(const bf16x8*)(ap + 32 * ks);
; #pragma unroll
;         for (int t = 0; t < 16; ++t) { const bf16x8 b = *(const bf16x8*)(bp + (size_t)16 * t * K + 32 * ks); acc[t] = __builtin_amdgcn_mfma_f32_16x16x32_bf16(b, a, acc[t], 0, 0, 0); }
;     }
	ds_read_b128 v[116:119], v136 offset:14336
	ds_read_b128 v[120:123], v136 offset:15360
	ds_read_b128 v[124:127], v136 offset:0
	ds_read_b128 v[128:131], v136 offset:1024
	s_waitcnt lgkmcnt(4)
	v_mfma_f32_16x16x32_bf16 v[50:53], v[96:99], v[92:95], v[50:53]
	v_mfma_f32_16x16x32_bf16 v[42:45], v[100:103], v[92:95], v[42:45]
	v_mfma_f32_16x16x32_bf16 v[38:41], v[104:107], v[92:95], v[38:41]
	v_mfma_f32_16x16x32_bf16 v[34:37], v[108:111], v[92:95], v[34:37]
	s_add_i32 m0, s4, 0x2800
	v_lshl_add_u64 v[144:145], v[146:147], 0, s[0:1]
	global_load_lds_dwordx4 v[144:145], off
	s_add_i32 m0, s4, 0x2c00
	v_lshl_add_u64 v[146:147], v[144:145], 0, s[0:1]
	global_load_lds_dwordx4 v[146:147], off
	s_add_i32 m0, s4, 0x3000
	v_lshl_add_u64 v[144:145], v[146:147], 0, s[0:1]
	global_load_lds_dwordx4 v[144:145], off
	s_add_i32 m0, s4, 0x3400
	v_lshl_add_u64 v[146:147], v[144:145], 0, s[0:1]
	global_load_lds_dwordx4 v[146:147], off
	s_waitcnt vmcnt(7)
	ds_read_b128 v[88:91], v136 offset:2048
	ds_read_b128 v[96:99], v136 offset:3072
	ds_read_b128 v[100:103], v136 offset:4096
	ds_read_b128 v[104:107], v136 offset:5120
	ds_read_b128 v[108:111], v136 offset:6144
	s_waitcnt lgkmcnt(5)
	v_mfma_f32_16x16x32_bf16 v[30:33], v[116:119], v[92:95], v[30:33]
	v_mfma_f32_16x16x32_bf16 v[26:29], v[120:123], v[92:95], v[26:29]
	v_mfma_f32_16x16x32_bf16 v[22:25], v[124:127], v[92:95], v[22:25]
	v_mfma_f32_16x16x32_bf16 v[18:21], v[128:131], v[92:95], v[18:21]
	s_add_i32 m0, s4, 0x3800
	v_lshl_add_u64 v[144:145], v[146:147], 0, s[0:1]
	global_load_lds_dwordx4 v[144:145], off
	s_add_i32 m0, s4, 0x3c00
	v_lshl_add_u64 v[146:147], v[144:145], 0, s[0:1]
	global_load_lds_dwordx4 v[146:147], off
	s_add_i32 m0, s4, 0x0
	v_lshl_add_u64 v[144:145], v[146:147], 0, s[0:1]
	global_load_lds_dwordx4 v[144:145], off
	s_add_i32 m0, s4, 0x400
	v_lshl_add_u64 v[146:147], v[144:145], 0, s[0:1]
	global_load_lds_dwordx4 v[146:147], off
	s_waitcnt vmcnt(7)
	ds_read_b128 v[116:119], v136 offset:7168
	ds_read_b128 v[120:123], v136 offset:8192
	ds_read_b128 v[124:127], v136 offset:9216
	ds_read_b128 v[128:131], v136 offset:10240
	s_waitcnt lgkmcnt(4)
	v_mfma_f32_16x16x32_bf16 v[46:49], v[96:99], v[88:91], v[46:49]
	v_mfma_f32_16x16x32_bf16 v[78:81], v[100:103], v[88:91], v[78:81]
	v_mfma_f32_16x16x32_bf16 v[74:77], v[104:107], v[88:91], v[74:77]
	v_mfma_f32_16x16x32_bf16 v[70:73], v[108:111], v[88:91], v[70:73]
	s_add_i32 m0, s4, 0x800
	v_lshl_add_u64 v[144:145], v[146:147], 0, s[0:1]
	global_load_lds_dwordx4 v[144:145], off
	v_lshl_add_u64 v[86:87], v[86:87], 0, 64
	s_add_i32 m0, s4, 0xc00
	s_nop 0
	global_load_lds_dwordx4 v[84:85], off
	v_lshl_add_u64 v[84:85], v[84:85], 0, 64
	s_add_i32 m0, s4, 0x1000
	s_nop 0
	global_load_lds_dwordx4 v[86:87], off
	s_add_i32 m0, s4, 0x1400
	v_lshl_add_u64 v[144:145], v[86:87], 0, s[0:1]
	global_load_lds_dwordx4 v[144:145], off
	s_add_i32 m0, s4, 0x1800
	v_lshl_add_u64 v[146:147], v[144:145], 0, s[0:1]
	global_load_lds_dwordx4 v[146:147], off
	s_waitcnt vmcnt(8)
	ds_read_b128 v[96:99], v136 offset:11264
	ds_read_b128 v[100:103], v136 offset:12288
	ds_read_b128 v[104:107], v136 offset:13312
	ds_read_b128 v[108:111], v136 offset:14336
	s_waitcnt lgkmcnt(4)
	v_mfma_f32_16x16x32_bf16 v[66:69], v[116:119], v[88:91], v[66:69]
	v_mfma_f32_16x16x32_bf16 v[62:65], v[120:123], v[88:91], v[62:65]
	v_mfma_f32_16x16x32_bf16 v[58:61], v[124:127], v[88:91], v[58:61]
	v_mfma_f32_16x16x32_bf16 v[54:57], v[128:131], v[88:91], v[54:57]
	s_add_i32 m0, s4, 0x1c00
	v_lshl_add_u64 v[144:145], v[146:147], 0, s[0:1]
	global_load_lds_dwordx4 v[144:145], off
	s_add_i32 m0, s4, 0x2000
	v_lshl_add_u64 v[146:147], v[144:145], 0, s[0:1]
	global_load_lds_dwordx4 v[146:147], off
	s_add_i32 m0, s4, 0x2400
	v_lshl_add_u64 v[144:145], v[146:147], 0, s[0:1]
	global_load_lds_dwordx4 v[144:145], off
	s_add_i32 m0, s4, 0x2800
	v_lshl_add_u64 v[146:147], v[144:145], 0, s[0:1]
	global_load_lds_dwordx4 v[146:147], off
	s_waitcnt vmcnt(8)
	ds_read_b128 v[116:119], v136 offset:15360
	ds_read_b128 v[120:123], v136 offset:0
	ds_read_b128 v[124:127], v136 offset:1024
	ds_read_b128 v[128:131], v136 offset:2048
	s_waitcnt lgkmcnt(4)
	v_mfma_f32_16x16x32_bf16 v[50:53], v[96:99], v[88:91], v[50:53]
	v_mfma_f32_16x16x32_bf16 v[42:45], v[100:103], v[88:91], v[42:45]
	v_mfma_f32_16x16x32_bf16 v[38:41], v[104:107], v[88:91], v[38:41]
	v_mfma_f32_16x16x32_bf16 v[34:37], v[108:111], v[88:91], v[34:37]
	s_add_i32 m0, s4, 0x2c00
	v_lshl_add_u64 v[144:145], v[146:147], 0, s[0:1]
	global_load_lds_dwordx4 v[144:145], off
	s_add_i32 m0, s4, 0x3000
	v_lshl_add_u64 v[146:147], v[144:145], 0, s[0:1]
	global_load_lds_dwordx4 v[146:147], off
	s_add_i32 m0, s4, 0x3400
	v_lshl_add_u64 v[144:145], v[146:147], 0, s[0:1]
	global_load_lds_dwordx4 v[144:145], off
	s_add_i32 m0, s4, 0x3800
	v_lshl_add_u64 v[146:147], v[144:145], 0, s[0:1]
	global_load_lds_dwordx4 v[146:147], off
	s_waitcnt vmcnt(7)
	ds_read_b128 v[92:95], v136 offset:3072
	ds_read_b128 v[96:99], v136 offset:4096
	ds_read_b128 v[100:103], v136 offset:5120
	ds_read_b128 v[104:107], v136 offset:6144
	ds_read_b128 v[108:111], v136 offset:7168
	s_waitcnt lgkmcnt(5)
	v_mfma_f32_16x16x32_bf16 v[30:33], v[116:119], v[88:91], v[30:33]
	v_mfma_f32_16x16x32_bf16 v[26:29], v[120:123], v[88:91], v[26:29]
	v_mfma_f32_16x16x32_bf16 v[22:25], v[124:127], v[88:91], v[22:25]
	v_mfma_f32_16x16x32_bf16 v[18:21], v[128:131], v[88:91], v[18:21]
	s_add_i32 m0, s4, 0x3c00
	v_lshl_add_u64 v[144:145], v[146:147], 0, s[0:1]
	global_load_lds_dwordx4 v[144:145], off
	s_add_i32 m0, s4, 0x0
	v_lshl_add_u64 v[146:147], v[144:145], 0, s[0:1]
	global_load_lds_dwordx4 v[146:147], off
	s_add_i32 m0, s4, 0x400
	v_lshl_add_u64 v[144:145], v[146:147], 0, s[0:1]
	global_load_lds_dwordx4 v[144:145], off
	s_add_i32 m0, s4, 0x800
	v_lshl_add_u64 v[146:147], v[144:145], 0, s[0:1]
	global_load_lds_dwordx4 v[146:147], off
	s_waitcnt vmcnt(7)
; #define LAS __attribute__((address_space(3)))
; __device__ __forceinline__ unsigned cvt_pk_bf16(float lo, float hi) { unsigned r; asm("v_cvt_pk_bf16_f32 %0, %1, %2" : "=v"(r) : "v"(lo), "v"(hi)); return r; }
; __device__ __forceinline__ void small_gemm_q256(LAS unsigned char* lds, const bf16_t* A, const bf16_t* Bt, int unit, const float* SS, float sc, bf16_t* OUT) {
;     ...
;     LAS float* red = (LAS float*)lds;
; #pragma unroll
;     for (int t = 0; t < 16; ++t) *(LAS f32x4*)(red + (wave * 16 + li) * 256 + 16 * t + 4 * g4) = acc[t];
;     __syncthreads();
;     float sm = 0.f;
; #pragma unroll
;     for (int q = 0; q < 4; ++q) sm += (sv[q][0] + sv[q][1]) + (sv[q][2] + sv[q][3]);
;     const float rs = __builtin_amdgcn_rsqf(sm * (1.0f / 1024.0f) + EPS) * sc;
; #pragma unroll
;     for (int cc = 0; cc < 2; ++cc) {
;         const int c4 = (tid & 31) * 4 + 128 * cc;
;         f32x4 sum = *(LAS f32x4*)(red + row * 256 + c4);
; #pragma unroll
;         for (int w = 1; w < 8; ++w) sum += *(LAS f32x4*)(red + (w * 16 + row) * 256 + c4);
;         u32x2 w; w.x = cvt_pk_bf16(sum[0] * rs, sum[1] * rs); w.y = cvt_pk_bf16(sum[2] * rs, sum[3] * rs);
;         *(u32x2*)(OUT + (size_t)(row0 + row) * D + col0 + c4) = w;
;     }
;     asm volatile("s_waitcnt vmcnt(0)" ::: "memory");
;     __syncthreads();
	ds_read_b128 v[116:119], v136 offset:8192
	ds_read_b128 v[120:123], v136 offset:9216
	ds_read_b128 v[124:127], v136 offset:10240
	ds_read_b128 v[128:131], v136 offset:11264
	s_waitcnt lgkmcnt(4)
	v_mfma_f32_16x16x32_bf16 v[46:49], v[96:99], v[92:95], v[46:49]
	v_mfma_f32_16x16x32_bf16 v[78:81], v[100:103], v[92:95], v[78:81]
	v_mfma_f32_16x16x32_bf16 v[74:77], v[104:107], v[92:95], v[74:77]
	v_mfma_f32_16x16x32_bf16 v[70:73], v[108:111], v[92:95], v[70:73]
	s_add_i32 m0, s4, 0xc00
	v_lshl_add_u64 v[144:145], v[146:147], 0, s[0:1]
	global_load_lds_dwordx4 v[144:145], off
	v_lshl_add_u64 v[86:87], v[86:87], 0, 64
	s_waitcnt vmcnt(4)
	ds_read_b128 v[96:99], v136 offset:12288
	ds_read_b128 v[100:103], v136 offset:13312
	ds_read_b128 v[104:107], v136 offset:14336
	ds_read_b128 v[108:111], v136 offset:15360
	s_waitcnt lgkmcnt(4)
	v_mfma_f32_16x16x32_bf16 v[66:69], v[116:119], v[92:95], v[66:69]
	v_mfma_f32_16x16x32_bf16 v[62:65], v[120:123], v[92:95], v[62:65]
	v_mfma_f32_16x16x32_bf16 v[58:61], v[124:127], v[92:95], v[58:61]
	v_mfma_f32_16x16x32_bf16 v[54:57], v[128:131], v[92:95], v[54:57]
	s_waitcnt vmcnt(0)
	ds_read_b128 v[116:119], v136 offset:0
	ds_read_b128 v[120:123], v136 offset:1024
	ds_read_b128 v[124:127], v136 offset:2048
	ds_read_b128 v[128:131], v136 offset:3072
	s_waitcnt lgkmcnt(4)
	v_mfma_f32_16x16x32_bf16 v[50:53], v[96:99], v[92:95], v[50:53]
	v_mfma_f32_16x16x32_bf16 v[42:45], v[100:103], v[92:95], v[42:45]
	v_mfma_f32_16x16x32_bf16 v[38:41], v[104:107], v[92:95], v[38:41]
	v_mfma_f32_16x16x32_bf16 v[34:37], v[108:111], v[92:95], v[34:37]
	s_waitcnt lgkmcnt(0)
	v_mfma_f32_16x16x32_bf16 v[30:33], v[116:119], v[92:95], v[30:33]
	v_mfma_f32_16x16x32_bf16 v[26:29], v[120:123], v[92:95], v[26:29]
	v_mfma_f32_16x16x32_bf16 v[22:25], v[124:127], v[92:95], v[22:25]
	v_mfma_f32_16x16x32_bf16 v[18:21], v[128:131], v[92:95], v[18:21]
	s_nop 1
	s_lshl_b32 s0, s14, 8
	v_and_b32_e32 v0, 3, v114
	s_and_b32 s15, s0, 0x300
	s_lshl_b32 s0, s3, 14
	s_add_i32 s0, s0, 0
	v_lshlrev_b32_e32 v0, 4, v0
	v_add3_u32 v0, s0, v115, v0
	ds_write_b128 v0, v[46:49]
	ds_write_b128 v0, v[78:81] offset:64
	ds_write_b128 v0, v[74:77] offset:128
	ds_write_b128 v0, v[70:73] offset:192
	ds_write_b128 v0, v[66:69] offset:256
	ds_write_b128 v0, v[62:65] offset:320
	ds_write_b128 v0, v[58:61] offset:384
	ds_write_b128 v0, v[54:57] offset:448
	ds_write_b128 v0, v[50:53] offset:512
	ds_write_b128 v0, v[42:45] offset:576
	ds_write_b128 v0, v[38:41] offset:640
	ds_write_b128 v0, v[34:37] offset:704
	ds_write_b128 v0, v[30:33] offset:768
	ds_write_b128 v0, v[26:29] offset:832
	ds_write_b128 v0, v[22:25] offset:896
	ds_write_b128 v0, v[18:21] offset:960
	v_mov_b32_e32 v18, v15
	v_mov_b32_e32 v19, v16
	v_mov_b32_e32 v15, v17
	v_mov_b32_e32 v16, v11
	v_mov_b32_e32 v17, v12
	v_mov_b32_e32 v11, v13
	v_pk_add_f32 v[14:15], v[18:19], v[14:15]
	v_pk_add_f32 v[10:11], v[16:17], v[10:11]
	v_add_f32_e32 v0, v14, v15
	v_pk_add_f32 v[10:11], v[10:11], v[10:11] op_sel:[0,1] op_sel_hi:[1,0]
	v_add_f32_e32 v14, 0, v0
	v_add_f32_e32 v6, v6, v7
	v_add_f32_e32 v8, v8, v9
	v_mov_b32_e32 v15, v2
	v_mov_b32_e32 v11, v3
	v_mov_b32_e32 v7, v4
	v_mov_b32_e32 v9, v5
	v_pk_add_f32 v[2:3], v[14:15], v[10:11]
	v_pk_add_f32 v[4:5], v[6:7], v[8:9]
	s_waitcnt lgkmcnt(0)
	v_pk_add_f32 v[2:3], v[2:3], v[4:5]
	s_barrier
	v_add_f32_e32 v0, v2, v3
	v_fmamk_f32 v0, v0, 0x3a800000, v209
	v_rsq_f32_e32 v0, v0
	v_lshlrev_b32_e32 v2, 10, v113
	v_lshlrev_b64 v[10:11], 11, v[82:83]
	v_mul_f32_e32 v20, 0x3db8aa3b, v0
	v_lshlrev_b32_e32 v0, 2, v112
	v_and_b32_e32 v0, 0x7c, v0
	v_lshlrev_b32_e32 v3, 2, v0
	v_add3_u32 v21, 0, v2, v3
	ds_read_b128 v[2:5], v21
	ds_read_b128 v[6:9], v21 offset:16384
	v_lshl_add_u64 v[14:15], s[30:31], 0, v[10:11]
	ds_read_b128 v[10:13], v21 offset:32768
	s_lshl_b32 s62, s15, 1
	v_lshl_add_u64 v[14:15], v[14:15], 0, s[62:63]
	s_waitcnt lgkmcnt(1)
	v_pk_add_f32 v[6:7], v[2:3], v[6:7]
	v_pk_add_f32 v[8:9], v[4:5], v[8:9]
	ds_read_b128 v[2:5], v21 offset:49152
	s_waitcnt lgkmcnt(1)
	v_pk_add_f32 v[10:11], v[6:7], v[10:11]
	v_add_u32_e32 v6, 0x10000, v21
	v_pk_add_f32 v[12:13], v[8:9], v[12:13]
	ds_read_b128 v[6:9], v6
	s_waitcnt lgkmcnt(1)
	v_pk_add_f32 v[10:11], v[10:11], v[2:3]
	v_add_u32_e32 v2, 0x14000, v21
	v_pk_add_f32 v[12:13], v[12:13], v[4:5]
	ds_read_b128 v[2:5], v2
	s_waitcnt lgkmcnt(1)
	v_pk_add_f32 v[18:19], v[10:11], v[6:7]
	v_add_u32_e32 v6, 0x18000, v21
	v_pk_add_f32 v[16:17], v[12:13], v[8:9]
	ds_read_b128 v[6:9], v6
	v_add_u32_e32 v10, 0x1c000, v21
	ds_read_b128 v[10:13], v10
	s_waitcnt lgkmcnt(2)
	v_pk_add_f32 v[2:3], v[18:19], v[2:3]
	v_pk_add_f32 v[4:5], v[16:17], v[4:5]
	s_waitcnt lgkmcnt(1)
	v_pk_add_f32 v[2:3], v[2:3], v[6:7]
	v_pk_add_f32 v[4:5], v[4:5], v[8:9]
	s_waitcnt lgkmcnt(0)
	v_pk_add_f32 v[2:3], v[2:3], v[10:11]
	v_pk_add_f32 v[4:5], v[4:5], v[12:13]
	v_mul_f32_e32 v2, v20, v2
	v_mul_f32_e32 v3, v20, v3
	v_lshlrev_b32_e32 v0, 1, v0
	v_cvt_pk_bf16_f32 v2, v2, v3
	v_mul_f32_e32 v3, v20, v4
	v_lshl_add_u64 v[14:15], v[14:15], 0, v[0:1]
	v_mul_f32_e32 v4, v20, v5
	v_cvt_pk_bf16_f32 v3, v3, v4
	flat_store_dwordx2 v[14:15], v[2:3]
	ds_read_b128 v[2:5], v21 offset:512
	ds_read_b128 v[6:9], v21 offset:16896
	ds_read_b128 v[10:13], v21 offset:33280
	v_add_u32_e32 v0, 0x10200, v21
	v_mov_b32_e32 v137, v208
	s_ashr_i32 s17, s14, 2
	s_waitcnt lgkmcnt(0)
	v_pk_add_f32 v[8:9], v[4:5], v[8:9]
	v_pk_add_f32 v[6:7], v[2:3], v[6:7]
	ds_read_b128 v[2:5], v21 offset:49664
	v_pk_add_f32 v[12:13], v[8:9], v[12:13]
	v_pk_add_f32 v[10:11], v[6:7], v[10:11]
	ds_read_b128 v[6:9], v0
	v_add_u32_e32 v0, 0x14200, v21
	s_waitcnt lgkmcnt(0)
	v_pk_add_f32 v[12:13], v[12:13], v[4:5]
	v_pk_add_f32 v[10:11], v[10:11], v[2:3]
	ds_read_b128 v[2:5], v0
	v_add_u32_e32 v0, 0x18200, v21
	v_pk_add_f32 v[16:17], v[12:13], v[8:9]
	v_pk_add_f32 v[18:19], v[10:11], v[6:7]
	ds_read_b128 v[6:9], v0
	v_add_u32_e32 v0, 0x1c200, v21
	ds_read_b128 v[10:13], v0
	s_waitcnt lgkmcnt(0)
	v_pk_add_f32 v[4:5], v[16:17], v[4:5]
	v_pk_add_f32 v[2:3], v[18:19], v[2:3]
	v_pk_add_f32 v[4:5], v[4:5], v[8:9]
	v_pk_add_f32 v[2:3], v[2:3], v[6:7]
	v_pk_add_f32 v[4:5], v[4:5], v[12:13]
	v_pk_add_f32 v[2:3], v[2:3], v[10:11]
	s_and_b32 s16, s2, 3
	v_mul_f32_e32 v0, v20, v2
	v_mul_f32_e32 v2, v20, v3
	v_mul_f32_e32 v3, v20, v5
	v_cvt_pk_bf16_f32 v2, v0, v2
	v_mul_f32_e32 v0, v20, v4
	v_cvt_pk_bf16_f32 v3, v0, v3
	flat_store_dwordx2 v[14:15], v[2:3] offset:256
	s_waitcnt vmcnt(0)
	s_waitcnt lgkmcnt(0)
	s_barrier
; #define LAS __attribute__((address_space(3)))
; __device__ __forceinline__ bf16x8 load8f_bf(const float* p) { const f32x4 a = *(const f32x4*)p, b = *(const f32x4*)(p + 4); return pack8v(a, b); }
; __device__ __forceinline__ int voff_x(int key, int d) { return ((key >> 3) * 8 + (d >> 5)) * 512 + (key & 7) * 64 + (d & 31) * 2; }
; __device__ __forceinline__ void xattn_sample_unit(const Params& P, int l, int b, int h, LAS unsigned char* lds, int tid_) {
;     ...
;     const float* CK = P.in[7] + ((size_t)(l * 32 + b) * 256 + 32 * wave) * 1024 + h * 256;
;     const float* CV = P.in[8] + ((size_t)(l * 32 + b) * 256 + 32 * wave) * 1024 + h * 256;
;     LAS unsigned char* wl = lds + wave * 16384;
;     LAS float* ml = (LAS float*)(lds + 131072);
;     const int qrow = TP + b * 16 + (r & 15);
; #pragma unroll 4
;     for (int i = 0; i < 16; ++i) { const int idx = lane + 64 * i, vr = idx >> 5, ch = idx & 31;
;         *(LAS bf16x8*)(wl + voff_x(vr, 8 * ch)) = load8f_bf(CV + (size_t)vr * 1024 + 8 * ch); }
;     f32x16 S;
; #pragma unroll
;     for (int e = 0; e < 16; ++e) S[e] = 0.f;
; #pragma unroll 4
;     for (int ks = 0; ks < 16; ++ks) {
;         const bf16x8 qf = *(const bf16x8*)(Q2 + (size_t)qrow * D + h * 256 + 16 * ks + 8 * hi);
;         const bf16x8 kf = load8f_bf(CK + (size_t)r * 1024 + 16 * ks + 8 * hi);
	s_add_i32 s2, s17, s7
	v_readfirstlane_b32 s0, v137
	s_ashr_i32 s4, s0, 6
	s_lshl_b32 s0, s4, 5
	s_ashr_i32 s3, s2, 31
	s_ashr_i32 s1, s0, 31
	s_lshl_b32 s5, s16, 10
	s_lshl_b32 s4, s4, 14
	s_lshl_b64 s[2:3], s[2:3], 20
	s_lshl_b64 s[24:25], s[0:1], 12
	v_lshlrev_b32_e32 v5, 7, v137
	v_lshlrev_b32_e32 v19, 4, v137
	v_bfe_u32 v18, v137, 5, 1
	s_add_u32 s1, s24, s2
	v_and_b32_e32 v136, 31, v137
	v_and_b32_e32 v5, 0xe00, v5
	v_and_b32_e32 v0, 48, v19
	s_addc_u32 s6, s25, s3
	v_lshl_or_b32 v2, v18, 12, s1
	v_lshlrev_b32_e32 v3, 5, v136
	v_readlane_b32 s36, v253, 7
	v_lshlrev_b32_e32 v4, 6, v18
	v_or_b32_e32 v5, s4, v5
	v_or3_b32 v2, v2, s5, v3
	v_mov_b32_e32 v3, s6
	v_readlane_b32 s37, v253, 8
	v_or3_b32 v0, v5, v4, v0
	v_and_b32_e32 v139, 63, v137
	v_lshl_add_u64 v[2:3], s[36:37], 0, v[2:3]
	v_add_u32_e32 v0, 0, v0
	s_mov_b64 s[26:27], 0
	v_readlane_b32 s38, v253, 9
	v_readlane_b32 s39, v253, 10
	v_readlane_b32 s40, v253, 11
	v_readlane_b32 s41, v253, 12
	v_readlane_b32 s42, v253, 13
	v_readlane_b32 s43, v253, 14
	v_readlane_b32 s44, v253, 15
	v_readlane_b32 s45, v253, 16
	v_readlane_b32 s46, v253, 17
	v_readlane_b32 s47, v253, 18
	v_readlane_b32 s48, v253, 19
	v_readlane_b32 s49, v253, 20
	v_readlane_b32 s50, v253, 21
	v_readlane_b32 s51, v253, 22
	v_mov_b32_e32 v128, v2
	v_mov_b32_e32 v129, v3
	v_mov_b32_e32 v138, v0
	s_lshl_b32 s1, s17, 4
	s_lshl_b32 s6, s16, 9
	v_and_b32_e32 v140, 15, v137
	s_addk_i32 s1, 0x4000
	v_or_b32_e32 v2, s1, v140
	s_add_u32 s1, s24, s2
	v_ashrrev_i32_e32 v3, 31, v2
	s_addc_u32 s3, s25, s3
	v_lshlrev_b64 v[134:135], 11, v[2:3]
	v_lshlrev_b32_e32 v0, 4, v18
	v_readlane_b32 s16, v254, 43
	s_add_u32 s2, s5, s1
	v_or3_b32 v2, v134, s6, v0
	v_mov_b32_e32 v3, v135
	v_readlane_b32 s17, v254, 44
	v_lshlrev_b32_e32 v0, 12, v136
	s_addc_u32 s3, 0, s3
	v_lshl_add_u64 v[20:21], s[16:17], 0, v[2:3]
	v_lshl_add_u64 v[2:3], s[2:3], 0, v[0:1]
	v_lshlrev_b32_e32 v0, 5, v18
	v_readlane_b32 s36, v253, 55
	v_lshl_add_u64 v[2:3], v[2:3], 0, v[0:1]
	v_readlane_b32 s50, v254, 5
	v_readlane_b32 s51, v254, 6
	s_mov_b64 s[2:3], 0
	v_readlane_b32 s37, v253, 56
	v_lshl_add_u64 v[22:23], s[50:51], 0, v[2:3]
	v_mov_b32_e32 v2, 0
	v_mov_b32_e32 v3, v2
	v_mov_b32_e32 v4, v2
	v_mov_b32_e32 v5, v2
	v_mov_b32_e32 v6, v2
	v_mov_b32_e32 v7, v2
	v_mov_b32_e32 v8, v2
	v_mov_b32_e32 v9, v2
	v_mov_b32_e32 v10, v2
	v_mov_b32_e32 v11, v2
	v_mov_b32_e32 v12, v2
	v_mov_b32_e32 v13, v2
	v_mov_b32_e32 v14, v2
	v_mov_b32_e32 v15, v2
	v_mov_b32_e32 v16, v2
	v_mov_b32_e32 v17, v2
	v_readlane_b32 s38, v253, 57
	v_readlane_b32 s39, v253, 58
	v_readlane_b32 s40, v253, 59
	v_readlane_b32 s41, v253, 60
	v_readlane_b32 s42, v253, 61
	v_readlane_b32 s43, v253, 62
	v_readlane_b32 s44, v253, 63
	v_readlane_b32 s45, v254, 0
	v_readlane_b32 s46, v254, 1
	v_readlane_b32 s47, v254, 2
	v_readlane_b32 s48, v254, 3
	v_readlane_b32 s49, v254, 4
	s_mov_b64 s[26:27], 0x8000
	v_lshl_add_u64 v[130:131], v[128:129], 0, s[26:27]
	v_lshl_add_u64 v[132:133], v[130:131], 0, s[26:27]
	v_lshl_add_u64 v[142:143], v[132:133], 0, s[26:27]
	global_load_dwordx4 v[24:27], v[128:129], off nt
	global_load_dwordx4 v[28:31], v[128:129], off offset:16 nt
	v_lshl_add_u64 v[144:145], v[128:129], 0, s[72:73]
	global_load_dwordx4 v[32:35], v[144:145], off nt
	global_load_dwordx4 v[36:39], v[144:145], off offset:16 nt
	v_lshl_add_u64 v[144:145], v[128:129], 0, s[74:75]
	global_load_dwordx4 v[40:43], v[144:145], off nt
	global_load_dwordx4 v[44:47], v[144:145], off offset:16 nt
	v_lshl_add_u64 v[144:145], v[128:129], 0, s[76:77]
	global_load_dwordx4 v[48:51], v[144:145], off nt
	global_load_dwordx4 v[52:55], v[144:145], off offset:16 nt
	global_load_dwordx4 v[56:59], v[130:131], off nt
	global_load_dwordx4 v[60:63], v[130:131], off offset:16 nt
	v_lshl_add_u64 v[144:145], v[130:131], 0, s[72:73]
	global_load_dwordx4 v[64:67], v[144:145], off nt
	global_load_dwordx4 v[68:71], v[144:145], off offset:16 nt
	v_lshl_add_u64 v[144:145], v[130:131], 0, s[74:75]
	global_load_dwordx4 v[72:75], v[144:145], off nt
	global_load_dwordx4 v[76:79], v[144:145], off offset:16 nt
	v_lshl_add_u64 v[144:145], v[130:131], 0, s[76:77]
	global_load_dwordx4 v[80:83], v[144:145], off nt
	global_load_dwordx4 v[84:87], v[144:145], off offset:16 nt
	global_load_dwordx4 v[88:91], v[132:133], off nt
	global_load_dwordx4 v[92:95], v[132:133], off offset:16 nt
	v_lshl_add_u64 v[144:145], v[132:133], 0, s[72:73]
	global_load_dwordx4 v[96:99], v[144:145], off nt
	global_load_dwordx4 v[100:103], v[144:145], off offset:16 nt
	v_lshl_add_u64 v[144:145], v[132:133], 0, s[74:75]
	global_load_dwordx4 v[104:107], v[144:145], off nt
	global_load_dwordx4 v[108:111], v[144:145], off offset:16 nt
	v_lshl_add_u64 v[144:145], v[132:133], 0, s[76:77]
	global_load_dwordx4 v[112:115], v[144:145], off nt
	global_load_dwordx4 v[116:119], v[144:145], off offset:16 nt
	global_load_dwordx4 v[120:123], v[142:143], off nt
	global_load_dwordx4 v[124:127], v[142:143], off offset:16 nt
	s_waitcnt vmcnt(24)
	v_cvt_pk_bf16_f32 v24, v24, v25
	v_cvt_pk_bf16_f32 v25, v26, v27
	v_cvt_pk_bf16_f32 v26, v28, v29
	v_cvt_pk_bf16_f32 v27, v30, v31
	ds_write_b128 v138, v[24:27]
	v_lshl_add_u64 v[144:145], v[142:143], 0, s[72:73]
	global_load_dwordx4 v[24:27], v[144:145], off nt
	global_load_dwordx4 v[28:31], v[144:145], off offset:16 nt
	s_waitcnt vmcnt(24)
	v_cvt_pk_bf16_f32 v32, v32, v33
	v_cvt_pk_bf16_f32 v33, v34, v35
	v_cvt_pk_bf16_f32 v34, v36, v37
	v_cvt_pk_bf16_f32 v35, v38, v39
	ds_write_b128 v138, v[32:35] offset:128
	v_lshl_add_u64 v[144:145], v[142:143], 0, s[74:75]
	global_load_dwordx4 v[32:35], v[144:145], off nt
	global_load_dwordx4 v[36:39], v[144:145], off offset:16 nt
	s_waitcnt vmcnt(24)
; #define LAS __attribute__((address_space(3)))
; __device__ __forceinline__ bf16x8 load8f_bf(const float* p) { const f32x4 a = *(const f32x4*)p, b = *(const f32x4*)(p + 4); return pack8v(a, b); }
; __device__ __forceinline__ int voff_x(int key, int d) { return ((key >> 3) * 8 + (d >> 5)) * 512 + (key & 7) * 64 + (d & 31) * 2; }
; __device__ __forceinline__ void xattn_sample_unit(const Params& P, int l, int b, int h, LAS unsigned char* lds, int tid_) {
;     ...
;     for (int i = 0; i < 16; ++i) { const int idx = lane + 64 * i, vr = idx >> 5, ch = idx & 31;
;         *(LAS bf16x8*)(wl + voff_x(vr, 8 * ch)) = load8f_bf(CV + (size_t)vr * 1024 + 8 * ch); }
;     f32x16 S;
; #pragma unroll
;     for (int e = 0; e < 16; ++e) S[e] = 0.f;
; #pragma unroll 4
;     for (int ks = 0; ks < 16; ++ks) {
;         const bf16x8 qf = *(const bf16x8*)(Q2 + (size_t)qrow * D + h * 256 + 16 * ks + 8 * hi);
;         const bf16x8 kf = load8f_bf(CK + (size_t)r * 1024 + 16 * ks + 8 * hi);
;         S = __builtin_amdgcn_mfma_f32_32x32x16_bf16(kf, qf, S, 0, 0, 0);
;     }
	v_cvt_pk_bf16_f32 v40, v40, v41
	v_cvt_pk_bf16_f32 v41, v42, v43
	v_cvt_pk_bf16_f32 v42, v44, v45
	v_cvt_pk_bf16_f32 v43, v46, v47
	ds_write_b128 v138, v[40:43] offset:256
	v_lshl_add_u64 v[144:145], v[142:143], 0, s[76:77]
	global_load_dwordx4 v[40:43], v[144:145], off nt
	global_load_dwordx4 v[44:47], v[144:145], off offset:16 nt
	s_waitcnt vmcnt(24)
	v_cvt_pk_bf16_f32 v48, v48, v49
	v_cvt_pk_bf16_f32 v49, v50, v51
	v_cvt_pk_bf16_f32 v50, v52, v53
	v_cvt_pk_bf16_f32 v51, v54, v55
	ds_write_b128 v138, v[48:51] offset:384
	global_load_dwordx4 v[48:51], v[20:21], off offset:-64
	global_load_dwordx4 v[52:55], v[22:23], off nt
	s_waitcnt vmcnt(24)
	v_cvt_pk_bf16_f32 v56, v56, v57
	v_cvt_pk_bf16_f32 v57, v58, v59
	v_cvt_pk_bf16_f32 v58, v60, v61
	v_cvt_pk_bf16_f32 v59, v62, v63
	ds_write_b128 v138, v[56:59] offset:4096
	global_load_dwordx4 v[56:59], v[22:23], off offset:16 nt
	global_load_dwordx4 v[60:63], v[20:21], off offset:-32
	s_waitcnt vmcnt(24)
	v_cvt_pk_bf16_f32 v64, v64, v65
	v_cvt_pk_bf16_f32 v65, v66, v67
	v_cvt_pk_bf16_f32 v66, v68, v69
	v_cvt_pk_bf16_f32 v67, v70, v71
	ds_write_b128 v138, v[64:67] offset:4224
	global_load_dwordx4 v[64:67], v[22:23], off offset:64 nt
	global_load_dwordx4 v[68:71], v[22:23], off offset:80 nt
	s_waitcnt vmcnt(24)
	v_cvt_pk_bf16_f32 v72, v72, v73
	v_cvt_pk_bf16_f32 v73, v74, v75
	v_cvt_pk_bf16_f32 v74, v76, v77
	v_cvt_pk_bf16_f32 v75, v78, v79
	ds_write_b128 v138, v[72:75] offset:4352
	global_load_dwordx4 v[72:75], v[20:21], off
	global_load_dwordx4 v[76:79], v[22:23], off offset:128 nt
	s_waitcnt vmcnt(24)
	v_cvt_pk_bf16_f32 v80, v80, v81
	v_cvt_pk_bf16_f32 v81, v82, v83
	v_cvt_pk_bf16_f32 v82, v84, v85
	v_cvt_pk_bf16_f32 v83, v86, v87
	ds_write_b128 v138, v[80:83] offset:4480
	global_load_dwordx4 v[80:83], v[22:23], off offset:144 nt
	global_load_dwordx4 v[84:87], v[20:21], off offset:32
	s_waitcnt vmcnt(24)
	v_cvt_pk_bf16_f32 v88, v88, v89
	v_cvt_pk_bf16_f32 v89, v90, v91
	v_cvt_pk_bf16_f32 v90, v92, v93
	v_cvt_pk_bf16_f32 v91, v94, v95
	ds_write_b128 v138, v[88:91] offset:8192
	global_load_dwordx4 v[88:91], v[22:23], off offset:192 nt
	global_load_dwordx4 v[92:95], v[22:23], off offset:208 nt
	s_waitcnt vmcnt(24)
	v_cvt_pk_bf16_f32 v96, v96, v97
	v_cvt_pk_bf16_f32 v97, v98, v99
	v_cvt_pk_bf16_f32 v98, v100, v101
	v_cvt_pk_bf16_f32 v99, v102, v103
	ds_write_b128 v138, v[96:99] offset:8320
	global_load_dwordx4 v[96:99], v[20:21], off offset:64
	global_load_dwordx4 v[100:103], v[22:23], off offset:256 nt
	s_waitcnt vmcnt(24)
	v_cvt_pk_bf16_f32 v104, v104, v105
	v_cvt_pk_bf16_f32 v105, v106, v107
	v_cvt_pk_bf16_f32 v106, v108, v109
	v_cvt_pk_bf16_f32 v107, v110, v111
	ds_write_b128 v138, v[104:107] offset:8448
	global_load_dwordx4 v[104:107], v[22:23], off offset:272 nt
	global_load_dwordx4 v[108:111], v[20:21], off offset:96
	s_waitcnt vmcnt(24)
	v_cvt_pk_bf16_f32 v112, v112, v113
	v_cvt_pk_bf16_f32 v113, v114, v115
	v_cvt_pk_bf16_f32 v114, v116, v117
	v_cvt_pk_bf16_f32 v115, v118, v119
	ds_write_b128 v138, v[112:115] offset:8576
	global_load_dwordx4 v[112:115], v[22:23], off offset:320 nt
	global_load_dwordx4 v[116:119], v[22:23], off offset:336 nt
	s_waitcnt vmcnt(24)
	v_cvt_pk_bf16_f32 v120, v120, v121
	v_cvt_pk_bf16_f32 v121, v122, v123
	v_cvt_pk_bf16_f32 v122, v124, v125
	v_cvt_pk_bf16_f32 v123, v126, v127
	ds_write_b128 v138, v[120:123] offset:12288
	global_load_dwordx4 v[120:123], v[20:21], off offset:128
	global_load_dwordx4 v[124:127], v[22:23], off offset:384 nt
	s_waitcnt vmcnt(24)
	v_cvt_pk_bf16_f32 v24, v24, v25
	v_cvt_pk_bf16_f32 v25, v26, v27
	v_cvt_pk_bf16_f32 v26, v28, v29
	v_cvt_pk_bf16_f32 v27, v30, v31
	ds_write_b128 v138, v[24:27] offset:12416
	global_load_dwordx4 v[24:27], v[22:23], off offset:400 nt
	global_load_dwordx4 v[28:31], v[20:21], off offset:160
	s_waitcnt vmcnt(24)
	v_cvt_pk_bf16_f32 v32, v32, v33
	v_cvt_pk_bf16_f32 v33, v34, v35
	v_cvt_pk_bf16_f32 v34, v36, v37
	v_cvt_pk_bf16_f32 v35, v38, v39
	ds_write_b128 v138, v[32:35] offset:12544
	global_load_dwordx4 v[32:35], v[22:23], off offset:448 nt
	global_load_dwordx4 v[36:39], v[22:23], off offset:464 nt
	s_waitcnt vmcnt(24)
	v_cvt_pk_bf16_f32 v40, v40, v41
	v_cvt_pk_bf16_f32 v41, v42, v43
	v_cvt_pk_bf16_f32 v42, v44, v45
	v_cvt_pk_bf16_f32 v43, v46, v47
	ds_write_b128 v138, v[40:43] offset:12672
	global_load_dwordx4 v[40:43], v[20:21], off offset:192
	global_load_dwordx4 v[44:47], v[22:23], off offset:512 nt
	s_waitcnt vmcnt(23)
	v_cvt_pk_bf16_f32 v52, v52, v53
	v_cvt_pk_bf16_f32 v53, v54, v55
	v_cvt_pk_bf16_f32 v54, v56, v57
	v_cvt_pk_bf16_f32 v55, v58, v59
	s_nop 1
	v_mfma_f32_32x32x16_bf16 v[2:17], v[52:55], v[48:51], v[2:17]
	global_load_dwordx4 v[48:51], v[22:23], off offset:528 nt
	global_load_dwordx4 v[52:55], v[20:21], off offset:224
	global_load_dwordx4 v[56:59], v[22:23], off offset:576 nt
	s_waitcnt vmcnt(23)
	v_cvt_pk_bf16_f32 v64, v64, v65
	v_cvt_pk_bf16_f32 v65, v66, v67
	v_cvt_pk_bf16_f32 v66, v68, v69
	v_cvt_pk_bf16_f32 v67, v70, v71
	s_nop 1
	v_mfma_f32_32x32x16_bf16 v[2:17], v[64:67], v[60:63], v[2:17]
	global_load_dwordx4 v[60:63], v[22:23], off offset:592 nt
	global_load_dwordx4 v[64:67], v[20:21], off offset:256
	global_load_dwordx4 v[68:71], v[22:23], off offset:640 nt
	s_waitcnt vmcnt(23)
	v_cvt_pk_bf16_f32 v76, v76, v77
	v_cvt_pk_bf16_f32 v77, v78, v79
	v_cvt_pk_bf16_f32 v78, v80, v81
	v_cvt_pk_bf16_f32 v79, v82, v83
	s_nop 1
	v_mfma_f32_32x32x16_bf16 v[2:17], v[76:79], v[72:75], v[2:17]
	global_load_dwordx4 v[72:75], v[22:23], off offset:656 nt
	global_load_dwordx4 v[76:79], v[20:21], off offset:288
	global_load_dwordx4 v[80:83], v[22:23], off offset:704 nt
	s_waitcnt vmcnt(23)
; __device__ __forceinline__ bf16x8 load8f_bf(const float* p) { const f32x4 a = *(const f32x4*)p, b = *(const f32x4*)(p + 4); return pack8v(a, b); }
; __device__ __forceinline__ void xattn_sample_unit(const Params& P, int l, int b, int h, LAS unsigned char* lds, int tid_) {
;     ...
;     for (int ks = 0; ks < 16; ++ks) {
;         const bf16x8 qf = *(const bf16x8*)(Q2 + (size_t)qrow * D + h * 256 + 16 * ks + 8 * hi);
;         const bf16x8 kf = load8f_bf(CK + (size_t)r * 1024 + 16 * ks + 8 * hi);
;         S = __builtin_amdgcn_mfma_f32_32x32x16_bf16(kf, qf, S, 0, 0, 0);
;     }
;     float mx = S[0];
; #pragma unroll
;     for (int e = 1; e < 16; ++e) mx = fmaxf(mx, S[e]);
;     mx = fmaxf(mx, __shfl_xor(mx, 32));
	v_cvt_pk_bf16_f32 v88, v88, v89
	v_cvt_pk_bf16_f32 v89, v90, v91
	v_cvt_pk_bf16_f32 v90, v92, v93
	v_cvt_pk_bf16_f32 v91, v94, v95
	s_nop 1
	v_mfma_f32_32x32x16_bf16 v[2:17], v[88:91], v[84:87], v[2:17]
	global_load_dwordx4 v[84:87], v[22:23], off offset:720 nt
	global_load_dwordx4 v[88:91], v[20:21], off offset:320
	global_load_dwordx4 v[92:95], v[22:23], off offset:768 nt
	s_waitcnt vmcnt(23)
	v_cvt_pk_bf16_f32 v100, v100, v101
	v_cvt_pk_bf16_f32 v101, v102, v103
	v_cvt_pk_bf16_f32 v102, v104, v105
	v_cvt_pk_bf16_f32 v103, v106, v107
	s_nop 1
	v_mfma_f32_32x32x16_bf16 v[2:17], v[100:103], v[96:99], v[2:17]
	global_load_dwordx4 v[96:99], v[22:23], off offset:784 nt
	global_load_dwordx4 v[100:103], v[20:21], off offset:352
	global_load_dwordx4 v[104:107], v[22:23], off offset:832 nt
	s_waitcnt vmcnt(23)
	v_cvt_pk_bf16_f32 v112, v112, v113
	v_cvt_pk_bf16_f32 v113, v114, v115
	v_cvt_pk_bf16_f32 v114, v116, v117
	v_cvt_pk_bf16_f32 v115, v118, v119
	s_nop 1
	v_mfma_f32_32x32x16_bf16 v[2:17], v[112:115], v[108:111], v[2:17]
	global_load_dwordx4 v[108:111], v[22:23], off offset:848 nt
	global_load_dwordx4 v[112:115], v[20:21], off offset:384
	global_load_dwordx4 v[116:119], v[22:23], off offset:896 nt
	s_waitcnt vmcnt(23)
	v_cvt_pk_bf16_f32 v124, v124, v125
	v_cvt_pk_bf16_f32 v125, v126, v127
	v_cvt_pk_bf16_f32 v126, v24, v25
	v_cvt_pk_bf16_f32 v127, v26, v27
	s_nop 1
	v_mfma_f32_32x32x16_bf16 v[2:17], v[124:127], v[120:123], v[2:17]
	global_load_dwordx4 v[120:123], v[22:23], off offset:912 nt
	global_load_dwordx4 v[124:127], v[20:21], off offset:416
	global_load_dwordx4 v[24:27], v[22:23], off offset:960 nt
	s_waitcnt vmcnt(23)
	v_cvt_pk_bf16_f32 v32, v32, v33
	v_cvt_pk_bf16_f32 v33, v34, v35
	v_cvt_pk_bf16_f32 v34, v36, v37
	v_cvt_pk_bf16_f32 v35, v38, v39
	s_nop 1
	v_mfma_f32_32x32x16_bf16 v[2:17], v[32:35], v[28:31], v[2:17]
	global_load_dwordx4 v[28:31], v[22:23], off offset:976 nt
	s_waitcnt vmcnt(21)
	v_cvt_pk_bf16_f32 v44, v44, v45
	v_cvt_pk_bf16_f32 v45, v46, v47
	v_cvt_pk_bf16_f32 v46, v48, v49
	v_cvt_pk_bf16_f32 v47, v50, v51
	s_nop 1
	v_mfma_f32_32x32x16_bf16 v[2:17], v[44:47], v[40:43], v[2:17]
	s_waitcnt vmcnt(18)
	v_cvt_pk_bf16_f32 v56, v56, v57
	v_cvt_pk_bf16_f32 v57, v58, v59
	v_cvt_pk_bf16_f32 v58, v60, v61
	v_cvt_pk_bf16_f32 v59, v62, v63
	s_nop 1
	v_mfma_f32_32x32x16_bf16 v[2:17], v[56:59], v[52:55], v[2:17]
	s_waitcnt vmcnt(15)
	v_cvt_pk_bf16_f32 v68, v68, v69
	v_cvt_pk_bf16_f32 v69, v70, v71
	v_cvt_pk_bf16_f32 v70, v72, v73
	v_cvt_pk_bf16_f32 v71, v74, v75
	s_nop 1
	v_mfma_f32_32x32x16_bf16 v[2:17], v[68:71], v[64:67], v[2:17]
	s_waitcnt vmcnt(12)
	v_cvt_pk_bf16_f32 v80, v80, v81
	v_cvt_pk_bf16_f32 v81, v82, v83
	v_cvt_pk_bf16_f32 v82, v84, v85
	v_cvt_pk_bf16_f32 v83, v86, v87
	s_nop 1
	v_mfma_f32_32x32x16_bf16 v[2:17], v[80:83], v[76:79], v[2:17]
	s_waitcnt vmcnt(9)
	v_cvt_pk_bf16_f32 v92, v92, v93
	v_cvt_pk_bf16_f32 v93, v94, v95
	v_cvt_pk_bf16_f32 v94, v96, v97
	v_cvt_pk_bf16_f32 v95, v98, v99
	s_nop 1
	v_mfma_f32_32x32x16_bf16 v[2:17], v[92:95], v[88:91], v[2:17]
	s_waitcnt vmcnt(6)
	v_cvt_pk_bf16_f32 v104, v104, v105
	v_cvt_pk_bf16_f32 v105, v106, v107
	v_cvt_pk_bf16_f32 v106, v108, v109
	v_cvt_pk_bf16_f32 v107, v110, v111
	s_nop 1
	v_mfma_f32_32x32x16_bf16 v[2:17], v[104:107], v[100:103], v[2:17]
	s_waitcnt vmcnt(3)
	v_cvt_pk_bf16_f32 v116, v116, v117
	v_cvt_pk_bf16_f32 v117, v118, v119
	v_cvt_pk_bf16_f32 v118, v120, v121
	v_cvt_pk_bf16_f32 v119, v122, v123
	s_nop 1
	v_mfma_f32_32x32x16_bf16 v[2:17], v[116:119], v[112:115], v[2:17]
	s_waitcnt vmcnt(0)
	v_cvt_pk_bf16_f32 v24, v24, v25
	v_cvt_pk_bf16_f32 v25, v26, v27
	v_cvt_pk_bf16_f32 v26, v28, v29
	v_cvt_pk_bf16_f32 v27, v30, v31
	s_nop 1
	v_mfma_f32_32x32x16_bf16 v[2:17], v[24:27], v[124:127], v[2:17]
	s_nop 1
	s_nop 10
	v_max_f32_e32 v0, v3, v3
	v_max_f32_e32 v20, v2, v2
	v_max_f32_e32 v0, v20, v0
	v_max3_f32 v0, v0, v4, v5
	v_max3_f32 v0, v0, v6, v7
	v_max3_f32 v0, v0, v8, v9
	v_and_b32_e32 v21, 64, v210
	v_max3_f32 v0, v0, v10, v11
	v_xor_b32_e32 v20, 32, v210
	v_add_u32_e32 v21, 64, v21
	v_max3_f32 v0, v0, v12, v13
	v_cmp_lt_i32_e32 vcc, v20, v21
	v_max3_f32 v0, v0, v14, v15
	v_max3_f32 v0, v0, v16, v17
	v_cndmask_b32_e32 v20, v210, v20, vcc
	v_lshlrev_b32_e32 v20, 2, v20
	ds_bpermute_b32 v21, v20, v0
	s_add_i32 s4, s4, 0
	v_lshlrev_b32_e32 v142, 8, v18
	v_cmp_gt_u32_e32 vcc, 16, v139
	s_waitcnt lgkmcnt(0)
; __device__ __forceinline__ unsigned cvt_pk_bf16(float lo, float hi) { unsigned r; asm("v_cvt_pk_bf16_f32 %0, %1, %2" : "=v"(r) : "v"(lo), "v"(hi)); return r; }
; __device__ __forceinline__ int voff_x(int key, int d) { return ((key >> 3) * 8 + (d >> 5)) * 512 + (key & 7) * 64 + (d & 31) * 2; }
; __device__ __forceinline__ void xattn_sample_unit(const Params& P, int l, int b, int h, LAS unsigned char* lds, int tid_) {
;     ...
;     float ls = 0.f;
; #pragma unroll
;     for (int e = 0; e < 16; ++e) { S[e] = __builtin_amdgcn_exp2f(S[e] - mx); ls += S[e]; }
;     ls += __shfl_xor(ls, 32);
;     bf16x8 pf[2];
; #pragma unroll
;     for (int s2 = 0; s2 < 2; ++s2) { u32x4 w; w.x = cvt_pk_bf16(S[8 * s2 + 0], S[8 * s2 + 1]); w.y = cvt_pk_bf16(S[8 * s2 + 2], S[8 * s2 + 3]); w.z = cvt_pk_bf16(S[8 * s2 + 4], S[8 * s2 + 5]); w.w = cvt_pk_bf16(S[8 * s2 + 6], S[8 * s2 + 7]);
;         pf[s2] = __builtin_bit_cast(bf16x8, w); }
;     f32x16 O[8];
;     const int trow = 4 * hi + ((lane & 15) >> 2), tcol = 16 * ((lane >> 4) & 1) + 4 * (lane & 3);
; #pragma unroll
;     for (int db = 0; db < 8; ++db) {
; #pragma unroll
;         for (int e = 0; e < 16; ++e) O[db][e] = 0.f;
; #pragma unroll
;         for (int s2 = 0; s2 < 2; ++s2) {
;             const s16x4 a0 = tr_read(wl + voff_x(16 * s2 + trow, 32 * db + tcol));
;             const s16x4 a1 = tr_read(wl + voff_x(16 * s2 + 8 + trow, 32 * db + tcol));
;             const bf16x8 vf = (bf16x8){a0[0], a0[1], a0[2], a0[3], a1[0], a1[1], a1[2], a1[3]};
;             O[db] = __builtin_amdgcn_mfma_f32_32x32x16_bf16(vf, pf[s2], O[db], 0, 0, 0);
;         }
;     }
;     if (lane < 16) { ml[(wave * 16 + lane) * 2] = mx; ml[(wave * 16 + lane) * 2 + 1] = ls; }
	v_max_f32_e32 v21, v21, v21
	v_max_f32_e32 v138, v0, v21
	v_sub_f32_e32 v0, v2, v138
	v_exp_f32_e32 v2, v0
	v_sub_f32_e32 v3, v3, v138
	v_exp_f32_e32 v3, v3
	v_sub_f32_e32 v4, v4, v138
	v_exp_f32_e32 v4, v4
	v_sub_f32_e32 v5, v5, v138
	v_exp_f32_e32 v5, v5
	v_sub_f32_e32 v6, v6, v138
	v_add_f32_e32 v0, 0, v2
	v_exp_f32_e32 v6, v6
	v_sub_f32_e32 v7, v7, v138
	v_add_f32_e32 v0, v3, v0
	v_exp_f32_e32 v7, v7
	v_sub_f32_e32 v8, v8, v138
	v_add_f32_e32 v0, v4, v0
	v_exp_f32_e32 v8, v8
	v_sub_f32_e32 v9, v9, v138
	v_add_f32_e32 v0, v5, v0
	v_exp_f32_e32 v9, v9
	v_sub_f32_e32 v10, v10, v138
	v_add_f32_e32 v0, v6, v0
	v_exp_f32_e32 v10, v10
	v_sub_f32_e32 v11, v11, v138
	v_add_f32_e32 v0, v7, v0
	v_exp_f32_e32 v11, v11
	v_sub_f32_e32 v12, v12, v138
	v_add_f32_e32 v0, v8, v0
	v_exp_f32_e32 v12, v12
	v_sub_f32_e32 v13, v13, v138
	v_cvt_pk_bf16_f32 v114, v2, v3
	v_and_b32_e32 v2, 16, v137
	v_lshlrev_b32_e32 v3, 2, v137
	v_add_f32_e32 v0, v9, v0
	v_exp_f32_e32 v13, v13
	v_sub_f32_e32 v14, v14, v138
	v_and_or_b32 v2, v3, 12, v2
	v_add_f32_e32 v0, v10, v0
	v_exp_f32_e32 v14, v14
	v_sub_f32_e32 v15, v15, v138
	v_cvt_pk_bf16_f32 v115, v4, v5
	v_and_b32_e32 v3, 0xc0, v19
	v_lshlrev_b32_e32 v2, 1, v2
	v_add_u32_e32 v4, s4, v142
	v_add_f32_e32 v0, v11, v0
	v_exp_f32_e32 v15, v15
	v_sub_f32_e32 v16, v16, v138
	v_add3_u32 v143, v4, v3, v2
	v_add_f32_e32 v0, v12, v0
	v_exp_f32_e32 v16, v16
	v_sub_f32_e32 v17, v17, v138
	ds_read_b64_tr_b16 v[2:3], v143
	ds_read_b64_tr_b16 v[4:5], v143 offset:4096
	v_add_f32_e32 v0, v13, v0
	v_exp_f32_e32 v17, v17
	v_add_f32_e32 v0, v14, v0
	v_add_f32_e32 v0, v15, v0
	v_add_f32_e32 v0, v16, v0
	v_add_f32_e32 v0, v17, v0
	v_cvt_pk_bf16_f32 v116, v6, v7
	v_cvt_pk_bf16_f32 v117, v8, v9
	v_cvt_pk_bf16_f32 v130, v10, v11
	v_cvt_pk_bf16_f32 v131, v12, v13
	v_cvt_pk_bf16_f32 v132, v14, v15
	v_cvt_pk_bf16_f32 v133, v16, v17
	ds_bpermute_b32 v141, v20, v0
	s_waitcnt lgkmcnt(1)
	v_mfma_f32_32x32x16_bf16 v[2:17], v[2:5], v[114:117], 0
	ds_read_b64_tr_b16 v[18:19], v143 offset:8192
	ds_read_b64_tr_b16 v[20:21], v143 offset:12288
	s_waitcnt lgkmcnt(0)
	v_mfma_f32_32x32x16_bf16 v[2:17], v[18:21], v[130:133], v[2:17]
	ds_read_b64_tr_b16 v[18:19], v143 offset:512
	ds_read_b64_tr_b16 v[20:21], v143 offset:4608
	ds_read_b64_tr_b16 v[34:35], v143 offset:8704
	ds_read_b64_tr_b16 v[36:37], v143 offset:12800
	s_waitcnt lgkmcnt(2)
	v_mfma_f32_32x32x16_bf16 v[18:33], v[18:21], v[114:117], 0
	s_waitcnt lgkmcnt(0)
	v_mfma_f32_32x32x16_bf16 v[18:33], v[34:37], v[130:133], v[18:33]
	ds_read_b64_tr_b16 v[34:35], v143 offset:1024
	ds_read_b64_tr_b16 v[36:37], v143 offset:5120
	ds_read_b64_tr_b16 v[50:51], v143 offset:9216
	ds_read_b64_tr_b16 v[52:53], v143 offset:13312
	s_waitcnt lgkmcnt(2)
	v_mfma_f32_32x32x16_bf16 v[34:49], v[34:37], v[114:117], 0
	s_waitcnt lgkmcnt(0)
	v_mfma_f32_32x32x16_bf16 v[34:49], v[50:53], v[130:133], v[34:49]
	ds_read_b64_tr_b16 v[50:51], v143 offset:1536
	ds_read_b64_tr_b16 v[52:53], v143 offset:5632
	ds_read_b64_tr_b16 v[66:67], v143 offset:9728
	ds_read_b64_tr_b16 v[68:69], v143 offset:13824
	s_waitcnt lgkmcnt(2)
	v_mfma_f32_32x32x16_bf16 v[50:65], v[50:53], v[114:117], 0
	s_waitcnt lgkmcnt(0)
	v_mfma_f32_32x32x16_bf16 v[50:65], v[66:69], v[130:133], v[50:65]
	ds_read_b64_tr_b16 v[66:67], v143 offset:2048
	ds_read_b64_tr_b16 v[68:69], v143 offset:6144
	ds_read_b64_tr_b16 v[82:83], v143 offset:10240
	ds_read_b64_tr_b16 v[84:85], v143 offset:14336
	s_waitcnt lgkmcnt(2)
	v_mfma_f32_32x32x16_bf16 v[66:81], v[66:69], v[114:117], 0
	s_waitcnt lgkmcnt(0)
	v_mfma_f32_32x32x16_bf16 v[66:81], v[82:85], v[130:133], v[66:81]
	ds_read_b64_tr_b16 v[82:83], v143 offset:2560
	ds_read_b64_tr_b16 v[84:85], v143 offset:6656
	ds_read_b64_tr_b16 v[98:99], v143 offset:10752
	ds_read_b64_tr_b16 v[100:101], v143 offset:14848
	s_waitcnt lgkmcnt(2)
	v_mfma_f32_32x32x16_bf16 v[82:97], v[82:85], v[114:117], 0
	s_waitcnt lgkmcnt(0)
	v_mfma_f32_32x32x16_bf16 v[82:97], v[98:101], v[130:133], v[82:97]
	ds_read_b64_tr_b16 v[98:99], v143 offset:3072
	ds_read_b64_tr_b16 v[100:101], v143 offset:7168
	ds_read_b64_tr_b16 v[118:119], v143 offset:11264
	ds_read_b64_tr_b16 v[120:121], v143 offset:15360
	s_waitcnt lgkmcnt(2)
	v_mfma_f32_32x32x16_bf16 v[98:113], v[98:101], v[114:117], 0
	s_waitcnt lgkmcnt(0)
	v_mfma_f32_32x32x16_bf16 v[98:113], v[118:121], v[130:133], v[98:113]
	ds_read_b64_tr_b16 v[118:119], v143 offset:3584
	ds_read_b64_tr_b16 v[120:121], v143 offset:7680
	ds_read_b64_tr_b16 v[144:145], v143 offset:11776
	ds_read_b64_tr_b16 v[146:147], v143 offset:15872
	s_waitcnt lgkmcnt(2)
	v_mfma_f32_32x32x16_bf16 v[114:129], v[118:121], v[114:117], 0
	s_waitcnt lgkmcnt(0)
	v_mfma_f32_32x32x16_bf16 v[114:129], v[144:147], v[130:133], v[114:129]
	s_and_saveexec_b64 s[2:3], vcc
	s_mov_b32 s45, s18
	s_mov_b32 s47, s19
	s_movk_i32 s48, 0xc0
	s_mov_b32 s39, 0x20000
	s_mov_b32 s40, 0x28000
	s_mov_b32 s41, 0x30000
	s_mov_b32 s42, 0x38000
	s_mov_b32 s43, 0x60000
	s_cbranch_execz .LBB0_594
	s_lshl_b32 s0, s0, 2
	s_add_i32 s0, s0, 0
	v_lshl_add_u32 v130, v139, 3, s0
	v_add_u32_e32 v130, 0x20000, v130
	v_add_f32_e32 v139, v0, v141
	ds_write_b64 v130, v[138:139]
